# GEMM loops: A-frag ring 8 + 4 deferred MFMA groups across barriers; attention softmax max-reduction rewritten as v_max3 tree (54 -> 16 VALU per tile)
# speedup vs baseline: 1.1171x; 1.0155x over previous
.LBB0_285:
	ds_read_b128 v[158:161], v251
	ds_read_b128 v[162:165], v249
	ds_read_b128 v[166:169], v251 offset:4096
	ds_read_b128 v[126:129], v255
	ds_read_b128 v[130:133], v253
	ds_read_b128 v[134:137], v255 offset:4096
	ds_read_b128 v[138:141], v253 offset:4096
	s_cmp_eq_u32 s98, 0
	s_cbranch_scc1 .Lnodef_B0_0
	v_mfma_f32_16x16x32_bf16 v[78:81], v[170:173], v[142:145], v[78:81]
	v_mfma_f32_16x16x32_bf16 v[74:77], v[174:177], v[142:145], v[74:77]
	v_mfma_f32_16x16x32_bf16 v[70:73], v[178:181], v[142:145], v[70:73]
	v_mfma_f32_16x16x32_bf16 v[66:69], v[170:173], v[146:149], v[66:69]
	v_mfma_f32_16x16x32_bf16 v[62:65], v[174:177], v[146:149], v[62:65]
	v_mfma_f32_16x16x32_bf16 v[58:61], v[178:181], v[146:149], v[58:61]
	v_mfma_f32_16x16x32_bf16 v[50:53], v[170:173], v[150:153], v[50:53]
	v_mfma_f32_16x16x32_bf16 v[46:49], v[174:177], v[150:153], v[46:49]
	v_mfma_f32_16x16x32_bf16 v[42:45], v[178:181], v[150:153], v[42:45]
	v_mfma_f32_16x16x32_bf16 v[38:41], v[170:173], v[154:157], v[38:41]
	v_mfma_f32_16x16x32_bf16 v[34:37], v[174:177], v[154:157], v[34:37]
	v_mfma_f32_16x16x32_bf16 v[30:33], v[178:181], v[154:157], v[30:33]
.Lnodef_B0_0:
	ds_read_b128 v[150:153], v255 offset:12288
	ds_read_b128 v[146:149], v253 offset:8192
	ds_read_b128 v[142:145], v255 offset:8192
	ds_read_b128 v[154:157], v253 offset:12288
	s_add_i32 s2, s35, -1
	s_cmp_lt_i32 s2, s30
	s_cselect_b64 s[14:15], -1, 0
	s_cmp_ge_i32 s2, s30
	s_waitcnt lgkmcnt(7)
	v_mfma_f32_16x16x32_bf16 v[122:125], v[158:161], v[126:129], v[122:125]
	v_mfma_f32_16x16x32_bf16 v[118:121], v[162:165], v[126:129], v[118:121]
	v_mfma_f32_16x16x32_bf16 v[114:117], v[166:169], v[126:129], v[114:117]
	ds_read_b128 v[126:129], v247
	s_waitcnt lgkmcnt(7)
	v_mfma_f32_16x16x32_bf16 v[110:113], v[158:161], v[130:133], v[110:113]
	v_mfma_f32_16x16x32_bf16 v[106:109], v[162:165], v[130:133], v[106:109]
	v_mfma_f32_16x16x32_bf16 v[102:105], v[166:169], v[130:133], v[102:105]
	s_waitcnt vmcnt(5)
	ds_write_b128 v238, v[26:29]
	ds_write_b128 v238, v[22:25] offset:8192
.LBB0_287:
	s_lshl_b32 s2, s44, 8
	s_ashr_i32 s3, s2, 31
	s_lshl_b64 s[4:5], s[2:3], 11
	s_lshl_b32 s2, s22, 6
	s_ashr_i32 s3, s2, 31
	s_add_u32 s20, s25, s4
	s_addc_u32 s21, s26, s5
	s_lshl_b64 s[12:13], s[2:3], 1
	s_add_u32 s20, s20, s12
	s_addc_u32 s21, s21, s13
	global_load_dwordx4 v[22:25], v237, s[20:21]
	global_load_dwordx4 v[26:29], v236, s[20:21]
	s_andn2_b64 vcc, exec, s[14:15]
	ds_read_b128 v[130:133], v245
	s_waitcnt lgkmcnt(9)
	v_mfma_f32_16x16x32_bf16 v[98:101], v[158:161], v[134:137], v[98:101]
	v_mfma_f32_16x16x32_bf16 v[94:97], v[162:165], v[134:137], v[94:97]
	v_mfma_f32_16x16x32_bf16 v[90:93], v[166:169], v[134:137], v[90:93]
	ds_read_b128 v[134:137], v247 offset:4096
	s_waitcnt lgkmcnt(9)
	v_mfma_f32_16x16x32_bf16 v[86:89], v[158:161], v[138:141], v[86:89]
	v_mfma_f32_16x16x32_bf16 v[82:85], v[162:165], v[138:141], v[82:85]
	v_mfma_f32_16x16x32_bf16 v[54:57], v[166:169], v[138:141], v[54:57]
	ds_read_b128 v[170:173], v243
	ds_read_b128 v[174:177], v241
	ds_read_b128 v[178:181], v243 offset:4096
	ds_read_b128 v[138:141], v245 offset:4096
	s_waitcnt lgkmcnt(10)
	v_mfma_f32_16x16x32_bf16 v[78:81], v[158:161], v[142:145], v[78:81]
	v_mfma_f32_16x16x32_bf16 v[74:77], v[162:165], v[142:145], v[74:77]
	v_mfma_f32_16x16x32_bf16 v[70:73], v[166:169], v[142:145], v[70:73]
	s_waitcnt vmcnt(5)
	ds_write_b128 v238, v[18:21] offset:16384
	ds_write_b128 v238, v[14:17] offset:24576
.LBB0_289:
	global_load_dwordx4 v[14:17], v235, s[20:21]
	global_load_dwordx4 v[18:21], v234, s[20:21]
	s_and_b64 vcc, exec, s[2:3]
	ds_read_b128 v[142:145], v247 offset:8192
	v_mfma_f32_16x16x32_bf16 v[66:69], v[158:161], v[146:149], v[66:69]
	v_mfma_f32_16x16x32_bf16 v[62:65], v[162:165], v[146:149], v[62:65]
	v_mfma_f32_16x16x32_bf16 v[58:61], v[166:169], v[146:149], v[58:61]
	ds_read_b128 v[146:149], v245 offset:8192
	v_mfma_f32_16x16x32_bf16 v[50:53], v[158:161], v[150:153], v[50:53]
	v_mfma_f32_16x16x32_bf16 v[46:49], v[162:165], v[150:153], v[46:49]
	v_mfma_f32_16x16x32_bf16 v[42:45], v[166:169], v[150:153], v[42:45]
	s_waitcnt vmcnt(5)
	s_waitcnt lgkmcnt(10)
	ds_write_b128 v238, v[10:13] offset:32768
	ds_write_b128 v238, v[6:9] offset:40960
.LBB0_291:
	s_mul_i32 s14, s43, 0xc0
	s_ashr_i32 s15, s14, 31
	s_lshl_b64 s[14:15], s[14:15], 11
	s_add_u32 s20, s27, s14
	s_addc_u32 s21, s28, s15
	s_add_u32 s12, s20, s12
	s_addc_u32 s13, s21, s13
	global_load_dwordx4 v[6:9], v237, s[12:13]
	global_load_dwordx4 v[10:13], v236, s[12:13]
	s_and_b64 vcc, exec, s[2:3]
	ds_read_b128 v[150:153], v247 offset:12288
	v_mfma_f32_16x16x32_bf16 v[38:41], v[158:161], v[154:157], v[38:41]
	v_mfma_f32_16x16x32_bf16 v[34:37], v[162:165], v[154:157], v[34:37]
	v_mfma_f32_16x16x32_bf16 v[30:33], v[166:169], v[154:157], v[30:33]
	ds_read_b128 v[154:157], v245 offset:12288
	s_waitcnt lgkmcnt(9)
	v_mfma_f32_16x16x32_bf16 v[122:125], v[170:173], v[126:129], v[122:125]
	v_mfma_f32_16x16x32_bf16 v[118:121], v[174:177], v[126:129], v[118:121]
	v_mfma_f32_16x16x32_bf16 v[114:117], v[178:181], v[126:129], v[114:117]
	v_mfma_f32_16x16x32_bf16 v[110:113], v[170:173], v[130:133], v[110:113]
	v_mfma_f32_16x16x32_bf16 v[106:109], v[174:177], v[130:133], v[106:109]
	v_mfma_f32_16x16x32_bf16 v[102:105], v[178:181], v[130:133], v[102:105]
	s_waitcnt vmcnt(6)
	ds_write_b128 v238, v[2:5] offset:49152
.LBB0_293:
	global_load_dwordx4 v[2:5], v235, s[12:13]
	v_mfma_f32_16x16x32_bf16 v[98:101], v[170:173], v[134:137], v[98:101]
	v_mfma_f32_16x16x32_bf16 v[94:97], v[174:177], v[134:137], v[94:97]
	v_mfma_f32_16x16x32_bf16 v[90:93], v[178:181], v[134:137], v[90:93]
	s_waitcnt lgkmcnt(9)
	v_mfma_f32_16x16x32_bf16 v[86:89], v[170:173], v[138:141], v[86:89]
	v_mfma_f32_16x16x32_bf16 v[82:85], v[174:177], v[138:141], v[82:85]
	v_mfma_f32_16x16x32_bf16 v[54:57], v[178:181], v[138:141], v[54:57]
	s_add_i32 s46, s22, 1
	s_cmp_lg_u32 s46, 16
	s_cbranch_scc1 .LBB0_297
	s_add_i32 s24, s24, s11
	s_cmpk_gt_i32 s24, 0x5f
	s_cbranch_scc1 .LBB0_296
	s_ashr_i32 s3, s24, 31
	s_lshr_b32 s3, s3, 27
	s_add_i32 s3, s24, s3
	s_ashr_i32 s3, s3, 5
	s_mov_b32 s2, s10
	s_lshl_b32 s4, s3, 6
	s_lshl_b32 s5, s24, 1
	s_sub_i32 s4, s5, s4
	s_and_b32 s2, s2, 7
	s_and_b32 s4, s4, -8
	s_or_b32 s44, s2, s4
	s_lshl_b32 s3, s3, 2
	s_and_b32 s5, s24, 3
	s_lshl_b32 s2, s44, 8
	s_or_b32 s43, s3, s5
	s_ashr_i32 s3, s2, 31
	s_lshl_b64 s[4:5], s[2:3], 11
	s_mul_i32 s2, s43, 0xc0
	s_ashr_i32 s3, s2, 31
	s_lshl_b64 s[14:15], s[2:3], 11

.LBB0_297:
	s_waitcnt lgkmcnt(0)
	s_barrier
	ds_read_b128 v[158:161], v250
	ds_read_b128 v[162:165], v248
	ds_read_b128 v[166:169], v250 offset:4096
	ds_read_b128 v[126:129], v254
	ds_read_b128 v[130:133], v252
	ds_read_b128 v[134:137], v254 offset:4096
	ds_read_b128 v[138:141], v252 offset:4096
	v_mfma_f32_16x16x32_bf16 v[78:81], v[170:173], v[142:145], v[78:81]
	v_mfma_f32_16x16x32_bf16 v[74:77], v[174:177], v[142:145], v[74:77]
	v_mfma_f32_16x16x32_bf16 v[70:73], v[178:181], v[142:145], v[70:73]
	v_mfma_f32_16x16x32_bf16 v[66:69], v[170:173], v[146:149], v[66:69]
	v_mfma_f32_16x16x32_bf16 v[62:65], v[174:177], v[146:149], v[62:65]
	v_mfma_f32_16x16x32_bf16 v[58:61], v[178:181], v[146:149], v[58:61]
	v_mfma_f32_16x16x32_bf16 v[50:53], v[170:173], v[150:153], v[50:53]
	v_mfma_f32_16x16x32_bf16 v[46:49], v[174:177], v[150:153], v[46:49]
	v_mfma_f32_16x16x32_bf16 v[42:45], v[178:181], v[150:153], v[42:45]
	v_mfma_f32_16x16x32_bf16 v[38:41], v[170:173], v[154:157], v[38:41]
	v_mfma_f32_16x16x32_bf16 v[34:37], v[174:177], v[154:157], v[34:37]
	v_mfma_f32_16x16x32_bf16 v[30:33], v[178:181], v[154:157], v[30:33]
	ds_read_b128 v[150:153], v254 offset:12288
	ds_read_b128 v[146:149], v252 offset:8192
	ds_read_b128 v[142:145], v254 offset:8192
	ds_read_b128 v[154:157], v252 offset:12288
	s_cmp_lt_i32 s35, s30
	s_cselect_b64 s[20:21], -1, 0
	s_cmp_ge_i32 s35, s30
	s_cselect_b64 s[12:13], -1, 0
	s_and_b64 vcc, exec, s[12:13]
	s_waitcnt lgkmcnt(7)
	v_mfma_f32_16x16x32_bf16 v[122:125], v[158:161], v[126:129], v[122:125]
	v_mfma_f32_16x16x32_bf16 v[118:121], v[162:165], v[126:129], v[118:121]
	v_mfma_f32_16x16x32_bf16 v[114:117], v[166:169], v[126:129], v[114:117]
	ds_read_b128 v[126:129], v246
	s_waitcnt lgkmcnt(7)
	v_mfma_f32_16x16x32_bf16 v[110:113], v[158:161], v[130:133], v[110:113]
	v_mfma_f32_16x16x32_bf16 v[106:109], v[162:165], v[130:133], v[106:109]
	v_mfma_f32_16x16x32_bf16 v[102:105], v[166:169], v[130:133], v[102:105]
	s_waitcnt vmcnt(5)
	ds_write_b128 v239, v[22:25]
	ds_write_b128 v239, v[26:29] offset:8192
.LBB0_299:
	s_lshl_b32 s2, s46, 6
	s_ashr_i32 s3, s2, 31
	s_add_u32 s22, s25, s4
	s_addc_u32 s23, s26, s5
	s_lshl_b64 s[4:5], s[2:3], 1
	s_add_u32 s22, s22, s4
	s_addc_u32 s23, s23, s5
	global_load_dwordx4 v[26:29], v237, s[22:23]
	global_load_dwordx4 v[22:25], v236, s[22:23]
	s_andn2_b64 vcc, exec, s[20:21]
	ds_read_b128 v[130:133], v244
	s_waitcnt lgkmcnt(9)
	v_mfma_f32_16x16x32_bf16 v[98:101], v[158:161], v[134:137], v[98:101]
	v_mfma_f32_16x16x32_bf16 v[94:97], v[162:165], v[134:137], v[94:97]
	v_mfma_f32_16x16x32_bf16 v[90:93], v[166:169], v[134:137], v[90:93]
	ds_read_b128 v[134:137], v246 offset:4096
	s_waitcnt lgkmcnt(9)
	v_mfma_f32_16x16x32_bf16 v[86:89], v[158:161], v[138:141], v[86:89]
	v_mfma_f32_16x16x32_bf16 v[82:85], v[162:165], v[138:141], v[82:85]
	v_mfma_f32_16x16x32_bf16 v[54:57], v[166:169], v[138:141], v[54:57]
	ds_read_b128 v[170:173], v242
	ds_read_b128 v[174:177], v240
	ds_read_b128 v[178:181], v242 offset:4096
	ds_read_b128 v[138:141], v244 offset:4096
	s_waitcnt lgkmcnt(10)
	v_mfma_f32_16x16x32_bf16 v[78:81], v[158:161], v[142:145], v[78:81]
	v_mfma_f32_16x16x32_bf16 v[74:77], v[162:165], v[142:145], v[74:77]
	v_mfma_f32_16x16x32_bf16 v[70:73], v[166:169], v[142:145], v[70:73]
	s_waitcnt vmcnt(5)
	ds_write_b128 v239, v[14:17] offset:16384
	ds_write_b128 v239, v[18:21] offset:24576
.LBB0_301:
	global_load_dwordx4 v[18:21], v235, s[22:23]
	global_load_dwordx4 v[14:17], v234, s[22:23]
	s_and_b64 vcc, exec, s[2:3]
	ds_read_b128 v[142:145], v246 offset:8192
	v_mfma_f32_16x16x32_bf16 v[66:69], v[158:161], v[146:149], v[66:69]
	v_mfma_f32_16x16x32_bf16 v[62:65], v[162:165], v[146:149], v[62:65]
	v_mfma_f32_16x16x32_bf16 v[58:61], v[166:169], v[146:149], v[58:61]
	ds_read_b128 v[146:149], v244 offset:8192
	v_mfma_f32_16x16x32_bf16 v[50:53], v[158:161], v[150:153], v[50:53]
	v_mfma_f32_16x16x32_bf16 v[46:49], v[162:165], v[150:153], v[46:49]
	v_mfma_f32_16x16x32_bf16 v[42:45], v[166:169], v[150:153], v[42:45]
	s_waitcnt vmcnt(5)
	s_waitcnt lgkmcnt(10)
	ds_write_b128 v239, v[6:9] offset:32768
	ds_write_b128 v239, v[10:13] offset:40960
.LBB0_303:
	s_add_u32 s14, s27, s14
	s_addc_u32 s15, s28, s15
	s_add_u32 s4, s14, s4
	s_addc_u32 s5, s15, s5
	global_load_dwordx4 v[10:13], v237, s[4:5]
	global_load_dwordx4 v[6:9], v236, s[4:5]
	s_and_b64 vcc, exec, s[2:3]
	ds_read_b128 v[150:153], v246 offset:12288
	v_mfma_f32_16x16x32_bf16 v[38:41], v[158:161], v[154:157], v[38:41]
	v_mfma_f32_16x16x32_bf16 v[34:37], v[162:165], v[154:157], v[34:37]
	v_mfma_f32_16x16x32_bf16 v[30:33], v[166:169], v[154:157], v[30:33]
	ds_read_b128 v[154:157], v244 offset:12288
	s_waitcnt lgkmcnt(9)
	v_mfma_f32_16x16x32_bf16 v[122:125], v[170:173], v[126:129], v[122:125]
	v_mfma_f32_16x16x32_bf16 v[118:121], v[174:177], v[126:129], v[118:121]
	v_mfma_f32_16x16x32_bf16 v[114:117], v[178:181], v[126:129], v[114:117]
	v_mfma_f32_16x16x32_bf16 v[110:113], v[170:173], v[130:133], v[110:113]
	v_mfma_f32_16x16x32_bf16 v[106:109], v[174:177], v[130:133], v[106:109]
	v_mfma_f32_16x16x32_bf16 v[102:105], v[178:181], v[130:133], v[102:105]
	s_waitcnt vmcnt(6)
	ds_write_b128 v239, v[2:5] offset:49152
.LBB0_305:
	global_load_dwordx4 v[2:5], v235, s[4:5]
	v_mfma_f32_16x16x32_bf16 v[98:101], v[170:173], v[134:137], v[98:101]
	v_mfma_f32_16x16x32_bf16 v[94:97], v[174:177], v[134:137], v[94:97]
	v_mfma_f32_16x16x32_bf16 v[90:93], v[178:181], v[134:137], v[90:93]
	s_waitcnt lgkmcnt(9)
	v_mfma_f32_16x16x32_bf16 v[86:89], v[170:173], v[138:141], v[86:89]
	v_mfma_f32_16x16x32_bf16 v[82:85], v[174:177], v[138:141], v[82:85]
	v_mfma_f32_16x16x32_bf16 v[54:57], v[178:181], v[138:141], v[54:57]
	s_add_i32 s22, s46, 1
	s_cmp_lg_u32 s22, 16
	s_cbranch_scc1 .LBB0_309
	s_add_i32 s24, s24, s11
	s_cmpk_gt_i32 s24, 0x5f
	s_cbranch_scc1 .LBB0_308
	s_ashr_i32 s3, s24, 31
	s_lshr_b32 s3, s3, 27
	s_add_i32 s3, s24, s3
	s_ashr_i32 s3, s3, 5
	s_mov_b32 s2, s10
	s_lshl_b32 s4, s3, 6
	s_lshl_b32 s5, s24, 1
	s_sub_i32 s4, s5, s4
	s_and_b32 s2, s2, 7
	s_and_b32 s4, s4, -8
	s_lshl_b32 s3, s3, 2
	s_and_b32 s5, s24, 3
	s_or_b32 s43, s3, s5
	s_or_b32 s44, s2, s4

.LBB0_309:
	s_add_i32 s45, s45, 2
	s_cmp_lg_u32 s45, 16
	s_waitcnt lgkmcnt(0)
	s_mov_b32 s98, 1
	s_cbranch_scc1 .LBB0_284
	s_mov_b32 s98, 0
	v_mfma_f32_16x16x32_bf16 v[78:81], v[170:173], v[142:145], v[78:81]
	v_mfma_f32_16x16x32_bf16 v[74:77], v[174:177], v[142:145], v[74:77]
	v_mfma_f32_16x16x32_bf16 v[70:73], v[178:181], v[142:145], v[70:73]
	v_mfma_f32_16x16x32_bf16 v[66:69], v[170:173], v[146:149], v[66:69]
	v_mfma_f32_16x16x32_bf16 v[62:65], v[174:177], v[146:149], v[62:65]
	v_mfma_f32_16x16x32_bf16 v[58:61], v[178:181], v[146:149], v[58:61]
	v_mfma_f32_16x16x32_bf16 v[50:53], v[170:173], v[150:153], v[50:53]
	v_mfma_f32_16x16x32_bf16 v[46:49], v[174:177], v[150:153], v[46:49]
	v_mfma_f32_16x16x32_bf16 v[42:45], v[178:181], v[150:153], v[42:45]
	v_mfma_f32_16x16x32_bf16 v[38:41], v[170:173], v[154:157], v[38:41]
	v_mfma_f32_16x16x32_bf16 v[34:37], v[174:177], v[154:157], v[34:37]
	v_mfma_f32_16x16x32_bf16 v[30:33], v[178:181], v[154:157], v[30:33]
	s_nop 7
	s_nop 7
	v_mov_b32_e32 v127, v0
	s_mul_i32 s2, s29, 0xc0
	s_nop 0
	v_lshrrev_b32_e32 v128, 2, v127
	v_bfe_u32 v126, v127, 6, 2
	v_and_or_b32 v128, v128, 12, s2
	v_mad_u32_u24 v126, v126, 48, v128
	v_ashrrev_i32_e32 v128, 1, v127
	v_and_b32_e32 v128, 0xffffff80, v128
	v_lshl_add_u32 v128, s31, 8, v128
	v_and_or_b32 v128, v127, 15, v128
	v_cmp_gt_i32_e32 vcc, s40, v126
	v_ashrrev_i32_e32 v127, 31, v126
	s_and_saveexec_b64 s[2:3], vcc
	s_cbranch_execz .LBB0_312
	v_cvt_pk_bf16_f32 v122, v122, v123
	v_cvt_pk_bf16_f32 v123, v124, v125
	v_mov_b64_e32 v[124:125], s[8:9]
	v_mad_i64_i32 v[124:125], s[4:5], v128, s41, v[124:125]
	v_lshl_add_u64 v[124:125], v[126:127], 1, v[124:125]
	global_store_dwordx2 v[124:125], v[122:123], off

.LBB0_787:
	ds_read_b128 v[36:39], v196
	s_waitcnt vmcnt(14)
	ds_read_b128 v[132:135], v196 offset:32
	s_add_i32 s9, s8, -2
	v_lshlrev_b32_e32 v170, 1, v160
	v_mov_b32_e32 v171, v3
	s_waitcnt lgkmcnt(1)
	v_mfma_f32_32x32x16_bf16 v[52:67], v[36:39], v[68:71], 0
	ds_read_b128 v[36:39], v196 offset:6656
	s_waitcnt vmcnt(13)
	ds_read_b128 v[136:139], v196 offset:6688
	s_waitcnt lgkmcnt(1)
	v_mfma_f32_32x32x16_bf16 v[36:51], v[36:39], v[68:71], 0
	v_mfma_f32_32x32x16_bf16 v[52:67], v[132:135], v[72:75], v[52:67]
	s_waitcnt lgkmcnt(0)
	v_mfma_f32_32x32x16_bf16 v[36:51], v[136:139], v[72:75], v[36:51]
	ds_read_b128 v[132:135], v196 offset:64
	ds_read_b128 v[136:139], v196 offset:96
	s_waitcnt lgkmcnt(1)
	v_mfma_f32_32x32x16_bf16 v[52:67], v[132:135], v[76:79], v[52:67]
	ds_read_b128 v[132:135], v196 offset:6720
	s_waitcnt vmcnt(12)
	ds_read_b128 v[140:143], v196 offset:6752
	s_waitcnt lgkmcnt(1)
	v_mfma_f32_32x32x16_bf16 v[36:51], v[132:135], v[76:79], v[36:51]
	ds_read_b128 v[132:135], v196 offset:128
	v_mfma_f32_32x32x16_bf16 v[52:67], v[136:139], v[80:83], v[52:67]
	v_min_u32_e32 v136, s9, v194
	v_mul_u32_u24_e32 v2, 0xc000, v136
	s_waitcnt vmcnt(11)
	v_lshl_add_u64 v[144:145], v[2:3], 1, v[162:163]
	v_lshlrev_b32_e32 v2, 7, v136
	v_lshl_add_u64 v[136:137], v[166:167], 1, v[144:145]
	v_lshl_add_u64 v[206:207], v[164:165], 0, v[2:3]
	v_lshlrev_b32_e32 v2, 1, v168
	s_waitcnt lgkmcnt(1)
	v_mfma_f32_32x32x16_bf16 v[36:51], v[140:143], v[80:83], v[36:51]
	ds_read_b128 v[140:143], v196 offset:6784
	ds_read_b128 v[202:205], v196 offset:160
	s_waitcnt lgkmcnt(2)
	v_mfma_f32_32x32x16_bf16 v[52:67], v[132:135], v[84:87], v[52:67]
	v_lshl_add_u64 v[132:133], v[156:157], 1, v[144:145]
	global_load_dwordx4 v[132:135], v[132:133], off
	s_nop 0
	global_load_dwordx4 v[136:139], v[136:137], off
	s_waitcnt vmcnt(12)
	ds_read_b128 v[148:151], v196 offset:6816
	s_waitcnt lgkmcnt(2)
	v_mfma_f32_32x32x16_bf16 v[36:51], v[140:143], v[84:87], v[36:51]
	v_lshl_add_u64 v[140:141], v[158:159], 1, v[144:145]
	v_lshl_add_u64 v[144:145], v[206:207], 0, v[2:3]
	global_load_dwordx4 v[140:143], v[140:141], off
	s_nop 0
	global_load_dwordx4 v[144:147], v[144:145], off
	s_waitcnt lgkmcnt(0)
	v_mfma_f32_32x32x16_bf16 v[36:51], v[148:151], v[100:103], v[36:51]
	v_lshl_add_u64 v[148:149], v[206:207], 0, v[170:171]
	global_load_dwordx4 v[148:151], v[148:149], off
	v_mfma_f32_32x32x16_bf16 v[52:67], v[202:205], v[100:103], v[52:67]
	s_nop 8
	v_max3_f32 v171, v36, v37, v38
	v_max3_f32 v172, v39, v40, v41
	v_max3_f32 v171, v171, v42, v43
	v_max3_f32 v172, v172, v44, v45
	v_max3_f32 v171, v171, v46, v47
	v_max3_f32 v172, v172, v48, v49
	v_max3_f32 v171, v171, v50, v51
	v_max3_f32 v172, v172, v52, v53
	v_max3_f32 v171, v171, v54, v55
	v_max3_f32 v172, v172, v56, v57
	v_max3_f32 v171, v171, v58, v59
	v_max3_f32 v172, v172, v60, v61
	v_max3_f32 v171, v171, v62, v63
	v_max3_f32 v172, v172, v64, v65
	v_max3_f32 v171, v171, v66, v67
	v_max_f32_e32 v171, v171, v172
	ds_bpermute_b32 v172, v185, v171
	v_mov_b32_e32 v198, v199
	s_waitcnt lgkmcnt(0)
	v_max3_f32 v199, v198, v171, v172
	v_sub_f32_e32 v171, v198, v199
	v_exp_f32_e32 v172, v171
	s_nop 0
	v_cmp_neq_f32_e32 vcc, 1.0, v172
	s_cbranch_vccz .LBB0_789
	v_pk_mul_f32 v[34:35], v[34:35], v[172:173] op_sel_hi:[1,0]
	v_pk_mul_f32 v[32:33], v[32:33], v[172:173] op_sel_hi:[1,0]
	v_pk_mul_f32 v[30:31], v[30:31], v[172:173] op_sel_hi:[1,0]
	v_pk_mul_f32 v[28:29], v[28:29], v[172:173] op_sel_hi:[1,0]
	v_pk_mul_f32 v[26:27], v[26:27], v[172:173] op_sel_hi:[1,0]
	v_pk_mul_f32 v[24:25], v[24:25], v[172:173] op_sel_hi:[1,0]
	v_pk_mul_f32 v[22:23], v[22:23], v[172:173] op_sel_hi:[1,0]
	v_pk_mul_f32 v[20:21], v[20:21], v[172:173] op_sel_hi:[1,0]
	v_pk_mul_f32 v[18:19], v[18:19], v[172:173] op_sel_hi:[1,0]
	v_pk_mul_f32 v[16:17], v[16:17], v[172:173] op_sel_hi:[1,0]
	v_pk_mul_f32 v[14:15], v[14:15], v[172:173] op_sel_hi:[1,0]
	v_pk_mul_f32 v[12:13], v[12:13], v[172:173] op_sel_hi:[1,0]
	v_pk_mul_f32 v[10:11], v[10:11], v[172:173] op_sel_hi:[1,0]
	v_pk_mul_f32 v[8:9], v[8:9], v[172:173] op_sel_hi:[1,0]
	v_pk_mul_f32 v[6:7], v[6:7], v[172:173] op_sel_hi:[1,0]
	v_pk_mul_f32 v[4:5], v[4:5], v[172:173] op_sel_hi:[1,0]

.LBB0_791:
	s_or_b64 exec, exec, s[6:7]
	s_add_i32 s6, s8, -1
	v_min_u32_e32 v67, s6, v194
	s_waitcnt vmcnt(13)
	v_mul_u32_u24_e32 v112, 0xc000, v67
	v_mov_b32_e32 v113, v3
	s_waitcnt vmcnt(12)
	v_lshl_add_u64 v[116:117], v[112:113], 1, v[162:163]
	v_lshlrev_b32_e32 v112, 7, v67
	s_waitcnt vmcnt(10)
	v_lshl_add_u64 v[120:121], v[164:165], 0, v[112:113]
	v_mov_b32_e32 v171, v3
	v_lshl_add_u64 v[112:113], v[156:157], 1, v[116:117]
	v_lshl_add_u64 v[114:115], v[166:167], 1, v[116:117]
	v_lshl_add_u64 v[116:117], v[158:159], 1, v[116:117]
	v_lshl_add_u64 v[122:123], v[120:121], 0, v[2:3]
	v_lshl_add_u64 v[120:121], v[120:121], 0, v[170:171]
	s_waitcnt lgkmcnt(0)
	s_barrier
	global_load_dwordx4 v[128:131], v[112:113], off
	s_nop 0
	global_load_dwordx4 v[112:115], v[114:115], off
	s_nop 0
	global_load_dwordx4 v[116:119], v[116:117], off
	s_nop 0
	global_load_dwordx4 v[124:127], v[122:123], off
	v_add_f32_e32 v52, v198, v52
	global_load_dwordx4 v[120:123], v[120:121], off
	v_add_f32_e32 v52, 0, v52
	v_add_f32_e32 v36, v53, v36
	v_add_f32_e32 v36, v36, v52
	v_add_f32_e32 v37, v54, v37
	v_add_f32_e32 v36, v37, v36
	v_add_f32_e32 v37, v55, v38
	v_add_f32_e32 v36, v37, v36
	v_add_f32_e32 v37, v56, v39
	v_add_f32_e32 v36, v37, v36
	v_add_f32_e32 v37, v57, v40
	v_add_f32_e32 v36, v37, v36
	v_add_f32_e32 v37, v58, v41
	v_add_f32_e32 v36, v37, v36
	v_add_f32_e32 v37, v66, v42
	v_add_f32_e32 v36, v37, v36
	v_add_f32_e32 v37, v44, v43
	v_add_f32_e32 v36, v37, v36
	v_add_f32_e32 v37, v45, v59
	v_add_f32_e32 v36, v37, v36
	v_add_f32_e32 v37, v46, v60
	v_add_f32_e32 v36, v37, v36
	v_add_f32_e32 v37, v47, v61
	v_add_f32_e32 v36, v37, v36
	v_add_f32_e32 v37, v48, v62
	v_add_f32_e32 v36, v37, v36
	v_add_f32_e32 v37, v49, v63
	v_add_f32_e32 v36, v37, v36
	v_add_f32_e32 v37, v50, v64
	v_add_f32_e32 v36, v37, v36
	v_add_f32_e32 v37, v51, v65
	v_add_f32_e32 v198, v37, v36
	v_fmac_f32_e32 v198, v200, v172
	s_and_saveexec_b64 s[6:7], vcc
	s_cbranch_execz .LBB0_795
	ds_read_b128 v[36:39], v196 offset:22016
	ds_read_b128 v[200:203], v196 offset:22048
	s_waitcnt lgkmcnt(1)
	v_mfma_f32_32x32x16_bf16 v[52:67], v[36:39], v[68:71], 0
	ds_read_b128 v[36:39], v196 offset:28672
	ds_read_b128 v[204:207], v196 offset:28704
	s_waitcnt lgkmcnt(1)
	v_mfma_f32_32x32x16_bf16 v[36:51], v[36:39], v[68:71], 0
	v_mfma_f32_32x32x16_bf16 v[52:67], v[200:203], v[72:75], v[52:67]
	s_waitcnt lgkmcnt(0)
	v_mfma_f32_32x32x16_bf16 v[36:51], v[204:207], v[72:75], v[36:51]
	ds_read_b128 v[200:203], v196 offset:22080
	ds_read_b128 v[204:207], v196 offset:22112
	s_waitcnt lgkmcnt(1)
	v_mfma_f32_32x32x16_bf16 v[52:67], v[200:203], v[76:79], v[52:67]
	ds_read_b128 v[200:203], v196 offset:28736
	ds_read_b128 v[208:211], v196 offset:28768
	s_waitcnt lgkmcnt(1)
	v_mfma_f32_32x32x16_bf16 v[36:51], v[200:203], v[76:79], v[36:51]
	v_mfma_f32_32x32x16_bf16 v[52:67], v[204:207], v[80:83], v[52:67]
	ds_read_b128 v[200:203], v196 offset:22144
	ds_read_b128 v[204:207], v196 offset:22176
	s_waitcnt lgkmcnt(2)
	v_mfma_f32_32x32x16_bf16 v[36:51], v[208:211], v[80:83], v[36:51]
	s_waitcnt lgkmcnt(1)
	v_mfma_f32_32x32x16_bf16 v[52:67], v[200:203], v[84:87], v[52:67]
	ds_read_b128 v[200:203], v196 offset:28800
	ds_read_b128 v[208:211], v196 offset:28832
	s_waitcnt lgkmcnt(1)
	v_mfma_f32_32x32x16_bf16 v[36:51], v[200:203], v[84:87], v[36:51]
	s_waitcnt lgkmcnt(0)
	v_mfma_f32_32x32x16_bf16 v[36:51], v[208:211], v[100:103], v[36:51]
	v_mfma_f32_32x32x16_bf16 v[52:67], v[204:207], v[100:103], v[52:67]
	s_nop 10
	v_max3_f32 v171, v36, v37, v38
	v_max3_f32 v172, v39, v40, v41
	v_max3_f32 v171, v171, v42, v43
	v_max3_f32 v172, v172, v44, v45
	v_max3_f32 v171, v171, v46, v47
	v_max3_f32 v172, v172, v48, v49
	v_max3_f32 v171, v171, v50, v51
	v_max3_f32 v172, v172, v52, v53
	v_max3_f32 v171, v171, v54, v55
	v_max3_f32 v172, v172, v56, v57
	v_max3_f32 v171, v171, v58, v59
	v_max3_f32 v172, v172, v60, v61
	v_max3_f32 v171, v171, v62, v63
	v_max3_f32 v172, v172, v64, v65
	v_max3_f32 v171, v171, v66, v67
	v_max_f32_e32 v171, v171, v172
	ds_bpermute_b32 v172, v185, v171
	s_waitcnt lgkmcnt(0)
	v_max3_f32 v171, v199, v171, v172
	v_sub_f32_e32 v172, v199, v171
	v_exp_f32_e32 v172, v172
	s_nop 0
	v_cmp_neq_f32_e32 vcc, 1.0, v172
	s_cbranch_vccz .LBB0_794
	v_pk_mul_f32 v[34:35], v[34:35], v[172:173] op_sel_hi:[1,0]
	v_pk_mul_f32 v[32:33], v[32:33], v[172:173] op_sel_hi:[1,0]
	v_pk_mul_f32 v[30:31], v[30:31], v[172:173] op_sel_hi:[1,0]
	v_pk_mul_f32 v[28:29], v[28:29], v[172:173] op_sel_hi:[1,0]
	v_pk_mul_f32 v[26:27], v[26:27], v[172:173] op_sel_hi:[1,0]
	v_pk_mul_f32 v[24:25], v[24:25], v[172:173] op_sel_hi:[1,0]
	v_pk_mul_f32 v[22:23], v[22:23], v[172:173] op_sel_hi:[1,0]
	v_pk_mul_f32 v[20:21], v[20:21], v[172:173] op_sel_hi:[1,0]
	v_pk_mul_f32 v[18:19], v[18:19], v[172:173] op_sel_hi:[1,0]
	v_pk_mul_f32 v[16:17], v[16:17], v[172:173] op_sel_hi:[1,0]
	v_pk_mul_f32 v[14:15], v[14:15], v[172:173] op_sel_hi:[1,0]
	v_pk_mul_f32 v[12:13], v[12:13], v[172:173] op_sel_hi:[1,0]
	v_pk_mul_f32 v[10:11], v[10:11], v[172:173] op_sel_hi:[1,0]
	v_pk_mul_f32 v[8:9], v[8:9], v[172:173] op_sel_hi:[1,0]
	v_pk_mul_f32 v[6:7], v[6:7], v[172:173] op_sel_hi:[1,0]
	v_pk_mul_f32 v[4:5], v[4:5], v[172:173] op_sel_hi:[1,0]

.LBB0_797:
	s_or_b64 exec, exec, s[6:7]
	v_min_u32_e32 v38, s8, v194
	v_mul_u32_u24_e32 v36, 0xc000, v38
	v_mov_b32_e32 v37, v3
	v_lshl_add_u64 v[36:37], v[36:37], 1, v[162:163]
	v_lshlrev_b32_e32 v38, 7, v38
	v_mov_b32_e32 v39, v3
	v_lshl_add_u64 v[38:39], v[164:165], 0, v[38:39]
	v_lshl_add_u64 v[40:41], v[156:157], 1, v[36:37]
	v_lshl_add_u64 v[42:43], v[166:167], 1, v[36:37]
	v_lshl_add_u64 v[36:37], v[158:159], 1, v[36:37]
	v_mov_b32_e32 v171, v3
	s_waitcnt lgkmcnt(0)
	s_barrier
	global_load_dwordx4 v[88:91], v[40:41], off
	global_load_dwordx4 v[92:95], v[42:43], off
	v_lshl_add_u64 v[40:41], v[38:39], 0, v[2:3]
	global_load_dwordx4 v[104:107], v[36:37], off
	global_load_dwordx4 v[96:99], v[40:41], off
	v_lshl_add_u64 v[36:37], v[38:39], 0, v[170:171]
	global_load_dwordx4 v[108:111], v[36:37], off
	s_and_saveexec_b64 s[6:7], vcc
	s_cbranch_execz .LBB0_801
	ds_read_b128 v[36:39], v196 offset:44032
	ds_read_b128 v[200:203], v196 offset:44064
	s_waitcnt lgkmcnt(1)
	v_mfma_f32_32x32x16_bf16 v[52:67], v[36:39], v[68:71], 0
	ds_read_b128 v[36:39], v196 offset:50688
	ds_read_b128 v[204:207], v196 offset:50720
	s_waitcnt lgkmcnt(1)
	v_mfma_f32_32x32x16_bf16 v[36:51], v[36:39], v[68:71], 0
	v_mfma_f32_32x32x16_bf16 v[52:67], v[200:203], v[72:75], v[52:67]
	s_waitcnt lgkmcnt(0)
	v_mfma_f32_32x32x16_bf16 v[36:51], v[204:207], v[72:75], v[36:51]
	ds_read_b128 v[200:203], v196 offset:44096
	ds_read_b128 v[204:207], v196 offset:44128
	s_waitcnt lgkmcnt(1)
	v_mfma_f32_32x32x16_bf16 v[52:67], v[200:203], v[76:79], v[52:67]
	ds_read_b128 v[200:203], v196 offset:50752
	ds_read_b128 v[208:211], v196 offset:50784
	s_waitcnt lgkmcnt(1)
	v_mfma_f32_32x32x16_bf16 v[36:51], v[200:203], v[76:79], v[36:51]
	v_mfma_f32_32x32x16_bf16 v[52:67], v[204:207], v[80:83], v[52:67]
	ds_read_b128 v[200:203], v196 offset:44160
	ds_read_b128 v[204:207], v196 offset:44192
	s_waitcnt lgkmcnt(2)
	v_mfma_f32_32x32x16_bf16 v[36:51], v[208:211], v[80:83], v[36:51]
	s_waitcnt lgkmcnt(1)
	v_mfma_f32_32x32x16_bf16 v[52:67], v[200:203], v[84:87], v[52:67]
	ds_read_b128 v[200:203], v196 offset:50816
	ds_read_b128 v[208:211], v196 offset:50848
	s_waitcnt lgkmcnt(1)
	v_mfma_f32_32x32x16_bf16 v[36:51], v[200:203], v[84:87], v[36:51]
	s_waitcnt lgkmcnt(0)
	v_mfma_f32_32x32x16_bf16 v[36:51], v[208:211], v[100:103], v[36:51]
	v_mfma_f32_32x32x16_bf16 v[52:67], v[204:207], v[100:103], v[52:67]
	s_nop 10
	v_max3_f32 v2, v36, v37, v38
	v_max3_f32 v170, v39, v40, v41
	v_max3_f32 v2, v2, v42, v43
	v_max3_f32 v170, v170, v44, v45
	v_max3_f32 v2, v2, v46, v47
	v_max3_f32 v170, v170, v48, v49
	v_max3_f32 v2, v2, v50, v51
	v_max3_f32 v170, v170, v52, v53
	v_max3_f32 v2, v2, v54, v55
	v_max3_f32 v170, v170, v56, v57
	v_max3_f32 v2, v2, v58, v59
	v_max3_f32 v170, v170, v60, v61
	v_max3_f32 v2, v2, v62, v63
	v_max3_f32 v170, v170, v64, v65
	v_max3_f32 v2, v2, v66, v67
	v_max_f32_e32 v2, v2, v170
	ds_bpermute_b32 v170, v185, v2
	s_waitcnt lgkmcnt(0)
	v_max3_f32 v170, v199, v2, v170
	v_sub_f32_e32 v2, v199, v170
	v_exp_f32_e32 v2, v2
	s_nop 0
	v_cmp_neq_f32_e32 vcc, 1.0, v2
	s_cbranch_vccz .LBB0_800
	v_pk_mul_f32 v[34:35], v[34:35], v[2:3] op_sel_hi:[1,0]
	v_pk_mul_f32 v[32:33], v[32:33], v[2:3] op_sel_hi:[1,0]
	v_pk_mul_f32 v[30:31], v[30:31], v[2:3] op_sel_hi:[1,0]
	v_pk_mul_f32 v[28:29], v[28:29], v[2:3] op_sel_hi:[1,0]
	v_pk_mul_f32 v[26:27], v[26:27], v[2:3] op_sel_hi:[1,0]
	v_pk_mul_f32 v[24:25], v[24:25], v[2:3] op_sel_hi:[1,0]
	v_pk_mul_f32 v[22:23], v[22:23], v[2:3] op_sel_hi:[1,0]
	v_pk_mul_f32 v[20:21], v[20:21], v[2:3] op_sel_hi:[1,0]
	v_pk_mul_f32 v[18:19], v[18:19], v[2:3] op_sel_hi:[1,0]
	v_pk_mul_f32 v[16:17], v[16:17], v[2:3] op_sel_hi:[1,0]
	v_pk_mul_f32 v[14:15], v[14:15], v[2:3] op_sel_hi:[1,0]
	v_pk_mul_f32 v[12:13], v[12:13], v[2:3] op_sel_hi:[1,0]
	v_pk_mul_f32 v[10:11], v[10:11], v[2:3] op_sel_hi:[1,0]
	v_pk_mul_f32 v[8:9], v[8:9], v[2:3] op_sel_hi:[1,0]
	v_pk_mul_f32 v[6:7], v[6:7], v[2:3] op_sel_hi:[1,0]
	v_pk_mul_f32 v[4:5], v[4:5], v[2:3] op_sel_hi:[1,0]

.LBB0_960:
	ds_read_b128 v[194:197], v251
	ds_read_b128 v[198:201], v249
	ds_read_b128 v[202:205], v251 offset:4096
	ds_read_b128 v[206:209], v249 offset:4096
	ds_read_b128 v[162:165], v255
	ds_read_b128 v[166:169], v253
	ds_read_b128 v[170:173], v255 offset:4096
	ds_read_b128 v[174:177], v253 offset:4096
	s_cmp_eq_u32 s98, 0
	s_cbranch_scc1 .Lnodef_G0_1
	v_mfma_f32_16x16x32_bf16 v[98:101], v[210:213], v[178:181], v[98:101]
	v_mfma_f32_16x16x32_bf16 v[94:97], v[214:217], v[178:181], v[94:97]
	v_mfma_f32_16x16x32_bf16 v[90:93], v[218:221], v[178:181], v[90:93]
	v_mfma_f32_16x16x32_bf16 v[86:89], v[222:225], v[178:181], v[86:89]
	v_mfma_f32_16x16x32_bf16 v[78:81], v[210:213], v[182:185], v[78:81]
	v_mfma_f32_16x16x32_bf16 v[74:77], v[214:217], v[182:185], v[74:77]
	v_mfma_f32_16x16x32_bf16 v[70:73], v[218:221], v[182:185], v[70:73]
	v_mfma_f32_16x16x32_bf16 v[66:69], v[222:225], v[182:185], v[66:69]
	v_mfma_f32_16x16x32_bf16 v[62:65], v[210:213], v[186:189], v[62:65]
	v_mfma_f32_16x16x32_bf16 v[58:61], v[214:217], v[186:189], v[58:61]
	v_mfma_f32_16x16x32_bf16 v[54:57], v[218:221], v[186:189], v[54:57]
	v_mfma_f32_16x16x32_bf16 v[50:53], v[222:225], v[186:189], v[50:53]
	v_mfma_f32_16x16x32_bf16 v[46:49], v[210:213], v[190:193], v[46:49]
	v_mfma_f32_16x16x32_bf16 v[42:45], v[214:217], v[190:193], v[42:45]
	v_mfma_f32_16x16x32_bf16 v[38:41], v[218:221], v[190:193], v[38:41]
	v_mfma_f32_16x16x32_bf16 v[34:37], v[222:225], v[190:193], v[34:37]
.Lnodef_G0_1:
	ds_read_b128 v[186:189], v255 offset:12288
	ds_read_b128 v[182:185], v253 offset:8192
	ds_read_b128 v[178:181], v255 offset:8192
	ds_read_b128 v[190:193], v253 offset:12288
	s_add_i32 s2, s42, -1
	s_cmp_lt_i32 s2, s37
	s_cselect_b64 s[24:25], -1, 0
	s_cmp_ge_i32 s2, s37
	s_waitcnt lgkmcnt(7)
	v_mfma_f32_16x16x32_bf16 v[158:161], v[194:197], v[162:165], v[158:161]
	v_mfma_f32_16x16x32_bf16 v[154:157], v[198:201], v[162:165], v[154:157]
	v_mfma_f32_16x16x32_bf16 v[150:153], v[202:205], v[162:165], v[150:153]
	v_mfma_f32_16x16x32_bf16 v[146:149], v[206:209], v[162:165], v[146:149]
	ds_read_b128 v[162:165], v247
	s_waitcnt lgkmcnt(7)
	v_mfma_f32_16x16x32_bf16 v[142:145], v[194:197], v[166:169], v[142:145]
	v_mfma_f32_16x16x32_bf16 v[138:141], v[198:201], v[166:169], v[138:141]
	v_mfma_f32_16x16x32_bf16 v[134:137], v[202:205], v[166:169], v[134:137]
	v_mfma_f32_16x16x32_bf16 v[130:133], v[206:209], v[166:169], v[130:133]
	s_waitcnt vmcnt(6)
	ds_write_b128 v235, v[30:33]
	ds_write_b128 v235, v[26:29] offset:8192
.LBB0_962:
	s_lshl_b32 s6, s51, 8
	s_ashr_i32 s7, s6, 31
	s_lshl_b32 s2, s28, 6
	s_ashr_i32 s3, s2, 31
	s_lshl_b64 s[22:23], s[6:7], 11
	s_add_u32 s26, s31, s22
	s_addc_u32 s27, s33, s23
	s_lshl_b64 s[22:23], s[2:3], 1
	s_add_u32 s26, s26, s22
	s_addc_u32 s27, s27, s23
	global_load_dwordx4 v[30:33], v233, s[26:27]
	global_load_dwordx4 v[26:29], v234, s[26:27]
	s_andn2_b64 vcc, exec, s[24:25]
	ds_read_b128 v[166:169], v245
	s_waitcnt lgkmcnt(9)
	v_mfma_f32_16x16x32_bf16 v[126:129], v[194:197], v[170:173], v[126:129]
	v_mfma_f32_16x16x32_bf16 v[122:125], v[198:201], v[170:173], v[122:125]
	v_mfma_f32_16x16x32_bf16 v[118:121], v[202:205], v[170:173], v[118:121]
	v_mfma_f32_16x16x32_bf16 v[114:117], v[206:209], v[170:173], v[114:117]
	ds_read_b128 v[170:173], v247 offset:4096
	s_waitcnt lgkmcnt(9)
	v_mfma_f32_16x16x32_bf16 v[110:113], v[194:197], v[174:177], v[110:113]
	v_mfma_f32_16x16x32_bf16 v[106:109], v[198:201], v[174:177], v[106:109]
	v_mfma_f32_16x16x32_bf16 v[102:105], v[202:205], v[174:177], v[102:105]
	v_mfma_f32_16x16x32_bf16 v[82:85], v[206:209], v[174:177], v[82:85]
	ds_read_b128 v[210:213], v243
	ds_read_b128 v[214:217], v241
	ds_read_b128 v[218:221], v243 offset:4096
	ds_read_b128 v[222:225], v241 offset:4096
	ds_read_b128 v[174:177], v245 offset:4096
	s_waitcnt lgkmcnt(11)
	v_mfma_f32_16x16x32_bf16 v[98:101], v[194:197], v[178:181], v[98:101]
	v_mfma_f32_16x16x32_bf16 v[94:97], v[198:201], v[178:181], v[94:97]
	v_mfma_f32_16x16x32_bf16 v[90:93], v[202:205], v[178:181], v[90:93]
	v_mfma_f32_16x16x32_bf16 v[86:89], v[206:209], v[178:181], v[86:89]
	s_waitcnt vmcnt(6)
	ds_write_b128 v235, v[22:25] offset:16384
	ds_write_b128 v235, v[18:21] offset:24576
.LBB0_964:
	global_load_dwordx4 v[18:21], v232, s[26:27]
	global_load_dwordx4 v[22:25], v231, s[26:27]
	s_and_b64 vcc, exec, s[2:3]
	ds_read_b128 v[178:181], v247 offset:8192
	v_mfma_f32_16x16x32_bf16 v[78:81], v[194:197], v[182:185], v[78:81]
	v_mfma_f32_16x16x32_bf16 v[74:77], v[198:201], v[182:185], v[74:77]
	v_mfma_f32_16x16x32_bf16 v[70:73], v[202:205], v[182:185], v[70:73]
	v_mfma_f32_16x16x32_bf16 v[66:69], v[206:209], v[182:185], v[66:69]
	s_waitcnt lgkmcnt(10)
	ds_read_b128 v[182:185], v245 offset:8192
	v_mfma_f32_16x16x32_bf16 v[62:65], v[194:197], v[186:189], v[62:65]
	v_mfma_f32_16x16x32_bf16 v[58:61], v[198:201], v[186:189], v[58:61]
	v_mfma_f32_16x16x32_bf16 v[54:57], v[202:205], v[186:189], v[54:57]
	v_mfma_f32_16x16x32_bf16 v[50:53], v[206:209], v[186:189], v[50:53]
	s_waitcnt vmcnt(6)
	ds_write_b128 v235, v[14:17] offset:32768
	ds_write_b128 v235, v[10:13] offset:40960
.LBB0_966:
	s_lshl_b32 s24, s50, 8
	s_ashr_i32 s25, s24, 31
	s_lshl_b64 s[26:27], s[24:25], 11
	s_add_u32 s26, s34, s26
	s_addc_u32 s27, s35, s27
	s_add_u32 s22, s26, s22
	s_addc_u32 s23, s27, s23
	global_load_dwordx4 v[10:13], v234, s[22:23]
	global_load_dwordx4 v[14:17], v233, s[22:23]
	s_and_b64 vcc, exec, s[2:3]
	ds_read_b128 v[186:189], v247 offset:12288
	v_mfma_f32_16x16x32_bf16 v[46:49], v[194:197], v[190:193], v[46:49]
	v_mfma_f32_16x16x32_bf16 v[42:45], v[198:201], v[190:193], v[42:45]
	v_mfma_f32_16x16x32_bf16 v[38:41], v[202:205], v[190:193], v[38:41]
	v_mfma_f32_16x16x32_bf16 v[34:37], v[206:209], v[190:193], v[34:37]
	s_waitcnt lgkmcnt(10)
	ds_read_b128 v[190:193], v245 offset:12288
	s_waitcnt lgkmcnt(9)
	v_mfma_f32_16x16x32_bf16 v[158:161], v[210:213], v[162:165], v[158:161]
	v_mfma_f32_16x16x32_bf16 v[154:157], v[214:217], v[162:165], v[154:157]
	v_mfma_f32_16x16x32_bf16 v[150:153], v[218:221], v[162:165], v[150:153]
	v_mfma_f32_16x16x32_bf16 v[146:149], v[222:225], v[162:165], v[146:149]
	v_mfma_f32_16x16x32_bf16 v[142:145], v[210:213], v[166:169], v[142:145]
	v_mfma_f32_16x16x32_bf16 v[138:141], v[214:217], v[166:169], v[138:141]
	v_mfma_f32_16x16x32_bf16 v[134:137], v[218:221], v[166:169], v[134:137]
	v_mfma_f32_16x16x32_bf16 v[130:133], v[222:225], v[166:169], v[130:133]
	s_waitcnt vmcnt(6)
	ds_write_b128 v235, v[6:9] offset:49152
	ds_write_b128 v235, v[2:5] offset:57344
.LBB0_968:
	global_load_dwordx4 v[2:5], v232, s[22:23]
	global_load_dwordx4 v[6:9], v231, s[22:23]
	v_mfma_f32_16x16x32_bf16 v[126:129], v[210:213], v[170:173], v[126:129]
	v_mfma_f32_16x16x32_bf16 v[122:125], v[214:217], v[170:173], v[122:125]
	v_mfma_f32_16x16x32_bf16 v[118:121], v[218:221], v[170:173], v[118:121]
	v_mfma_f32_16x16x32_bf16 v[114:117], v[222:225], v[170:173], v[114:117]
	s_waitcnt lgkmcnt(10)
	v_mfma_f32_16x16x32_bf16 v[110:113], v[210:213], v[174:177], v[110:113]
	v_mfma_f32_16x16x32_bf16 v[106:109], v[214:217], v[174:177], v[106:109]
	v_mfma_f32_16x16x32_bf16 v[102:105], v[218:221], v[174:177], v[102:105]
	v_mfma_f32_16x16x32_bf16 v[82:85], v[222:225], v[174:177], v[82:85]
	s_lshl_b64 s[2:3], s[6:7], 10
	s_lshl_b64 s[22:23], s[24:25], 10
	s_add_i32 s53, s28, 1
	s_cmp_lg_u32 s53, 16
	s_cbranch_scc1 .LBB0_972
	s_add_i32 s30, s30, s11
	s_cmp_gt_i32 s30, 31
	s_cbranch_scc1 .LBB0_971
	s_ashr_i32 s3, s30, 31
	s_lshr_b32 s3, s3, 27
	s_add_i32 s3, s30, s3
	s_ashr_i32 s3, s3, 5
	s_mov_b32 s2, s10
	s_lshl_b32 s6, s3, 6
	s_lshl_b32 s7, s30, 1
	s_sub_i32 s6, s7, s6
	s_and_b32 s2, s2, 7
	s_and_b32 s6, s6, -8
	s_lshl_b32 s3, s3, 2
	s_and_b32 s7, s30, 3
	s_or_b32 s50, s3, s7
	s_or_b32 s51, s2, s6
	s_lshl_b32 s2, s51, 8
	s_lshl_b32 s6, s50, 8
	s_ashr_i32 s3, s2, 31
	s_ashr_i32 s7, s6, 31
	s_lshl_b64 s[2:3], s[2:3], 10
	s_lshl_b64 s[22:23], s[6:7], 10

.LBB0_972:
	s_waitcnt lgkmcnt(0)
	s_barrier
	ds_read_b128 v[194:197], v250
	ds_read_b128 v[198:201], v248
	ds_read_b128 v[202:205], v250 offset:4096
	ds_read_b128 v[206:209], v248 offset:4096
	ds_read_b128 v[162:165], v254
	ds_read_b128 v[166:169], v252
	ds_read_b128 v[170:173], v254 offset:4096
	ds_read_b128 v[174:177], v252 offset:4096
	v_mfma_f32_16x16x32_bf16 v[98:101], v[210:213], v[178:181], v[98:101]
	v_mfma_f32_16x16x32_bf16 v[94:97], v[214:217], v[178:181], v[94:97]
	v_mfma_f32_16x16x32_bf16 v[90:93], v[218:221], v[178:181], v[90:93]
	v_mfma_f32_16x16x32_bf16 v[86:89], v[222:225], v[178:181], v[86:89]
	v_mfma_f32_16x16x32_bf16 v[78:81], v[210:213], v[182:185], v[78:81]
	v_mfma_f32_16x16x32_bf16 v[74:77], v[214:217], v[182:185], v[74:77]
	v_mfma_f32_16x16x32_bf16 v[70:73], v[218:221], v[182:185], v[70:73]
	v_mfma_f32_16x16x32_bf16 v[66:69], v[222:225], v[182:185], v[66:69]
	v_mfma_f32_16x16x32_bf16 v[62:65], v[210:213], v[186:189], v[62:65]
	v_mfma_f32_16x16x32_bf16 v[58:61], v[214:217], v[186:189], v[58:61]
	v_mfma_f32_16x16x32_bf16 v[54:57], v[218:221], v[186:189], v[54:57]
	v_mfma_f32_16x16x32_bf16 v[50:53], v[222:225], v[186:189], v[50:53]
	v_mfma_f32_16x16x32_bf16 v[46:49], v[210:213], v[190:193], v[46:49]
	v_mfma_f32_16x16x32_bf16 v[42:45], v[214:217], v[190:193], v[42:45]
	v_mfma_f32_16x16x32_bf16 v[38:41], v[218:221], v[190:193], v[38:41]
	v_mfma_f32_16x16x32_bf16 v[34:37], v[222:225], v[190:193], v[34:37]
	ds_read_b128 v[186:189], v254 offset:12288
	ds_read_b128 v[182:185], v252 offset:8192
	ds_read_b128 v[178:181], v254 offset:8192
	ds_read_b128 v[190:193], v252 offset:12288
	s_cmp_lt_i32 s42, s37
	s_cselect_b64 s[26:27], -1, 0
	s_cmp_ge_i32 s42, s37
	s_cselect_b64 s[6:7], -1, 0
	s_and_b64 vcc, exec, s[6:7]
	s_waitcnt lgkmcnt(7)
	v_mfma_f32_16x16x32_bf16 v[158:161], v[194:197], v[162:165], v[158:161]
	v_mfma_f32_16x16x32_bf16 v[154:157], v[198:201], v[162:165], v[154:157]
	v_mfma_f32_16x16x32_bf16 v[150:153], v[202:205], v[162:165], v[150:153]
	v_mfma_f32_16x16x32_bf16 v[146:149], v[206:209], v[162:165], v[146:149]
	ds_read_b128 v[162:165], v246
	s_waitcnt lgkmcnt(7)
	v_mfma_f32_16x16x32_bf16 v[142:145], v[194:197], v[166:169], v[142:145]
	v_mfma_f32_16x16x32_bf16 v[138:141], v[198:201], v[166:169], v[138:141]
	v_mfma_f32_16x16x32_bf16 v[134:137], v[202:205], v[166:169], v[134:137]
	v_mfma_f32_16x16x32_bf16 v[130:133], v[206:209], v[166:169], v[130:133]
	s_waitcnt vmcnt(6)
	ds_write_b128 v236, v[26:29]
	ds_write_b128 v236, v[30:33] offset:8192
.LBB0_974:
	s_lshl_b32 s24, s53, 6
	s_ashr_i32 s25, s24, 31
	s_lshl_b64 s[2:3], s[2:3], 1
	s_add_u32 s2, s31, s2
	s_addc_u32 s3, s33, s3
	s_lshl_b64 s[24:25], s[24:25], 1
	s_add_u32 s28, s2, s24
	s_addc_u32 s29, s3, s25
	global_load_dwordx4 v[30:33], v234, s[28:29]
	global_load_dwordx4 v[26:29], v233, s[28:29]
	s_andn2_b64 vcc, exec, s[26:27]
	ds_read_b128 v[166:169], v244
	s_waitcnt lgkmcnt(9)
	v_mfma_f32_16x16x32_bf16 v[126:129], v[194:197], v[170:173], v[126:129]
	v_mfma_f32_16x16x32_bf16 v[122:125], v[198:201], v[170:173], v[122:125]
	v_mfma_f32_16x16x32_bf16 v[118:121], v[202:205], v[170:173], v[118:121]
	v_mfma_f32_16x16x32_bf16 v[114:117], v[206:209], v[170:173], v[114:117]
	ds_read_b128 v[170:173], v246 offset:4096
	s_waitcnt lgkmcnt(9)
	v_mfma_f32_16x16x32_bf16 v[110:113], v[194:197], v[174:177], v[110:113]
	v_mfma_f32_16x16x32_bf16 v[106:109], v[198:201], v[174:177], v[106:109]
	v_mfma_f32_16x16x32_bf16 v[102:105], v[202:205], v[174:177], v[102:105]
	v_mfma_f32_16x16x32_bf16 v[82:85], v[206:209], v[174:177], v[82:85]
	ds_read_b128 v[210:213], v242
	ds_read_b128 v[214:217], v237
	ds_read_b128 v[218:221], v242 offset:4096
	ds_read_b128 v[222:225], v237 offset:4096
	ds_read_b128 v[174:177], v244 offset:4096
	s_waitcnt lgkmcnt(11)
	v_mfma_f32_16x16x32_bf16 v[98:101], v[194:197], v[178:181], v[98:101]
	v_mfma_f32_16x16x32_bf16 v[94:97], v[198:201], v[178:181], v[94:97]
	v_mfma_f32_16x16x32_bf16 v[90:93], v[202:205], v[178:181], v[90:93]
	v_mfma_f32_16x16x32_bf16 v[86:89], v[206:209], v[178:181], v[86:89]
	s_waitcnt vmcnt(6)
	ds_write_b128 v236, v[18:21] offset:16384
	ds_write_b128 v236, v[22:25] offset:24576
.LBB0_976:
	global_load_dwordx4 v[22:25], v232, s[28:29]
	global_load_dwordx4 v[18:21], v231, s[28:29]
	s_and_b64 vcc, exec, s[2:3]
	ds_read_b128 v[178:181], v246 offset:8192
	v_mfma_f32_16x16x32_bf16 v[78:81], v[194:197], v[182:185], v[78:81]
	v_mfma_f32_16x16x32_bf16 v[74:77], v[198:201], v[182:185], v[74:77]
	v_mfma_f32_16x16x32_bf16 v[70:73], v[202:205], v[182:185], v[70:73]
	v_mfma_f32_16x16x32_bf16 v[66:69], v[206:209], v[182:185], v[66:69]
	s_waitcnt lgkmcnt(10)
	ds_read_b128 v[182:185], v244 offset:8192
	v_mfma_f32_16x16x32_bf16 v[62:65], v[194:197], v[186:189], v[62:65]
	v_mfma_f32_16x16x32_bf16 v[58:61], v[198:201], v[186:189], v[58:61]
	v_mfma_f32_16x16x32_bf16 v[54:57], v[202:205], v[186:189], v[54:57]
	v_mfma_f32_16x16x32_bf16 v[50:53], v[206:209], v[186:189], v[50:53]
	s_waitcnt vmcnt(6)
	ds_write_b128 v236, v[10:13] offset:32768
	ds_write_b128 v236, v[14:17] offset:40960
.LBB0_978:
	s_lshl_b64 s[22:23], s[22:23], 1
	s_add_u32 s22, s34, s22
	s_addc_u32 s23, s35, s23
	s_add_u32 s22, s22, s24
	s_addc_u32 s23, s23, s25
	global_load_dwordx4 v[14:17], v234, s[22:23]
	global_load_dwordx4 v[10:13], v233, s[22:23]
	s_and_b64 vcc, exec, s[2:3]
	ds_read_b128 v[186:189], v246 offset:12288
	v_mfma_f32_16x16x32_bf16 v[46:49], v[194:197], v[190:193], v[46:49]
	v_mfma_f32_16x16x32_bf16 v[42:45], v[198:201], v[190:193], v[42:45]
	v_mfma_f32_16x16x32_bf16 v[38:41], v[202:205], v[190:193], v[38:41]
	v_mfma_f32_16x16x32_bf16 v[34:37], v[206:209], v[190:193], v[34:37]
	s_waitcnt lgkmcnt(10)
	ds_read_b128 v[190:193], v244 offset:12288
	s_waitcnt lgkmcnt(9)
	v_mfma_f32_16x16x32_bf16 v[158:161], v[210:213], v[162:165], v[158:161]
	v_mfma_f32_16x16x32_bf16 v[154:157], v[214:217], v[162:165], v[154:157]
	v_mfma_f32_16x16x32_bf16 v[150:153], v[218:221], v[162:165], v[150:153]
	v_mfma_f32_16x16x32_bf16 v[146:149], v[222:225], v[162:165], v[146:149]
	v_mfma_f32_16x16x32_bf16 v[142:145], v[210:213], v[166:169], v[142:145]
	v_mfma_f32_16x16x32_bf16 v[138:141], v[214:217], v[166:169], v[138:141]
	v_mfma_f32_16x16x32_bf16 v[134:137], v[218:221], v[166:169], v[134:137]
	v_mfma_f32_16x16x32_bf16 v[130:133], v[222:225], v[166:169], v[130:133]
	s_waitcnt vmcnt(6)
	ds_write_b128 v236, v[2:5] offset:49152
	ds_write_b128 v236, v[6:9] offset:57344
.LBB0_980:
	global_load_dwordx4 v[6:9], v232, s[22:23]
	global_load_dwordx4 v[2:5], v231, s[22:23]
	v_mfma_f32_16x16x32_bf16 v[126:129], v[210:213], v[170:173], v[126:129]
	v_mfma_f32_16x16x32_bf16 v[122:125], v[214:217], v[170:173], v[122:125]
	v_mfma_f32_16x16x32_bf16 v[118:121], v[218:221], v[170:173], v[118:121]
	v_mfma_f32_16x16x32_bf16 v[114:117], v[222:225], v[170:173], v[114:117]
	s_waitcnt lgkmcnt(10)
	v_mfma_f32_16x16x32_bf16 v[110:113], v[210:213], v[174:177], v[110:113]
	v_mfma_f32_16x16x32_bf16 v[106:109], v[214:217], v[174:177], v[106:109]
	v_mfma_f32_16x16x32_bf16 v[102:105], v[218:221], v[174:177], v[102:105]
	v_mfma_f32_16x16x32_bf16 v[82:85], v[222:225], v[174:177], v[82:85]
	s_add_i32 s28, s53, 1
	s_cmp_lg_u32 s28, 16
	s_cbranch_scc1 .LBB0_984
	s_add_i32 s30, s30, s11
	s_cmp_gt_i32 s30, 31
	s_cbranch_scc1 .LBB0_983
	s_ashr_i32 s3, s30, 31
	s_lshr_b32 s3, s3, 27
	s_add_i32 s3, s30, s3
	s_ashr_i32 s3, s3, 5
	s_mov_b32 s2, s10
	s_lshl_b32 s22, s3, 6
	s_lshl_b32 s23, s30, 1
	s_sub_i32 s22, s23, s22
	s_and_b32 s2, s2, 7
	s_and_b32 s22, s22, -8
	s_lshl_b32 s3, s3, 2
	s_and_b32 s23, s30, 3
	s_or_b32 s50, s3, s23
	s_or_b32 s51, s2, s22

.LBB0_984:
	s_add_i32 s52, s52, 2
	s_cmp_lg_u32 s52, 16
	s_waitcnt lgkmcnt(0)
	s_mov_b32 s98, 1
	s_cbranch_scc1 .LBB0_959
	s_mov_b32 s98, 0
	v_mfma_f32_16x16x32_bf16 v[98:101], v[210:213], v[178:181], v[98:101]
	v_mfma_f32_16x16x32_bf16 v[94:97], v[214:217], v[178:181], v[94:97]
	v_mfma_f32_16x16x32_bf16 v[90:93], v[218:221], v[178:181], v[90:93]
	v_mfma_f32_16x16x32_bf16 v[86:89], v[222:225], v[178:181], v[86:89]
	v_mfma_f32_16x16x32_bf16 v[78:81], v[210:213], v[182:185], v[78:81]
	v_mfma_f32_16x16x32_bf16 v[74:77], v[214:217], v[182:185], v[74:77]
	v_mfma_f32_16x16x32_bf16 v[70:73], v[218:221], v[182:185], v[70:73]
	v_mfma_f32_16x16x32_bf16 v[66:69], v[222:225], v[182:185], v[66:69]
	v_mfma_f32_16x16x32_bf16 v[62:65], v[210:213], v[186:189], v[62:65]
	v_mfma_f32_16x16x32_bf16 v[58:61], v[214:217], v[186:189], v[58:61]
	v_mfma_f32_16x16x32_bf16 v[54:57], v[218:221], v[186:189], v[54:57]
	v_mfma_f32_16x16x32_bf16 v[50:53], v[222:225], v[186:189], v[50:53]
	v_mfma_f32_16x16x32_bf16 v[46:49], v[210:213], v[190:193], v[46:49]
	v_mfma_f32_16x16x32_bf16 v[42:45], v[214:217], v[190:193], v[42:45]
	v_mfma_f32_16x16x32_bf16 v[38:41], v[218:221], v[190:193], v[38:41]
	v_mfma_f32_16x16x32_bf16 v[34:37], v[222:225], v[190:193], v[34:37]
	s_nop 7
	s_nop 7
	v_mov_b32_e32 v172, v0
	s_nop 0
	v_ashrrev_i32_e32 v162, 1, v172
	v_and_b32_e32 v162, 0xffffff80, v162
	v_lshl_add_u32 v162, s38, 8, v162
	v_and_or_b32 v164, v172, 15, v162
	v_add_u32_e32 v162, 0xffffe000, v162
	v_ashrrev_i32_e32 v162, 11, v162
	v_mad_i32_i24 v162, v162, s47, s47
	v_cmp_lt_i32_e32 vcc, s48, v164
	v_ashrrev_i32_e32 v163, 31, v162
	s_and_saveexec_b64 s[2:3], vcc
	s_xor_b64 s[2:3], exec, s[2:3]
	v_add_u32_e32 v238, 0xffffe000, v164
	v_lshlrev_b64 v[166:167], 12, v[238:239]
	v_mov_b32_e32 v165, v239
	v_lshl_add_u64 v[168:169], s[14:15], 0, v[166:167]
	v_lshlrev_b64 v[170:171], 12, v[164:165]
	v_mov_b64_e32 v[166:167], v[162:163]
	s_andn2_saveexec_b64 s[2:3], s[2:3]
	v_ashrrev_i32_e32 v165, 31, v164
	v_lshlrev_b64 v[170:171], 12, v[164:165]
	v_lshl_add_u64 v[168:169], s[12:13], 0, v[170:171]
	v_mov_b64_e32 v[166:167], 0
	s_or_b64 exec, exec, s[2:3]
	v_and_b32_e32 v165, 0xc0, v172
	v_lshrrev_b32_e32 v172, 2, v172
	s_lshl_b32 s2, s36, 8
	v_and_b32_e32 v172, 12, v172
	v_or3_b32 v172, v165, s2, v172
	v_ashrrev_i32_e32 v173, 31, v172
	v_lshl_add_u64 v[176:177], v[166:167], 2, s[20:21]
	v_lshlrev_b64 v[166:167], 2, v[172:173]
	v_lshl_add_u64 v[180:181], v[168:169], 0, v[166:167]
	v_lshl_add_u64 v[182:183], v[176:177], 0, v[166:167]
	global_load_dwordx4 v[172:175], v[180:181], off
	global_load_dwordx4 v[176:179], v[182:183], off
	v_lshl_add_u64 v[168:169], s[4:5], 0, v[170:171]
	v_lshl_add_u64 v[184:185], v[168:169], 0, v[166:167]
	s_waitcnt vmcnt(0)
	v_pk_fma_f32 v[160:161], v[160:161], v[178:179], v[174:175]
	v_pk_fma_f32 v[158:159], v[158:159], v[176:177], v[172:173]
	global_store_dwordx4 v[184:185], v[158:161], off
	global_load_dwordx4 v[158:161], v[180:181], off offset:64
	s_nop 0
	global_load_dwordx4 v[168:171], v[182:183], off offset:64
	s_waitcnt vmcnt(0)
	v_pk_fma_f32 v[156:157], v[156:157], v[170:171], v[160:161]
	v_pk_fma_f32 v[154:155], v[154:155], v[168:169], v[158:159]
	global_store_dwordx4 v[184:185], v[154:157], off offset:64
	global_load_dwordx4 v[154:157], v[180:181], off offset:128
	s_nop 0
	global_load_dwordx4 v[158:161], v[182:183], off offset:128
	s_waitcnt vmcnt(0)
	v_pk_fma_f32 v[152:153], v[152:153], v[160:161], v[156:157]
	v_pk_fma_f32 v[150:151], v[150:151], v[158:159], v[154:155]
	global_store_dwordx4 v[184:185], v[150:153], off offset:128
	global_load_dwordx4 v[152:155], v[180:181], off offset:192
	s_nop 0
	global_load_dwordx4 v[156:159], v[182:183], off offset:192
	v_or_b32_e32 v150, 16, v164
	v_cmp_lt_i32_e32 vcc, s48, v150
	s_waitcnt vmcnt(0)
	v_pk_fma_f32 v[148:149], v[148:149], v[158:159], v[154:155]
	v_pk_fma_f32 v[146:147], v[146:147], v[156:157], v[152:153]
	global_store_dwordx4 v[184:185], v[146:149], off offset:192
	s_and_saveexec_b64 s[2:3], vcc
	s_xor_b64 s[2:3], exec, s[2:3]
	v_add_u32_e32 v238, 0xffffe010, v164
	v_lshlrev_b64 v[146:147], 12, v[238:239]
	v_mov_b32_e32 v151, v239
	v_lshl_add_u64 v[146:147], s[14:15], 0, v[146:147]
	v_lshlrev_b64 v[148:149], 12, v[150:151]
	v_mov_b64_e32 v[152:153], v[162:163]
	s_andn2_saveexec_b64 s[2:3], s[2:3]
	v_ashrrev_i32_e32 v151, 31, v150
	v_lshlrev_b64 v[148:149], 12, v[150:151]
	v_lshl_add_u64 v[146:147], s[12:13], 0, v[148:149]
	v_mov_b64_e32 v[152:153], 0
	s_or_b64 exec, exec, s[2:3]
	v_lshl_add_u64 v[154:155], v[152:153], 2, s[20:21]
	v_lshl_add_u64 v[158:159], v[146:147], 0, v[166:167]
	v_lshl_add_u64 v[160:161], v[154:155], 0, v[166:167]
	global_load_dwordx4 v[150:153], v[158:159], off
	global_load_dwordx4 v[154:157], v[160:161], off
	v_lshl_add_u64 v[146:147], s[4:5], 0, v[148:149]
	v_lshl_add_u64 v[168:169], v[146:147], 0, v[166:167]
	s_waitcnt vmcnt(0)
	v_pk_fma_f32 v[144:145], v[144:145], v[156:157], v[152:153]
	v_pk_fma_f32 v[142:143], v[142:143], v[154:155], v[150:151]
	global_store_dwordx4 v[168:169], v[142:145], off
	global_load_dwordx4 v[142:145], v[158:159], off offset:64
	s_nop 0
	global_load_dwordx4 v[146:149], v[160:161], off offset:64
	s_waitcnt vmcnt(0)
	v_pk_fma_f32 v[140:141], v[140:141], v[148:149], v[144:145]
	v_pk_fma_f32 v[138:139], v[138:139], v[146:147], v[142:143]
	global_store_dwordx4 v[168:169], v[138:141], off offset:64
	global_load_dwordx4 v[138:141], v[158:159], off offset:128
	s_nop 0
	global_load_dwordx4 v[142:145], v[160:161], off offset:128
	s_waitcnt vmcnt(0)
	v_pk_fma_f32 v[136:137], v[136:137], v[144:145], v[140:141]
	v_pk_fma_f32 v[134:135], v[134:135], v[142:143], v[138:139]
	global_store_dwordx4 v[168:169], v[134:137], off offset:128
	global_load_dwordx4 v[136:139], v[158:159], off offset:192
	s_nop 0
	global_load_dwordx4 v[140:143], v[160:161], off offset:192
	v_or_b32_e32 v134, 32, v164
	v_cmp_lt_i32_e32 vcc, s48, v134
	s_waitcnt vmcnt(0)
	v_pk_fma_f32 v[132:133], v[132:133], v[142:143], v[138:139]
	v_pk_fma_f32 v[130:131], v[130:131], v[140:141], v[136:137]
	global_store_dwordx4 v[168:169], v[130:133], off offset:192
	s_and_saveexec_b64 s[2:3], vcc
	s_xor_b64 s[2:3], exec, s[2:3]
	v_add_u32_e32 v238, 0xffffe020, v164
	v_lshlrev_b64 v[130:131], 12, v[238:239]
	v_mov_b32_e32 v135, v239
	v_lshl_add_u64 v[130:131], s[14:15], 0, v[130:131]
	v_lshlrev_b64 v[132:133], 12, v[134:135]
	v_mov_b64_e32 v[136:137], v[162:163]
	s_andn2_saveexec_b64 s[2:3], s[2:3]
	v_ashrrev_i32_e32 v135, 31, v134
	v_lshlrev_b64 v[132:133], 12, v[134:135]
	v_lshl_add_u64 v[130:131], s[12:13], 0, v[132:133]
	v_mov_b64_e32 v[136:137], 0
	s_or_b64 exec, exec, s[2:3]
	v_lshl_add_u64 v[138:139], v[136:137], 2, s[20:21]
	v_lshl_add_u64 v[142:143], v[130:131], 0, v[166:167]
	v_lshl_add_u64 v[144:145], v[138:139], 0, v[166:167]
	global_load_dwordx4 v[134:137], v[142:143], off
	global_load_dwordx4 v[138:141], v[144:145], off
	v_lshl_add_u64 v[130:131], s[4:5], 0, v[132:133]
	v_lshl_add_u64 v[146:147], v[130:131], 0, v[166:167]
	s_waitcnt vmcnt(0)
	v_pk_fma_f32 v[128:129], v[128:129], v[140:141], v[136:137]
	v_pk_fma_f32 v[126:127], v[126:127], v[138:139], v[134:135]
	global_store_dwordx4 v[146:147], v[126:129], off
	global_load_dwordx4 v[126:129], v[142:143], off offset:64
	s_nop 0
	global_load_dwordx4 v[130:133], v[144:145], off offset:64
	s_waitcnt vmcnt(0)
	v_pk_fma_f32 v[124:125], v[124:125], v[132:133], v[128:129]
	v_pk_fma_f32 v[122:123], v[122:123], v[130:131], v[126:127]
	global_store_dwordx4 v[146:147], v[122:125], off offset:64
	global_load_dwordx4 v[122:125], v[142:143], off offset:128
	s_nop 0
	global_load_dwordx4 v[126:129], v[144:145], off offset:128
	s_waitcnt vmcnt(0)
	v_pk_fma_f32 v[120:121], v[120:121], v[128:129], v[124:125]
	v_pk_fma_f32 v[118:119], v[118:119], v[126:127], v[122:123]
	global_store_dwordx4 v[146:147], v[118:121], off offset:128
	global_load_dwordx4 v[120:123], v[142:143], off offset:192
	s_nop 0
	global_load_dwordx4 v[124:127], v[144:145], off offset:192
	v_or_b32_e32 v118, 48, v164
	v_cmp_lt_i32_e32 vcc, s48, v118
	s_waitcnt vmcnt(0)
	v_pk_fma_f32 v[116:117], v[116:117], v[126:127], v[122:123]
	v_pk_fma_f32 v[114:115], v[114:115], v[124:125], v[120:121]
	global_store_dwordx4 v[146:147], v[114:117], off offset:192
	s_and_saveexec_b64 s[2:3], vcc
	s_xor_b64 s[2:3], exec, s[2:3]
	v_add_u32_e32 v238, 0xffffe030, v164
	v_lshlrev_b64 v[114:115], 12, v[238:239]
	v_mov_b32_e32 v119, v239
	v_lshl_add_u64 v[114:115], s[14:15], 0, v[114:115]
	v_lshlrev_b64 v[116:117], 12, v[118:119]
	v_mov_b64_e32 v[120:121], v[162:163]
	s_andn2_saveexec_b64 s[2:3], s[2:3]
	v_ashrrev_i32_e32 v119, 31, v118
	v_lshlrev_b64 v[116:117], 12, v[118:119]
	v_lshl_add_u64 v[114:115], s[12:13], 0, v[116:117]
	v_mov_b64_e32 v[120:121], 0
	s_or_b64 exec, exec, s[2:3]
	v_lshl_add_u64 v[122:123], v[120:121], 2, s[20:21]
	v_lshl_add_u64 v[126:127], v[114:115], 0, v[166:167]
	v_lshl_add_u64 v[128:129], v[122:123], 0, v[166:167]
	global_load_dwordx4 v[118:121], v[126:127], off
	global_load_dwordx4 v[122:125], v[128:129], off
	v_lshl_add_u64 v[114:115], s[4:5], 0, v[116:117]
	v_lshl_add_u64 v[130:131], v[114:115], 0, v[166:167]
	s_waitcnt vmcnt(0)
	v_pk_fma_f32 v[112:113], v[112:113], v[124:125], v[120:121]
	v_pk_fma_f32 v[110:111], v[110:111], v[122:123], v[118:119]
	global_store_dwordx4 v[130:131], v[110:113], off
	global_load_dwordx4 v[110:113], v[126:127], off offset:64
	s_nop 0
	global_load_dwordx4 v[114:117], v[128:129], off offset:64
	s_waitcnt vmcnt(0)
	v_pk_fma_f32 v[108:109], v[108:109], v[116:117], v[112:113]
	v_pk_fma_f32 v[106:107], v[106:107], v[114:115], v[110:111]
	global_store_dwordx4 v[130:131], v[106:109], off offset:64
	global_load_dwordx4 v[106:109], v[126:127], off offset:128
	s_nop 0
	global_load_dwordx4 v[110:113], v[128:129], off offset:128
	s_waitcnt vmcnt(0)
	v_pk_fma_f32 v[104:105], v[104:105], v[112:113], v[108:109]
	v_pk_fma_f32 v[102:103], v[102:103], v[110:111], v[106:107]
	global_store_dwordx4 v[130:131], v[102:105], off offset:128
	global_load_dwordx4 v[104:107], v[126:127], off offset:192
	s_nop 0
	global_load_dwordx4 v[108:111], v[128:129], off offset:192
	v_or_b32_e32 v102, 64, v164
	v_cmp_lt_i32_e32 vcc, s48, v102
	s_waitcnt vmcnt(0)
	v_pk_fma_f32 v[84:85], v[84:85], v[110:111], v[106:107]
	v_pk_fma_f32 v[82:83], v[82:83], v[108:109], v[104:105]
	global_store_dwordx4 v[130:131], v[82:85], off offset:192
	s_and_saveexec_b64 s[2:3], vcc
	s_xor_b64 s[2:3], exec, s[2:3]
	v_add_u32_e32 v238, 0xffffe040, v164
	v_lshlrev_b64 v[82:83], 12, v[238:239]
	v_mov_b32_e32 v103, v239
	v_lshl_add_u64 v[82:83], s[14:15], 0, v[82:83]
	v_lshlrev_b64 v[84:85], 12, v[102:103]
	v_mov_b64_e32 v[104:105], v[162:163]
	s_andn2_saveexec_b64 s[2:3], s[2:3]
	v_ashrrev_i32_e32 v103, 31, v102
	v_lshlrev_b64 v[84:85], 12, v[102:103]
	v_lshl_add_u64 v[82:83], s[12:13], 0, v[84:85]
	v_mov_b64_e32 v[104:105], 0
	s_or_b64 exec, exec, s[2:3]
	v_lshl_add_u64 v[106:107], v[104:105], 2, s[20:21]
	v_lshl_add_u64 v[110:111], v[82:83], 0, v[166:167]
	v_lshl_add_u64 v[112:113], v[106:107], 0, v[166:167]
	global_load_dwordx4 v[102:105], v[110:111], off
	global_load_dwordx4 v[106:109], v[112:113], off
	v_lshl_add_u64 v[82:83], s[4:5], 0, v[84:85]
	v_lshl_add_u64 v[114:115], v[82:83], 0, v[166:167]
	s_waitcnt vmcnt(0)
	v_pk_fma_f32 v[84:85], v[100:101], v[108:109], v[104:105]
	v_pk_fma_f32 v[82:83], v[98:99], v[106:107], v[102:103]
	global_store_dwordx4 v[114:115], v[82:85], off
	global_load_dwordx4 v[82:85], v[110:111], off offset:64
	s_nop 0
	global_load_dwordx4 v[98:101], v[112:113], off offset:64
	s_waitcnt vmcnt(0)
	v_pk_fma_f32 v[84:85], v[96:97], v[100:101], v[84:85]
	v_pk_fma_f32 v[82:83], v[94:95], v[98:99], v[82:83]
	global_store_dwordx4 v[114:115], v[82:85], off offset:64
	global_load_dwordx4 v[82:85], v[110:111], off offset:128
	s_nop 0
	global_load_dwordx4 v[94:97], v[112:113], off offset:128
	s_waitcnt vmcnt(0)
	v_pk_fma_f32 v[84:85], v[92:93], v[96:97], v[84:85]
	v_pk_fma_f32 v[82:83], v[90:91], v[94:95], v[82:83]
	global_store_dwordx4 v[114:115], v[82:85], off offset:128
	global_load_dwordx4 v[90:93], v[110:111], off offset:192
	global_load_dwordx4 v[94:97], v[112:113], off offset:192
	v_or_b32_e32 v84, 0x50, v164
	v_cmp_lt_i32_e32 vcc, s48, v84
	s_waitcnt vmcnt(0)
	v_pk_fma_f32 v[88:89], v[88:89], v[96:97], v[92:93]
	v_pk_fma_f32 v[86:87], v[86:87], v[94:95], v[90:91]
	global_store_dwordx4 v[114:115], v[86:89], off offset:192
	s_and_saveexec_b64 s[2:3], vcc
	s_xor_b64 s[2:3], exec, s[2:3]
	v_add_u32_e32 v238, 0xffffe050, v164
	v_lshlrev_b64 v[82:83], 12, v[238:239]
	v_mov_b32_e32 v85, v239
	v_lshl_add_u64 v[82:83], s[14:15], 0, v[82:83]
	v_lshlrev_b64 v[86:87], 12, v[84:85]
	v_mov_b64_e32 v[88:89], v[162:163]
	s_andn2_saveexec_b64 s[2:3], s[2:3]
	v_ashrrev_i32_e32 v85, 31, v84
	v_lshlrev_b64 v[86:87], 12, v[84:85]
	v_lshl_add_u64 v[82:83], s[12:13], 0, v[86:87]
	v_mov_b64_e32 v[88:89], 0
	s_or_b64 exec, exec, s[2:3]
	v_lshl_add_u64 v[88:89], v[88:89], 2, s[20:21]
	v_lshl_add_u64 v[92:93], v[82:83], 0, v[166:167]
	v_lshl_add_u64 v[94:95], v[88:89], 0, v[166:167]
	global_load_dwordx4 v[82:85], v[92:93], off
	global_load_dwordx4 v[88:91], v[94:95], off
	v_lshl_add_u64 v[86:87], s[4:5], 0, v[86:87]
	v_lshl_add_u64 v[86:87], v[86:87], 0, v[166:167]
	s_waitcnt vmcnt(0)
	v_pk_fma_f32 v[80:81], v[80:81], v[90:91], v[84:85]
	v_pk_fma_f32 v[78:79], v[78:79], v[88:89], v[82:83]
	global_store_dwordx4 v[86:87], v[78:81], off
	global_load_dwordx4 v[78:81], v[92:93], off offset:64
	s_nop 0
	global_load_dwordx4 v[82:85], v[94:95], off offset:64
	s_waitcnt vmcnt(0)
	v_pk_fma_f32 v[76:77], v[76:77], v[84:85], v[80:81]
	v_pk_fma_f32 v[74:75], v[74:75], v[82:83], v[78:79]
	global_store_dwordx4 v[86:87], v[74:77], off offset:64
	global_load_dwordx4 v[74:77], v[92:93], off offset:128
	s_nop 0
	global_load_dwordx4 v[78:81], v[94:95], off offset:128
	s_waitcnt vmcnt(0)
	v_pk_fma_f32 v[72:73], v[72:73], v[80:81], v[76:77]
	v_pk_fma_f32 v[70:71], v[70:71], v[78:79], v[74:75]
	global_store_dwordx4 v[86:87], v[70:73], off offset:128
	global_load_dwordx4 v[72:75], v[92:93], off offset:192
	s_nop 0
	global_load_dwordx4 v[76:79], v[94:95], off offset:192
	v_or_b32_e32 v70, 0x60, v164
	v_cmp_lt_i32_e32 vcc, s48, v70
	s_waitcnt vmcnt(0)
	v_pk_fma_f32 v[68:69], v[68:69], v[78:79], v[74:75]
	v_pk_fma_f32 v[66:67], v[66:67], v[76:77], v[72:73]
	global_store_dwordx4 v[86:87], v[66:69], off offset:192
	s_and_saveexec_b64 s[2:3], vcc
	s_xor_b64 s[2:3], exec, s[2:3]
	v_add_u32_e32 v238, 0xffffe060, v164
	v_lshlrev_b64 v[66:67], 12, v[238:239]
	v_mov_b32_e32 v71, v239
	v_lshl_add_u64 v[66:67], s[14:15], 0, v[66:67]
	v_lshlrev_b64 v[68:69], 12, v[70:71]
	v_mov_b64_e32 v[72:73], v[162:163]
	s_andn2_saveexec_b64 s[2:3], s[2:3]
	v_ashrrev_i32_e32 v71, 31, v70
	v_lshlrev_b64 v[68:69], 12, v[70:71]
	v_lshl_add_u64 v[66:67], s[12:13], 0, v[68:69]
	v_mov_b64_e32 v[72:73], 0
	s_or_b64 exec, exec, s[2:3]
	v_lshl_add_u64 v[74:75], v[72:73], 2, s[20:21]
	v_lshl_add_u64 v[78:79], v[66:67], 0, v[166:167]
	v_lshl_add_u64 v[80:81], v[74:75], 0, v[166:167]
	global_load_dwordx4 v[70:73], v[78:79], off
	global_load_dwordx4 v[74:77], v[80:81], off
	v_lshl_add_u64 v[66:67], s[4:5], 0, v[68:69]
	v_lshl_add_u64 v[82:83], v[66:67], 0, v[166:167]
	s_waitcnt vmcnt(0)
	v_pk_fma_f32 v[64:65], v[64:65], v[76:77], v[72:73]
	v_pk_fma_f32 v[62:63], v[62:63], v[74:75], v[70:71]
	global_store_dwordx4 v[82:83], v[62:65], off
	global_load_dwordx4 v[62:65], v[78:79], off offset:64
	s_nop 0
	global_load_dwordx4 v[66:69], v[80:81], off offset:64
	s_waitcnt vmcnt(0)
	v_pk_fma_f32 v[60:61], v[60:61], v[68:69], v[64:65]
	v_pk_fma_f32 v[58:59], v[58:59], v[66:67], v[62:63]
	global_store_dwordx4 v[82:83], v[58:61], off offset:64
	global_load_dwordx4 v[58:61], v[78:79], off offset:128
	s_nop 0
	global_load_dwordx4 v[62:65], v[80:81], off offset:128
	s_waitcnt vmcnt(0)
	v_pk_fma_f32 v[56:57], v[56:57], v[64:65], v[60:61]
	v_pk_fma_f32 v[54:55], v[54:55], v[62:63], v[58:59]
	global_store_dwordx4 v[82:83], v[54:57], off offset:128
	global_load_dwordx4 v[56:59], v[78:79], off offset:192
	s_nop 0
	global_load_dwordx4 v[60:63], v[80:81], off offset:192
	v_or_b32_e32 v54, 0x70, v164
	v_cmp_lt_i32_e32 vcc, s48, v54
	s_waitcnt vmcnt(0)
	v_pk_fma_f32 v[52:53], v[52:53], v[62:63], v[58:59]
	v_pk_fma_f32 v[50:51], v[50:51], v[60:61], v[56:57]
	global_store_dwordx4 v[82:83], v[50:53], off offset:192
	s_and_saveexec_b64 s[2:3], vcc
	s_xor_b64 s[2:3], exec, s[2:3]
	v_add_u32_e32 v238, 0xffffe070, v164
	v_lshlrev_b64 v[50:51], 12, v[238:239]
	v_mov_b32_e32 v55, v239
	v_lshl_add_u64 v[50:51], s[14:15], 0, v[50:51]
	v_lshlrev_b64 v[52:53], 12, v[54:55]
	s_andn2_saveexec_b64 s[2:3], s[2:3]
	v_ashrrev_i32_e32 v55, 31, v54
	v_lshlrev_b64 v[52:53], 12, v[54:55]
	v_lshl_add_u64 v[50:51], s[12:13], 0, v[52:53]
	v_mov_b64_e32 v[162:163], 0
	s_or_b64 exec, exec, s[2:3]
	v_lshl_add_u64 v[58:59], v[162:163], 2, s[20:21]
	v_lshl_add_u64 v[62:63], v[50:51], 0, v[166:167]
	v_lshl_add_u64 v[64:65], v[58:59], 0, v[166:167]
	global_load_dwordx4 v[54:57], v[62:63], off
	global_load_dwordx4 v[58:61], v[64:65], off
	v_lshl_add_u64 v[50:51], s[4:5], 0, v[52:53]
	v_lshl_add_u64 v[66:67], v[50:51], 0, v[166:167]
	s_add_i32 s49, s49, s11
	s_cmp_gt_i32 s49, 31
	s_waitcnt vmcnt(0)
	v_pk_fma_f32 v[48:49], v[48:49], v[60:61], v[56:57]
	v_pk_fma_f32 v[46:47], v[46:47], v[58:59], v[54:55]
	global_store_dwordx4 v[66:67], v[46:49], off
	global_load_dwordx4 v[46:49], v[62:63], off offset:64
	s_nop 0
	global_load_dwordx4 v[50:53], v[64:65], off offset:64
	s_waitcnt vmcnt(0)
	v_pk_fma_f32 v[44:45], v[44:45], v[52:53], v[48:49]
	v_pk_fma_f32 v[42:43], v[42:43], v[50:51], v[46:47]
	global_store_dwordx4 v[66:67], v[42:45], off offset:64
	global_load_dwordx4 v[42:45], v[62:63], off offset:128
	s_nop 0
	global_load_dwordx4 v[46:49], v[64:65], off offset:128
	s_waitcnt vmcnt(0)
	v_pk_fma_f32 v[40:41], v[40:41], v[48:49], v[44:45]
	v_pk_fma_f32 v[38:39], v[38:39], v[46:47], v[42:43]
	global_store_dwordx4 v[66:67], v[38:41], off offset:128
	global_load_dwordx4 v[38:41], v[62:63], off offset:192
	s_nop 0
	global_load_dwordx4 v[42:45], v[64:65], off offset:192
	s_waitcnt vmcnt(0)
	v_pk_fma_f32 v[40:41], v[36:37], v[44:45], v[40:41]
	v_pk_fma_f32 v[38:39], v[34:35], v[42:43], v[38:39]
	v_mov_b32_e32 v37, 0
	global_store_dwordx4 v[66:67], v[38:41], off offset:192
	s_cbranch_scc1 .LBB0_958
	s_ashr_i32 s3, s49, 31
	s_lshr_b32 s3, s3, 27
	s_add_i32 s3, s49, s3
	s_ashr_i32 s3, s3, 5
	s_mov_b32 s2, s10
	s_lshl_b32 s22, s3, 6
	s_lshl_b32 s23, s49, 1
	s_sub_i32 s22, s23, s22
	s_and_b32 s2, s2, 7
	s_and_b32 s22, s22, -8
	s_lshl_b32 s3, s3, 2
	s_and_b32 s23, s49, 3
	s_or_b32 s36, s3, s23
	s_or_b32 s38, s2, s22
	s_branch .LBB0_958

.LBB0_1148:
	ds_read_b128 v[194:197], v251
	ds_read_b128 v[198:201], v249
	ds_read_b128 v[202:205], v251 offset:4096
	ds_read_b128 v[206:209], v249 offset:4096
	ds_read_b128 v[162:165], v255
	ds_read_b128 v[166:169], v253
	ds_read_b128 v[170:173], v255 offset:4096
	ds_read_b128 v[174:177], v253 offset:4096
	s_cmp_eq_u32 s98, 0
	s_cbranch_scc1 .Lnodef_I0_2
	v_mfma_f32_16x16x32_bf16 v[98:101], v[210:213], v[178:181], v[98:101]
	v_mfma_f32_16x16x32_bf16 v[90:93], v[214:217], v[178:181], v[90:93]
	v_mfma_f32_16x16x32_bf16 v[94:97], v[218:221], v[178:181], v[94:97]
	v_mfma_f32_16x16x32_bf16 v[86:89], v[222:225], v[178:181], v[86:89]
	v_mfma_f32_16x16x32_bf16 v[82:85], v[210:213], v[182:185], v[82:85]
	v_mfma_f32_16x16x32_bf16 v[74:77], v[214:217], v[182:185], v[74:77]
	v_mfma_f32_16x16x32_bf16 v[78:81], v[218:221], v[182:185], v[78:81]
	v_mfma_f32_16x16x32_bf16 v[70:73], v[222:225], v[182:185], v[70:73]
	v_mfma_f32_16x16x32_bf16 v[62:65], v[210:213], v[186:189], v[62:65]
	v_mfma_f32_16x16x32_bf16 v[54:57], v[214:217], v[186:189], v[54:57]
	v_mfma_f32_16x16x32_bf16 v[58:61], v[218:221], v[186:189], v[58:61]
	v_mfma_f32_16x16x32_bf16 v[50:53], v[222:225], v[186:189], v[50:53]
	v_mfma_f32_16x16x32_bf16 v[46:49], v[210:213], v[190:193], v[46:49]
	v_mfma_f32_16x16x32_bf16 v[38:41], v[214:217], v[190:193], v[38:41]
	v_mfma_f32_16x16x32_bf16 v[42:45], v[218:221], v[190:193], v[42:45]
	v_mfma_f32_16x16x32_bf16 v[34:37], v[222:225], v[190:193], v[34:37]
.Lnodef_I0_2:
	ds_read_b128 v[186:189], v255 offset:12288
	ds_read_b128 v[182:185], v253 offset:8192
	ds_read_b128 v[178:181], v255 offset:8192
	ds_read_b128 v[190:193], v253 offset:12288
	s_add_i32 s2, s41, -1
	s_cmp_lt_i32 s2, s40
	s_cselect_b64 s[14:15], -1, 0
	s_cmp_ge_i32 s2, s40
	s_waitcnt lgkmcnt(7)
	v_mfma_f32_16x16x32_bf16 v[158:161], v[194:197], v[162:165], v[158:161]
	v_mfma_f32_16x16x32_bf16 v[150:153], v[198:201], v[162:165], v[150:153]
	v_mfma_f32_16x16x32_bf16 v[154:157], v[202:205], v[162:165], v[154:157]
	v_mfma_f32_16x16x32_bf16 v[146:149], v[206:209], v[162:165], v[146:149]
	ds_read_b128 v[162:165], v247
	s_waitcnt lgkmcnt(7)
	v_mfma_f32_16x16x32_bf16 v[142:145], v[194:197], v[166:169], v[142:145]
	v_mfma_f32_16x16x32_bf16 v[134:137], v[198:201], v[166:169], v[134:137]
	v_mfma_f32_16x16x32_bf16 v[138:141], v[202:205], v[166:169], v[138:141]
	v_mfma_f32_16x16x32_bf16 v[130:133], v[206:209], v[166:169], v[130:133]
	s_waitcnt vmcnt(6)
	ds_write_b128 v235, v[30:33]
	ds_write_b128 v235, v[26:29] offset:8192
.LBB0_1150:
	s_lshl_b32 s2, s48, 8
	s_ashr_i32 s3, s2, 31
	s_lshl_b64 s[12:13], s[2:3], 11
	s_lshl_b32 s2, s22, 6
	s_ashr_i32 s3, s2, 31
	s_add_u32 s20, s11, s12
	s_addc_u32 s21, s24, s13
	s_lshl_b64 s[8:9], s[2:3], 1
	s_add_u32 s20, s20, s8
	s_addc_u32 s21, s21, s9
	global_load_dwordx4 v[30:33], v233, s[20:21]
	global_load_dwordx4 v[26:29], v234, s[20:21]
	s_andn2_b64 vcc, exec, s[14:15]
	ds_read_b128 v[166:169], v245
	s_waitcnt lgkmcnt(9)
	v_mfma_f32_16x16x32_bf16 v[126:129], v[194:197], v[170:173], v[126:129]
	v_mfma_f32_16x16x32_bf16 v[118:121], v[198:201], v[170:173], v[118:121]
	v_mfma_f32_16x16x32_bf16 v[122:125], v[202:205], v[170:173], v[122:125]
	v_mfma_f32_16x16x32_bf16 v[114:117], v[206:209], v[170:173], v[114:117]
	ds_read_b128 v[170:173], v247 offset:4096
	s_waitcnt lgkmcnt(9)
	v_mfma_f32_16x16x32_bf16 v[110:113], v[194:197], v[174:177], v[110:113]
	v_mfma_f32_16x16x32_bf16 v[102:105], v[198:201], v[174:177], v[102:105]
	v_mfma_f32_16x16x32_bf16 v[106:109], v[202:205], v[174:177], v[106:109]
	v_mfma_f32_16x16x32_bf16 v[66:69], v[206:209], v[174:177], v[66:69]
	ds_read_b128 v[210:213], v243
	ds_read_b128 v[214:217], v241
	ds_read_b128 v[218:221], v243 offset:4096
	ds_read_b128 v[222:225], v241 offset:4096
	ds_read_b128 v[174:177], v245 offset:4096
	s_waitcnt lgkmcnt(11)
	v_mfma_f32_16x16x32_bf16 v[98:101], v[194:197], v[178:181], v[98:101]
	v_mfma_f32_16x16x32_bf16 v[90:93], v[198:201], v[178:181], v[90:93]
	v_mfma_f32_16x16x32_bf16 v[94:97], v[202:205], v[178:181], v[94:97]
	v_mfma_f32_16x16x32_bf16 v[86:89], v[206:209], v[178:181], v[86:89]
	s_waitcnt vmcnt(6)
	ds_write_b128 v235, v[22:25] offset:16384
	ds_write_b128 v235, v[18:21] offset:24576
.LBB0_1152:
	global_load_dwordx4 v[18:21], v232, s[20:21]
	global_load_dwordx4 v[22:25], v231, s[20:21]
	s_and_b64 vcc, exec, s[2:3]
	ds_read_b128 v[178:181], v247 offset:8192
	v_mfma_f32_16x16x32_bf16 v[82:85], v[194:197], v[182:185], v[82:85]
	v_mfma_f32_16x16x32_bf16 v[74:77], v[198:201], v[182:185], v[74:77]
	v_mfma_f32_16x16x32_bf16 v[78:81], v[202:205], v[182:185], v[78:81]
	v_mfma_f32_16x16x32_bf16 v[70:73], v[206:209], v[182:185], v[70:73]
	s_waitcnt lgkmcnt(10)
	ds_read_b128 v[182:185], v245 offset:8192
	v_mfma_f32_16x16x32_bf16 v[62:65], v[194:197], v[186:189], v[62:65]
	v_mfma_f32_16x16x32_bf16 v[54:57], v[198:201], v[186:189], v[54:57]
	v_mfma_f32_16x16x32_bf16 v[58:61], v[202:205], v[186:189], v[58:61]
	v_mfma_f32_16x16x32_bf16 v[50:53], v[206:209], v[186:189], v[50:53]
	s_waitcnt vmcnt(6)
	ds_write_b128 v235, v[14:17] offset:32768
	ds_write_b128 v235, v[10:13] offset:40960
.LBB0_1154:
	s_lshl_b32 s14, s47, 8
	s_ashr_i32 s15, s14, 31
	s_lshl_b64 s[14:15], s[14:15], 11
	s_add_u32 s20, s25, s14
	s_addc_u32 s21, s26, s15
	s_add_u32 s8, s20, s8
	s_addc_u32 s9, s21, s9
	global_load_dwordx4 v[10:13], v234, s[8:9]
	global_load_dwordx4 v[14:17], v233, s[8:9]
	s_and_b64 vcc, exec, s[2:3]
	ds_read_b128 v[186:189], v247 offset:12288
	v_mfma_f32_16x16x32_bf16 v[46:49], v[194:197], v[190:193], v[46:49]
	v_mfma_f32_16x16x32_bf16 v[38:41], v[198:201], v[190:193], v[38:41]
	v_mfma_f32_16x16x32_bf16 v[42:45], v[202:205], v[190:193], v[42:45]
	v_mfma_f32_16x16x32_bf16 v[34:37], v[206:209], v[190:193], v[34:37]
	s_waitcnt lgkmcnt(10)
	ds_read_b128 v[190:193], v245 offset:12288
	s_waitcnt lgkmcnt(9)
	v_mfma_f32_16x16x32_bf16 v[158:161], v[210:213], v[162:165], v[158:161]
	v_mfma_f32_16x16x32_bf16 v[150:153], v[214:217], v[162:165], v[150:153]
	v_mfma_f32_16x16x32_bf16 v[154:157], v[218:221], v[162:165], v[154:157]
	v_mfma_f32_16x16x32_bf16 v[146:149], v[222:225], v[162:165], v[146:149]
	v_mfma_f32_16x16x32_bf16 v[142:145], v[210:213], v[166:169], v[142:145]
	v_mfma_f32_16x16x32_bf16 v[134:137], v[214:217], v[166:169], v[134:137]
	v_mfma_f32_16x16x32_bf16 v[138:141], v[218:221], v[166:169], v[138:141]
	v_mfma_f32_16x16x32_bf16 v[130:133], v[222:225], v[166:169], v[130:133]
	s_waitcnt vmcnt(6)
	ds_write_b128 v235, v[6:9] offset:49152
	ds_write_b128 v235, v[2:5] offset:57344
.LBB0_1156:
	global_load_dwordx4 v[2:5], v232, s[8:9]
	global_load_dwordx4 v[6:9], v231, s[8:9]
	v_mfma_f32_16x16x32_bf16 v[126:129], v[210:213], v[170:173], v[126:129]
	v_mfma_f32_16x16x32_bf16 v[118:121], v[214:217], v[170:173], v[118:121]
	v_mfma_f32_16x16x32_bf16 v[122:125], v[218:221], v[170:173], v[122:125]
	v_mfma_f32_16x16x32_bf16 v[114:117], v[222:225], v[170:173], v[114:117]
	s_waitcnt lgkmcnt(10)
	v_mfma_f32_16x16x32_bf16 v[110:113], v[210:213], v[174:177], v[110:113]
	v_mfma_f32_16x16x32_bf16 v[102:105], v[214:217], v[174:177], v[102:105]
	v_mfma_f32_16x16x32_bf16 v[106:109], v[218:221], v[174:177], v[106:109]
	v_mfma_f32_16x16x32_bf16 v[66:69], v[222:225], v[174:177], v[66:69]
	s_add_i32 s50, s22, 1
	s_cmp_lg_u32 s50, 16
	s_cbranch_scc1 .LBB0_1164
	s_add_i32 s31, s31, s28
	s_cmp_ge_i32 s31, s33
	s_cbranch_scc1 .LBB0_1163
	s_mov_b32 s8, s10
	s_cmpk_gt_i32 s31, 0x9f
	s_mov_b64 s[2:3], -1
	s_cbranch_scc0 .LBB0_1160
	s_lshl_b32 s2, s31, 2
	s_add_i32 s2, s2, 0x7ffffd80
	s_and_b32 s9, s2, 0x7ffffff8
	s_and_b32 s2, s31, 1
	s_or_b32 s47, s2, 20
	s_mov_b64 s[2:3], 0

.LBB0_1164:
	s_waitcnt lgkmcnt(0)
	s_barrier
	ds_read_b128 v[194:197], v250
	ds_read_b128 v[198:201], v248
	ds_read_b128 v[202:205], v250 offset:4096
	ds_read_b128 v[206:209], v248 offset:4096
	ds_read_b128 v[162:165], v254
	ds_read_b128 v[166:169], v252
	ds_read_b128 v[170:173], v254 offset:4096
	ds_read_b128 v[174:177], v252 offset:4096
	v_mfma_f32_16x16x32_bf16 v[98:101], v[210:213], v[178:181], v[98:101]
	v_mfma_f32_16x16x32_bf16 v[90:93], v[214:217], v[178:181], v[90:93]
	v_mfma_f32_16x16x32_bf16 v[94:97], v[218:221], v[178:181], v[94:97]
	v_mfma_f32_16x16x32_bf16 v[86:89], v[222:225], v[178:181], v[86:89]
	v_mfma_f32_16x16x32_bf16 v[82:85], v[210:213], v[182:185], v[82:85]
	v_mfma_f32_16x16x32_bf16 v[74:77], v[214:217], v[182:185], v[74:77]
	v_mfma_f32_16x16x32_bf16 v[78:81], v[218:221], v[182:185], v[78:81]
	v_mfma_f32_16x16x32_bf16 v[70:73], v[222:225], v[182:185], v[70:73]
	v_mfma_f32_16x16x32_bf16 v[62:65], v[210:213], v[186:189], v[62:65]
	v_mfma_f32_16x16x32_bf16 v[54:57], v[214:217], v[186:189], v[54:57]
	v_mfma_f32_16x16x32_bf16 v[58:61], v[218:221], v[186:189], v[58:61]
	v_mfma_f32_16x16x32_bf16 v[50:53], v[222:225], v[186:189], v[50:53]
	v_mfma_f32_16x16x32_bf16 v[46:49], v[210:213], v[190:193], v[46:49]
	v_mfma_f32_16x16x32_bf16 v[38:41], v[214:217], v[190:193], v[38:41]
	v_mfma_f32_16x16x32_bf16 v[42:45], v[218:221], v[190:193], v[42:45]
	v_mfma_f32_16x16x32_bf16 v[34:37], v[222:225], v[190:193], v[34:37]
	ds_read_b128 v[186:189], v254 offset:12288
	ds_read_b128 v[182:185], v252 offset:8192
	ds_read_b128 v[178:181], v254 offset:8192
	ds_read_b128 v[190:193], v252 offset:12288
	s_cmp_lt_i32 s41, s40
	s_cselect_b64 s[20:21], -1, 0
	s_cmp_ge_i32 s41, s40
	s_cselect_b64 s[8:9], -1, 0
	s_and_b64 vcc, exec, s[8:9]
	s_waitcnt lgkmcnt(7)
	v_mfma_f32_16x16x32_bf16 v[158:161], v[194:197], v[162:165], v[158:161]
	v_mfma_f32_16x16x32_bf16 v[150:153], v[198:201], v[162:165], v[150:153]
	v_mfma_f32_16x16x32_bf16 v[154:157], v[202:205], v[162:165], v[154:157]
	v_mfma_f32_16x16x32_bf16 v[146:149], v[206:209], v[162:165], v[146:149]
	ds_read_b128 v[162:165], v246
	s_waitcnt lgkmcnt(7)
	v_mfma_f32_16x16x32_bf16 v[142:145], v[194:197], v[166:169], v[142:145]
	v_mfma_f32_16x16x32_bf16 v[134:137], v[198:201], v[166:169], v[134:137]
	v_mfma_f32_16x16x32_bf16 v[138:141], v[202:205], v[166:169], v[138:141]
	v_mfma_f32_16x16x32_bf16 v[130:133], v[206:209], v[166:169], v[130:133]
	s_waitcnt vmcnt(6)
	ds_write_b128 v236, v[26:29]
	ds_write_b128 v236, v[30:33] offset:8192
.LBB0_1166:
	s_lshl_b32 s2, s50, 6
	s_ashr_i32 s3, s2, 31
	s_add_u32 s22, s11, s12
	s_addc_u32 s23, s24, s13
	s_lshl_b64 s[12:13], s[2:3], 1
	s_add_u32 s22, s22, s12
	s_addc_u32 s23, s23, s13
	global_load_dwordx4 v[30:33], v234, s[22:23]
	global_load_dwordx4 v[26:29], v233, s[22:23]
	s_andn2_b64 vcc, exec, s[20:21]
	ds_read_b128 v[166:169], v244
	s_waitcnt lgkmcnt(9)
	v_mfma_f32_16x16x32_bf16 v[126:129], v[194:197], v[170:173], v[126:129]
	v_mfma_f32_16x16x32_bf16 v[118:121], v[198:201], v[170:173], v[118:121]
	v_mfma_f32_16x16x32_bf16 v[122:125], v[202:205], v[170:173], v[122:125]
	v_mfma_f32_16x16x32_bf16 v[114:117], v[206:209], v[170:173], v[114:117]
	ds_read_b128 v[170:173], v246 offset:4096
	s_waitcnt lgkmcnt(9)
	v_mfma_f32_16x16x32_bf16 v[110:113], v[194:197], v[174:177], v[110:113]
	v_mfma_f32_16x16x32_bf16 v[102:105], v[198:201], v[174:177], v[102:105]
	v_mfma_f32_16x16x32_bf16 v[106:109], v[202:205], v[174:177], v[106:109]
	v_mfma_f32_16x16x32_bf16 v[66:69], v[206:209], v[174:177], v[66:69]
	ds_read_b128 v[210:213], v242
	ds_read_b128 v[214:217], v237
	ds_read_b128 v[218:221], v242 offset:4096
	ds_read_b128 v[222:225], v237 offset:4096
	ds_read_b128 v[174:177], v244 offset:4096
	s_waitcnt lgkmcnt(11)
	v_mfma_f32_16x16x32_bf16 v[98:101], v[194:197], v[178:181], v[98:101]
	v_mfma_f32_16x16x32_bf16 v[90:93], v[198:201], v[178:181], v[90:93]
	v_mfma_f32_16x16x32_bf16 v[94:97], v[202:205], v[178:181], v[94:97]
	v_mfma_f32_16x16x32_bf16 v[86:89], v[206:209], v[178:181], v[86:89]
	s_waitcnt vmcnt(6)
	ds_write_b128 v236, v[18:21] offset:16384
	ds_write_b128 v236, v[22:25] offset:24576
.LBB0_1168:
	global_load_dwordx4 v[22:25], v232, s[22:23]
	global_load_dwordx4 v[18:21], v231, s[22:23]
	s_and_b64 vcc, exec, s[2:3]
	ds_read_b128 v[178:181], v246 offset:8192
	v_mfma_f32_16x16x32_bf16 v[82:85], v[194:197], v[182:185], v[82:85]
	v_mfma_f32_16x16x32_bf16 v[74:77], v[198:201], v[182:185], v[74:77]
	v_mfma_f32_16x16x32_bf16 v[78:81], v[202:205], v[182:185], v[78:81]
	v_mfma_f32_16x16x32_bf16 v[70:73], v[206:209], v[182:185], v[70:73]
	s_waitcnt lgkmcnt(10)
	ds_read_b128 v[182:185], v244 offset:8192
	v_mfma_f32_16x16x32_bf16 v[62:65], v[194:197], v[186:189], v[62:65]
	v_mfma_f32_16x16x32_bf16 v[54:57], v[198:201], v[186:189], v[54:57]
	v_mfma_f32_16x16x32_bf16 v[58:61], v[202:205], v[186:189], v[58:61]
	v_mfma_f32_16x16x32_bf16 v[50:53], v[206:209], v[186:189], v[50:53]
	s_waitcnt vmcnt(6)
	ds_write_b128 v236, v[10:13] offset:32768
	ds_write_b128 v236, v[14:17] offset:40960
.LBB0_1170:
	s_add_u32 s14, s25, s14
	s_addc_u32 s15, s26, s15
	s_add_u32 s12, s14, s12
	s_addc_u32 s13, s15, s13
	global_load_dwordx4 v[14:17], v234, s[12:13]
	global_load_dwordx4 v[10:13], v233, s[12:13]
	s_and_b64 vcc, exec, s[2:3]
	ds_read_b128 v[186:189], v246 offset:12288
	v_mfma_f32_16x16x32_bf16 v[46:49], v[194:197], v[190:193], v[46:49]
	v_mfma_f32_16x16x32_bf16 v[38:41], v[198:201], v[190:193], v[38:41]
	v_mfma_f32_16x16x32_bf16 v[42:45], v[202:205], v[190:193], v[42:45]
	v_mfma_f32_16x16x32_bf16 v[34:37], v[206:209], v[190:193], v[34:37]
	s_waitcnt lgkmcnt(10)
	ds_read_b128 v[190:193], v244 offset:12288
	s_waitcnt lgkmcnt(9)
	v_mfma_f32_16x16x32_bf16 v[158:161], v[210:213], v[162:165], v[158:161]
	v_mfma_f32_16x16x32_bf16 v[150:153], v[214:217], v[162:165], v[150:153]
	v_mfma_f32_16x16x32_bf16 v[154:157], v[218:221], v[162:165], v[154:157]
	v_mfma_f32_16x16x32_bf16 v[146:149], v[222:225], v[162:165], v[146:149]
	v_mfma_f32_16x16x32_bf16 v[142:145], v[210:213], v[166:169], v[142:145]
	v_mfma_f32_16x16x32_bf16 v[134:137], v[214:217], v[166:169], v[134:137]
	v_mfma_f32_16x16x32_bf16 v[138:141], v[218:221], v[166:169], v[138:141]
	v_mfma_f32_16x16x32_bf16 v[130:133], v[222:225], v[166:169], v[130:133]
	s_waitcnt vmcnt(6)
	ds_write_b128 v236, v[2:5] offset:49152
	ds_write_b128 v236, v[6:9] offset:57344
.LBB0_1172:
	global_load_dwordx4 v[6:9], v232, s[12:13]
	global_load_dwordx4 v[2:5], v231, s[12:13]
	v_mfma_f32_16x16x32_bf16 v[126:129], v[210:213], v[170:173], v[126:129]
	v_mfma_f32_16x16x32_bf16 v[118:121], v[214:217], v[170:173], v[118:121]
	v_mfma_f32_16x16x32_bf16 v[122:125], v[218:221], v[170:173], v[122:125]
	v_mfma_f32_16x16x32_bf16 v[114:117], v[222:225], v[170:173], v[114:117]
	s_waitcnt lgkmcnt(10)
	v_mfma_f32_16x16x32_bf16 v[110:113], v[210:213], v[174:177], v[110:113]
	v_mfma_f32_16x16x32_bf16 v[102:105], v[214:217], v[174:177], v[102:105]
	v_mfma_f32_16x16x32_bf16 v[106:109], v[218:221], v[174:177], v[106:109]
	v_mfma_f32_16x16x32_bf16 v[66:69], v[222:225], v[174:177], v[66:69]
	s_add_i32 s22, s50, 1
	s_cmp_lg_u32 s22, 16
	s_cbranch_scc1 .LBB0_1180
	s_add_i32 s31, s31, s28
	s_cmp_ge_i32 s31, s33
	s_cbranch_scc1 .LBB0_1179
	s_mov_b32 s12, s10
	s_cmpk_gt_i32 s31, 0x9f
	s_mov_b64 s[2:3], -1
	s_cbranch_scc0 .LBB0_1176
	s_lshl_b32 s2, s31, 2
	s_add_i32 s2, s2, 0x7ffffd80
	s_and_b32 s13, s2, 0x7ffffff8
	s_and_b32 s2, s31, 1
	s_or_b32 s47, s2, 20
	s_mov_b64 s[2:3], 0

.LBB0_1180:
	s_add_i32 s49, s49, 2
	s_cmp_lg_u32 s49, 16
	s_waitcnt lgkmcnt(0)
	s_mov_b32 s98, 1
	s_cbranch_scc1 .LBB0_1147
	s_mov_b32 s98, 0
	v_mfma_f32_16x16x32_bf16 v[98:101], v[210:213], v[178:181], v[98:101]
	v_mfma_f32_16x16x32_bf16 v[90:93], v[214:217], v[178:181], v[90:93]
	v_mfma_f32_16x16x32_bf16 v[94:97], v[218:221], v[178:181], v[94:97]
	v_mfma_f32_16x16x32_bf16 v[86:89], v[222:225], v[178:181], v[86:89]
	v_mfma_f32_16x16x32_bf16 v[82:85], v[210:213], v[182:185], v[82:85]
	v_mfma_f32_16x16x32_bf16 v[74:77], v[214:217], v[182:185], v[74:77]
	v_mfma_f32_16x16x32_bf16 v[78:81], v[218:221], v[182:185], v[78:81]
	v_mfma_f32_16x16x32_bf16 v[70:73], v[222:225], v[182:185], v[70:73]
	v_mfma_f32_16x16x32_bf16 v[62:65], v[210:213], v[186:189], v[62:65]
	v_mfma_f32_16x16x32_bf16 v[54:57], v[214:217], v[186:189], v[54:57]
	v_mfma_f32_16x16x32_bf16 v[58:61], v[218:221], v[186:189], v[58:61]
	v_mfma_f32_16x16x32_bf16 v[50:53], v[222:225], v[186:189], v[50:53]
	v_mfma_f32_16x16x32_bf16 v[46:49], v[210:213], v[190:193], v[46:49]
	v_mfma_f32_16x16x32_bf16 v[38:41], v[214:217], v[190:193], v[38:41]
	v_mfma_f32_16x16x32_bf16 v[42:45], v[218:221], v[190:193], v[42:45]
	v_mfma_f32_16x16x32_bf16 v[34:37], v[222:225], v[190:193], v[34:37]
	s_nop 7
	s_nop 7
	v_mul_f32_e32 v165, 0xbfb8aa3b, v158
	v_exp_f32_e32 v165, v165
	v_mov_b32_e32 v163, v0
	v_mul_f32_e32 v166, 0xbfb8aa3b, v159
	v_add_f32_e32 v165, 1.0, v165
	v_rcp_f32_e32 v165, v165
	v_ashrrev_i32_e32 v162, 1, v163
	v_exp_f32_e32 v166, v166
	v_and_b32_e32 v164, 0xc0, v163
	v_and_b32_e32 v162, 0xffffff80, v162
	v_lshl_add_u32 v162, s38, 8, v162
	v_lshl_or_b32 v164, s34, 8, v164
	v_and_or_b32 v162, v163, 15, v162
	v_ashrrev_i32_e32 v164, 1, v164
	v_lshrrev_b32_e32 v163, 2, v163
	v_mul_f32_e32 v158, v158, v165
	v_and_or_b32 v164, v163, 12, v164
	v_mul_f32_e32 v154, v154, v158
	v_add_f32_e32 v158, 1.0, v166
	v_mul_f32_e32 v163, 0xbfb8aa3b, v160
	v_rcp_f32_e32 v158, v158
	v_exp_f32_e32 v163, v163
	v_mul_f32_e32 v165, 0xbfb8aa3b, v161
	v_exp_f32_e32 v165, v165
	v_mul_f32_e32 v158, v159, v158
	v_add_f32_e32 v159, 1.0, v163
	v_rcp_f32_e32 v159, v159
	v_add_f32_e32 v163, 1.0, v165
	v_rcp_f32_e32 v163, v163
	v_mul_f32_e32 v155, v155, v158
	v_mul_f32_e32 v158, v160, v159
	v_mul_f32_e32 v156, v156, v158
	v_mul_f32_e32 v158, v161, v163
	v_mul_f32_e32 v157, v157, v158
	v_cvt_pk_bf16_f32 v159, v156, v157
	v_mul_f32_e32 v156, 0xbfb8aa3b, v150
	v_exp_f32_e32 v163, v156
	v_ashrrev_i32_e32 v165, 31, v164
	v_lshlrev_b64 v[156:157], 1, v[164:165]
	v_mul_f32_e32 v164, 0xbfb8aa3b, v151
	v_add_f32_e32 v163, 1.0, v163
	v_rcp_f32_e32 v163, v163
	v_exp_f32_e32 v164, v164
	v_cvt_pk_bf16_f32 v158, v154, v155
	v_mov_b64_e32 v[154:155], s[6:7]
	v_mad_i64_i32 v[160:161], s[2:3], v162, s45, v[154:155]
	v_lshl_add_u64 v[160:161], v[160:161], 0, v[156:157]
	v_mul_f32_e32 v150, v150, v163
	global_store_dwordx2 v[160:161], v[158:159], off
	v_mul_f32_e32 v146, v146, v150
	v_add_f32_e32 v150, 1.0, v164
	v_mul_f32_e32 v158, 0xbfb8aa3b, v152
	v_rcp_f32_e32 v150, v150
	v_exp_f32_e32 v158, v158
	v_mul_f32_e32 v159, 0xbfb8aa3b, v153
	v_exp_f32_e32 v159, v159
	v_mul_f32_e32 v150, v151, v150
	v_add_f32_e32 v151, 1.0, v158
	v_rcp_f32_e32 v151, v151
	v_add_f32_e32 v158, 1.0, v159
	v_rcp_f32_e32 v158, v158
	v_mul_f32_e32 v147, v147, v150
	v_mul_f32_e32 v150, v152, v151
	v_mul_f32_e32 v148, v148, v150
	v_mul_f32_e32 v150, v153, v158
	v_mul_f32_e32 v149, v149, v150
	v_mul_f32_e32 v150, 0xbfb8aa3b, v142
	v_exp_f32_e32 v150, v150
	v_cvt_pk_bf16_f32 v146, v146, v147
	v_cvt_pk_bf16_f32 v147, v148, v149
	global_store_dwordx2 v[160:161], v[146:147], off offset:32
	v_add_f32_e32 v146, 1.0, v150
	v_rcp_f32_e32 v146, v146
	v_mul_f32_e32 v147, 0xbfb8aa3b, v143
	v_exp_f32_e32 v147, v147
	v_or_b32_e32 v148, 16, v162
	v_mul_f32_e32 v142, v142, v146
	v_mul_f32_e32 v138, v138, v142
	v_add_f32_e32 v142, 1.0, v147
	v_mul_f32_e32 v146, 0xbfb8aa3b, v144
	v_rcp_f32_e32 v142, v142
	v_exp_f32_e32 v146, v146
	v_mul_f32_e32 v147, 0xbfb8aa3b, v145
	v_exp_f32_e32 v147, v147
	v_mul_f32_e32 v142, v143, v142
	v_add_f32_e32 v143, 1.0, v146
	v_rcp_f32_e32 v143, v143
	v_add_f32_e32 v146, 1.0, v147
	v_rcp_f32_e32 v146, v146
	v_mul_f32_e32 v139, v139, v142
	v_mul_f32_e32 v142, v144, v143
	v_mul_f32_e32 v140, v140, v142
	v_mul_f32_e32 v142, v145, v146
	v_mul_f32_e32 v141, v141, v142
	v_cvt_pk_bf16_f32 v138, v138, v139
	v_cvt_pk_bf16_f32 v139, v140, v141
	v_mul_f32_e32 v140, 0xbfb8aa3b, v134
	v_exp_f32_e32 v142, v140
	v_mul_f32_e32 v143, 0xbfb8aa3b, v135
	v_exp_f32_e32 v143, v143
	v_mad_i64_i32 v[140:141], s[2:3], v148, s45, v[154:155]
	v_add_f32_e32 v142, 1.0, v142
	v_rcp_f32_e32 v142, v142
	v_lshl_add_u64 v[140:141], v[140:141], 0, v[156:157]
	global_store_dwordx2 v[140:141], v[138:139], off
	v_mul_f32_e32 v138, 0xbfb8aa3b, v136
	v_mul_f32_e32 v134, v134, v142
	v_mul_f32_e32 v130, v130, v134
	v_add_f32_e32 v134, 1.0, v143
	v_rcp_f32_e32 v134, v134
	v_exp_f32_e32 v138, v138
	v_mul_f32_e32 v139, 0xbfb8aa3b, v137
	v_exp_f32_e32 v139, v139
	v_mul_f32_e32 v134, v135, v134
	v_add_f32_e32 v135, 1.0, v138
	v_rcp_f32_e32 v135, v135
	v_add_f32_e32 v138, 1.0, v139
	v_rcp_f32_e32 v138, v138
	v_mul_f32_e32 v131, v131, v134
	v_mul_f32_e32 v134, v136, v135
	v_mul_f32_e32 v132, v132, v134
	v_mul_f32_e32 v134, v137, v138
	v_mul_f32_e32 v133, v133, v134
	v_mul_f32_e32 v134, 0xbfb8aa3b, v126
	v_exp_f32_e32 v134, v134
	v_cvt_pk_bf16_f32 v130, v130, v131
	v_cvt_pk_bf16_f32 v131, v132, v133
	global_store_dwordx2 v[140:141], v[130:131], off offset:32
	v_add_f32_e32 v130, 1.0, v134
	v_rcp_f32_e32 v130, v130
	v_mul_f32_e32 v131, 0xbfb8aa3b, v127
	v_exp_f32_e32 v131, v131
	v_or_b32_e32 v132, 32, v162
	v_mul_f32_e32 v126, v126, v130
	v_mul_f32_e32 v122, v122, v126
	v_add_f32_e32 v126, 1.0, v131
	v_mul_f32_e32 v130, 0xbfb8aa3b, v128
	v_rcp_f32_e32 v126, v126
	v_exp_f32_e32 v130, v130
	v_mul_f32_e32 v131, 0xbfb8aa3b, v129
	v_exp_f32_e32 v131, v131
	v_mul_f32_e32 v126, v127, v126
	v_add_f32_e32 v127, 1.0, v130
	v_rcp_f32_e32 v127, v127
	v_add_f32_e32 v130, 1.0, v131
	v_rcp_f32_e32 v130, v130
	v_mul_f32_e32 v123, v123, v126
	v_mul_f32_e32 v126, v128, v127
	v_mul_f32_e32 v124, v124, v126
	v_mul_f32_e32 v126, v129, v130
	v_mul_f32_e32 v125, v125, v126
	v_cvt_pk_bf16_f32 v122, v122, v123
	v_cvt_pk_bf16_f32 v123, v124, v125
	v_mul_f32_e32 v124, 0xbfb8aa3b, v118
	v_exp_f32_e32 v126, v124
	v_mul_f32_e32 v127, 0xbfb8aa3b, v119
	v_exp_f32_e32 v127, v127
	v_mad_i64_i32 v[124:125], s[2:3], v132, s45, v[154:155]
	v_add_f32_e32 v126, 1.0, v126
	v_rcp_f32_e32 v126, v126
	v_lshl_add_u64 v[124:125], v[124:125], 0, v[156:157]
	global_store_dwordx2 v[124:125], v[122:123], off
	v_mul_f32_e32 v122, 0xbfb8aa3b, v120
	v_mul_f32_e32 v118, v118, v126
	v_mul_f32_e32 v114, v114, v118
	v_add_f32_e32 v118, 1.0, v127
	v_rcp_f32_e32 v118, v118
	v_exp_f32_e32 v122, v122
	v_mul_f32_e32 v123, 0xbfb8aa3b, v121
	v_exp_f32_e32 v123, v123
	v_mul_f32_e32 v118, v119, v118
	v_add_f32_e32 v119, 1.0, v122
	v_rcp_f32_e32 v119, v119
	v_add_f32_e32 v122, 1.0, v123
	v_rcp_f32_e32 v122, v122
	v_mul_f32_e32 v115, v115, v118
	v_mul_f32_e32 v118, v120, v119
	v_mul_f32_e32 v116, v116, v118
	v_mul_f32_e32 v118, v121, v122
	v_mul_f32_e32 v117, v117, v118
	v_mul_f32_e32 v118, 0xbfb8aa3b, v110
	v_exp_f32_e32 v118, v118
	v_cvt_pk_bf16_f32 v114, v114, v115
	v_cvt_pk_bf16_f32 v115, v116, v117
	global_store_dwordx2 v[124:125], v[114:115], off offset:32
	v_add_f32_e32 v114, 1.0, v118
	v_rcp_f32_e32 v114, v114
	v_mul_f32_e32 v115, 0xbfb8aa3b, v111
	v_exp_f32_e32 v115, v115
	v_or_b32_e32 v116, 48, v162
	v_mul_f32_e32 v110, v110, v114
	v_mul_f32_e32 v106, v106, v110
	v_add_f32_e32 v110, 1.0, v115
	v_mul_f32_e32 v114, 0xbfb8aa3b, v112
	v_rcp_f32_e32 v110, v110
	v_exp_f32_e32 v114, v114
	v_mul_f32_e32 v115, 0xbfb8aa3b, v113
	v_exp_f32_e32 v115, v115
	v_mul_f32_e32 v110, v111, v110
	v_add_f32_e32 v111, 1.0, v114
	v_rcp_f32_e32 v111, v111
	v_add_f32_e32 v114, 1.0, v115
	v_rcp_f32_e32 v114, v114
	v_mul_f32_e32 v107, v107, v110
	v_mul_f32_e32 v110, v112, v111
	v_mul_f32_e32 v108, v108, v110
	v_mul_f32_e32 v110, v113, v114
	v_mul_f32_e32 v109, v109, v110
	v_cvt_pk_bf16_f32 v106, v106, v107
	v_cvt_pk_bf16_f32 v107, v108, v109
	v_mul_f32_e32 v108, 0xbfb8aa3b, v102
	v_exp_f32_e32 v110, v108
	v_mul_f32_e32 v111, 0xbfb8aa3b, v103
	v_exp_f32_e32 v111, v111
	v_mad_i64_i32 v[108:109], s[2:3], v116, s45, v[154:155]
	v_add_f32_e32 v110, 1.0, v110
	v_rcp_f32_e32 v110, v110
	v_lshl_add_u64 v[108:109], v[108:109], 0, v[156:157]
	global_store_dwordx2 v[108:109], v[106:107], off
	v_mul_f32_e32 v106, 0xbfb8aa3b, v104
	v_mul_f32_e32 v102, v102, v110
	v_mul_f32_e32 v66, v66, v102
	v_add_f32_e32 v102, 1.0, v111
	v_rcp_f32_e32 v102, v102
	v_exp_f32_e32 v106, v106
	v_mul_f32_e32 v107, 0xbfb8aa3b, v105
	v_exp_f32_e32 v107, v107
	v_mul_f32_e32 v102, v103, v102
	v_add_f32_e32 v103, 1.0, v106
	v_rcp_f32_e32 v103, v103
	v_add_f32_e32 v106, 1.0, v107
	v_rcp_f32_e32 v106, v106
	v_mul_f32_e32 v67, v67, v102
	v_mul_f32_e32 v102, v104, v103
	v_mul_f32_e32 v68, v68, v102
	v_mul_f32_e32 v102, v105, v106
	v_mul_f32_e32 v69, v69, v102
	v_mul_f32_e32 v102, 0xbfb8aa3b, v98
	v_exp_f32_e32 v102, v102
	v_cvt_pk_bf16_f32 v66, v66, v67
	v_cvt_pk_bf16_f32 v67, v68, v69
	global_store_dwordx2 v[108:109], v[66:67], off offset:32
	v_add_f32_e32 v66, 1.0, v102
	v_rcp_f32_e32 v66, v66
	v_mul_f32_e32 v67, 0xbfb8aa3b, v99
	v_mul_f32_e32 v69, 0xbfb8aa3b, v100
	v_exp_f32_e32 v67, v67
	v_mul_f32_e32 v66, v98, v66
	v_mul_f32_e32 v66, v94, v66
	v_exp_f32_e32 v69, v69
	v_mul_f32_e32 v94, 0xbfb8aa3b, v101
	v_exp_f32_e32 v94, v94
	v_add_f32_e32 v67, 1.0, v67
	v_add_f32_e32 v69, 1.0, v69
	v_rcp_f32_e32 v67, v67
	v_rcp_f32_e32 v69, v69
	v_add_f32_e32 v94, 1.0, v94
	v_rcp_f32_e32 v94, v94
	v_mul_f32_e32 v67, v99, v67
	v_mul_f32_e32 v69, v100, v69
	v_mul_f32_e32 v67, v95, v67
	v_mul_f32_e32 v69, v96, v69
	v_mul_f32_e32 v94, v101, v94
	v_mul_f32_e32 v94, v97, v94
	v_cvt_pk_bf16_f32 v66, v66, v67
	v_cvt_pk_bf16_f32 v67, v69, v94
	v_mul_f32_e32 v69, 0xbfb8aa3b, v90
	v_exp_f32_e32 v94, v69
	v_or_b32_e32 v68, 64, v162
	v_mad_i64_i32 v[68:69], s[2:3], v68, s45, v[154:155]
	v_add_f32_e32 v94, 1.0, v94
	v_rcp_f32_e32 v94, v94
	v_lshl_add_u64 v[68:69], v[68:69], 0, v[156:157]
	global_store_dwordx2 v[68:69], v[66:67], off
	v_mul_f32_e32 v95, 0xbfb8aa3b, v91
	v_mul_f32_e32 v66, v90, v94
	v_mul_f32_e32 v66, v86, v66
	v_mul_f32_e32 v86, 0xbfb8aa3b, v92
	v_exp_f32_e32 v86, v86
	v_exp_f32_e32 v95, v95
	v_mul_f32_e32 v90, 0xbfb8aa3b, v93
	v_exp_f32_e32 v90, v90
	v_add_f32_e32 v86, 1.0, v86
	v_rcp_f32_e32 v86, v86
	v_add_f32_e32 v67, 1.0, v95
	v_rcp_f32_e32 v67, v67
	v_add_f32_e32 v90, 1.0, v90
	v_mul_f32_e32 v86, v92, v86
	v_rcp_f32_e32 v90, v90
	v_mul_f32_e32 v86, v88, v86
	v_mul_f32_e32 v88, 0xbfb8aa3b, v82
	v_exp_f32_e32 v88, v88
	v_mul_f32_e32 v67, v91, v67
	v_mul_f32_e32 v67, v87, v67
	v_mul_f32_e32 v87, v93, v90
	v_cvt_pk_bf16_f32 v66, v66, v67
	v_mul_f32_e32 v87, v89, v87
	v_cvt_pk_bf16_f32 v67, v86, v87
	global_store_dwordx2 v[68:69], v[66:67], off offset:32
	v_add_f32_e32 v66, 1.0, v88
	v_rcp_f32_e32 v66, v66
	v_mul_f32_e32 v67, 0xbfb8aa3b, v83
	v_mul_f32_e32 v69, 0xbfb8aa3b, v84
	v_exp_f32_e32 v67, v67
	v_mul_f32_e32 v66, v82, v66
	v_mul_f32_e32 v66, v78, v66
	v_exp_f32_e32 v69, v69
	v_mul_f32_e32 v78, 0xbfb8aa3b, v85
	v_exp_f32_e32 v78, v78
	v_add_f32_e32 v67, 1.0, v67
	v_add_f32_e32 v69, 1.0, v69
	v_rcp_f32_e32 v67, v67
	v_rcp_f32_e32 v69, v69
	v_add_f32_e32 v78, 1.0, v78
	v_rcp_f32_e32 v78, v78
	v_mul_f32_e32 v67, v83, v67
	v_mul_f32_e32 v69, v84, v69
	v_mul_f32_e32 v67, v79, v67
	v_mul_f32_e32 v69, v80, v69
	v_mul_f32_e32 v78, v85, v78
	v_mul_f32_e32 v78, v81, v78
	v_cvt_pk_bf16_f32 v66, v66, v67
	v_cvt_pk_bf16_f32 v67, v69, v78
	v_mul_f32_e32 v69, 0xbfb8aa3b, v74
	v_exp_f32_e32 v78, v69
	v_or_b32_e32 v68, 0x50, v162
	v_mad_i64_i32 v[68:69], s[2:3], v68, s45, v[154:155]
	v_add_f32_e32 v78, 1.0, v78
	v_rcp_f32_e32 v78, v78
	v_lshl_add_u64 v[68:69], v[68:69], 0, v[156:157]
	global_store_dwordx2 v[68:69], v[66:67], off
	v_mul_f32_e32 v79, 0xbfb8aa3b, v75
	v_mul_f32_e32 v66, v74, v78
	v_mul_f32_e32 v66, v70, v66
	v_mul_f32_e32 v70, 0xbfb8aa3b, v76
	v_exp_f32_e32 v70, v70
	v_exp_f32_e32 v79, v79
	v_mul_f32_e32 v74, 0xbfb8aa3b, v77
	v_exp_f32_e32 v74, v74
	v_add_f32_e32 v70, 1.0, v70
	v_rcp_f32_e32 v70, v70
	v_add_f32_e32 v67, 1.0, v79
	v_rcp_f32_e32 v67, v67
	v_add_f32_e32 v74, 1.0, v74
	v_mul_f32_e32 v70, v76, v70
	v_rcp_f32_e32 v74, v74
	v_mul_f32_e32 v70, v72, v70
	v_mul_f32_e32 v72, 0xbfb8aa3b, v62
	v_exp_f32_e32 v72, v72
	v_mul_f32_e32 v67, v75, v67
	v_mul_f32_e32 v67, v71, v67
	v_mul_f32_e32 v71, v77, v74
	v_cvt_pk_bf16_f32 v66, v66, v67
	v_mul_f32_e32 v71, v73, v71
	v_cvt_pk_bf16_f32 v67, v70, v71
	global_store_dwordx2 v[68:69], v[66:67], off offset:32
	v_add_f32_e32 v66, 1.0, v72
	v_rcp_f32_e32 v66, v66
	v_mul_f32_e32 v67, 0xbfb8aa3b, v63
	v_exp_f32_e32 v67, v67
	v_or_b32_e32 v68, 0x60, v162
	v_mul_f32_e32 v62, v62, v66
	v_mul_f32_e32 v58, v58, v62
	v_add_f32_e32 v62, 1.0, v67
	v_mul_f32_e32 v66, 0xbfb8aa3b, v64
	v_rcp_f32_e32 v62, v62
	v_exp_f32_e32 v66, v66
	v_mul_f32_e32 v67, 0xbfb8aa3b, v65
	v_exp_f32_e32 v67, v67
	v_mul_f32_e32 v62, v63, v62
	v_add_f32_e32 v63, 1.0, v66
	v_rcp_f32_e32 v63, v63
	v_add_f32_e32 v66, 1.0, v67
	v_rcp_f32_e32 v66, v66
	v_mul_f32_e32 v59, v59, v62
	v_mul_f32_e32 v62, v64, v63
	v_mul_f32_e32 v60, v60, v62
	v_mul_f32_e32 v62, v65, v66
	v_mul_f32_e32 v61, v61, v62
	v_cvt_pk_bf16_f32 v58, v58, v59
	v_cvt_pk_bf16_f32 v59, v60, v61
	v_mul_f32_e32 v60, 0xbfb8aa3b, v54
	v_exp_f32_e32 v62, v60
	v_mul_f32_e32 v63, 0xbfb8aa3b, v55
	v_exp_f32_e32 v63, v63
	v_mad_i64_i32 v[60:61], s[2:3], v68, s45, v[154:155]
	v_add_f32_e32 v62, 1.0, v62
	v_rcp_f32_e32 v62, v62
	v_lshl_add_u64 v[60:61], v[60:61], 0, v[156:157]
	global_store_dwordx2 v[60:61], v[58:59], off
	v_mul_f32_e32 v58, 0xbfb8aa3b, v56
	v_mul_f32_e32 v54, v54, v62
	v_mul_f32_e32 v50, v50, v54
	v_add_f32_e32 v54, 1.0, v63
	v_rcp_f32_e32 v54, v54
	v_exp_f32_e32 v58, v58
	v_mul_f32_e32 v59, 0xbfb8aa3b, v57
	v_exp_f32_e32 v59, v59
	v_mul_f32_e32 v54, v55, v54
	v_add_f32_e32 v55, 1.0, v58
	v_rcp_f32_e32 v55, v55
	v_add_f32_e32 v58, 1.0, v59
	v_rcp_f32_e32 v58, v58
	v_mul_f32_e32 v51, v51, v54
	v_mul_f32_e32 v54, v56, v55
	v_mul_f32_e32 v52, v52, v54
	v_mul_f32_e32 v54, v57, v58
	v_mul_f32_e32 v53, v53, v54
	v_mul_f32_e32 v54, 0xbfb8aa3b, v46
	v_exp_f32_e32 v54, v54
	v_cvt_pk_bf16_f32 v50, v50, v51
	v_cvt_pk_bf16_f32 v51, v52, v53
	global_store_dwordx2 v[60:61], v[50:51], off offset:32
	v_add_f32_e32 v50, 1.0, v54
	v_rcp_f32_e32 v50, v50
	v_mul_f32_e32 v51, 0xbfb8aa3b, v47
	v_exp_f32_e32 v51, v51
	v_or_b32_e32 v52, 0x70, v162
	v_mul_f32_e32 v46, v46, v50
	v_mul_f32_e32 v42, v42, v46
	v_add_f32_e32 v46, 1.0, v51
	v_mul_f32_e32 v50, 0xbfb8aa3b, v48
	v_rcp_f32_e32 v46, v46
	v_exp_f32_e32 v50, v50
	v_mul_f32_e32 v51, 0xbfb8aa3b, v49
	v_exp_f32_e32 v51, v51
	v_mul_f32_e32 v46, v47, v46
	v_add_f32_e32 v47, 1.0, v50
	v_rcp_f32_e32 v47, v47
	v_add_f32_e32 v50, 1.0, v51
	v_rcp_f32_e32 v50, v50
	v_mul_f32_e32 v43, v43, v46
	v_mul_f32_e32 v46, v48, v47
	v_mul_f32_e32 v44, v44, v46
	v_mul_f32_e32 v46, v49, v50
	v_mul_f32_e32 v45, v45, v46
	v_cvt_pk_bf16_f32 v42, v42, v43
	v_cvt_pk_bf16_f32 v43, v44, v45
	v_mul_f32_e32 v44, 0xbfb8aa3b, v38
	v_exp_f32_e32 v46, v44
	v_mul_f32_e32 v47, 0xbfb8aa3b, v39
	v_exp_f32_e32 v47, v47
	v_mad_i64_i32 v[44:45], s[2:3], v52, s45, v[154:155]
	v_add_f32_e32 v46, 1.0, v46
	v_rcp_f32_e32 v46, v46
	v_lshl_add_u64 v[44:45], v[44:45], 0, v[156:157]
	global_store_dwordx2 v[44:45], v[42:43], off
	v_mul_f32_e32 v42, 0xbfb8aa3b, v40
	v_mul_f32_e32 v38, v38, v46
	v_mul_f32_e32 v34, v34, v38
	v_add_f32_e32 v38, 1.0, v47
	v_rcp_f32_e32 v38, v38
	v_exp_f32_e32 v42, v42
	v_mul_f32_e32 v43, 0xbfb8aa3b, v41
	v_exp_f32_e32 v43, v43
	v_mul_f32_e32 v38, v39, v38
	v_add_f32_e32 v39, 1.0, v42
	v_rcp_f32_e32 v39, v39
	v_add_f32_e32 v42, 1.0, v43
	v_rcp_f32_e32 v42, v42
	v_mul_f32_e32 v35, v35, v38
	v_mul_f32_e32 v38, v40, v39
	v_mul_f32_e32 v36, v36, v38
	v_mul_f32_e32 v38, v41, v42
	v_mul_f32_e32 v37, v37, v38
	s_add_i32 s46, s46, s28
	v_cvt_pk_bf16_f32 v34, v34, v35
	v_cvt_pk_bf16_f32 v35, v36, v37
	v_mov_b32_e32 v37, 0
	s_cmp_ge_i32 s46, s33
	global_store_dwordx2 v[44:45], v[34:35], off offset:32
	s_cbranch_scc1 .LBB0_1146
	s_mov_b32 s12, s10
	s_cmpk_gt_i32 s46, 0x9f
	s_mov_b64 s[2:3], -1
	s_cbranch_scc0 .LBB0_1184
	s_lshl_b32 s2, s46, 2
	s_add_i32 s2, s2, 0x7ffffd80
	s_and_b32 s13, s2, 0x7ffffff8
	s_and_b32 s2, s46, 1
	s_or_b32 s34, s2, 20
	s_mov_b64 s[2:3], 0

.LBB0_1203:
	ds_read_b128 v[122:125], v251
	ds_read_b128 v[126:129], v249
	ds_read_b128 v[130:133], v251 offset:4096
	ds_read_b128 v[134:137], v249 offset:4096
	ds_read_b128 v[90:93], v255
	ds_read_b128 v[94:97], v253
	ds_read_b128 v[98:101], v255 offset:4096
	ds_read_b128 v[102:105], v253 offset:4096
	ds_read_b128 v[106:109], v247
	ds_read_b128 v[110:113], v245
	s_cmp_eq_u32 s98, 0
	s_cbranch_scc1 .Lnodef_I0_3
	v_mfma_f32_16x16x32_bf16 v[54:57], v[138:141], v[114:117], v[54:57]
	v_mfma_f32_16x16x32_bf16 v[46:49], v[142:145], v[114:117], v[46:49]
	v_mfma_f32_16x16x32_bf16 v[50:53], v[146:149], v[114:117], v[50:53]
	v_mfma_f32_16x16x32_bf16 v[42:45], v[150:153], v[114:117], v[42:45]
	v_mfma_f32_16x16x32_bf16 v[34:37], v[138:141], v[118:121], v[34:37]
	v_mfma_f32_16x16x32_bf16 v[30:33], v[142:145], v[118:121], v[30:33]
	v_mfma_f32_16x16x32_bf16 v[38:41], v[146:149], v[118:121], v[38:41]
	v_mfma_f32_16x16x32_bf16 v[26:29], v[150:153], v[118:121], v[26:29]
.Lnodef_I0_3:
	ds_read_b128 v[114:117], v247 offset:4096
	ds_read_b128 v[118:121], v245 offset:4096
	s_add_i32 s2, s36, -1
	s_cmp_lt_i32 s2, s35
	s_cselect_b64 s[8:9], -1, 0
	s_cmp_ge_i32 s2, s35
	s_waitcnt lgkmcnt(7)
	v_mfma_f32_16x16x32_bf16 v[58:61], v[122:125], v[90:93], v[58:61]
	v_mfma_f32_16x16x32_bf16 v[82:85], v[126:129], v[90:93], v[82:85]
	v_mfma_f32_16x16x32_bf16 v[86:89], v[130:133], v[90:93], v[86:89]
	v_mfma_f32_16x16x32_bf16 v[78:81], v[134:137], v[90:93], v[78:81]
	s_waitcnt lgkmcnt(6)
	v_mfma_f32_16x16x32_bf16 v[74:77], v[122:125], v[94:97], v[74:77]
	v_mfma_f32_16x16x32_bf16 v[66:69], v[126:129], v[94:97], v[66:69]
	v_mfma_f32_16x16x32_bf16 v[70:73], v[130:133], v[94:97], v[70:73]
	v_mfma_f32_16x16x32_bf16 v[62:65], v[134:137], v[94:97], v[62:65]
	s_waitcnt vmcnt(4)
	ds_write_b128 v238, v[22:25]
	ds_write_b128 v238, v[18:21] offset:8192
.LBB0_1205:
	s_lshl_b32 s2, s43, 8
	s_or_b32 s2, s2, s27
	s_ashr_i32 s3, s2, 31
	s_lshl_b64 s[12:13], s[2:3], 11
	s_lshl_b32 s2, s45, 6
	s_ashr_i32 s3, s2, 31
	s_add_u32 s14, s11, s12
	s_addc_u32 s15, s24, s13
	s_lshl_b64 s[20:21], s[2:3], 1
	s_add_u32 s2, s14, s20
	s_addc_u32 s3, s15, s21
	global_load_dwordx4 v[18:21], v237, s[2:3]
	global_load_dwordx4 v[22:25], v236, s[2:3]
	s_andn2_b64 vcc, exec, s[8:9]
	ds_read_b128 v[138:141], v243
	ds_read_b128 v[142:145], v241
	ds_read_b128 v[146:149], v243 offset:4096
	ds_read_b128 v[150:153], v241 offset:4096
	s_waitcnt lgkmcnt(11)
	v_mfma_f32_16x16x32_bf16 v[54:57], v[122:125], v[98:101], v[54:57]
	v_mfma_f32_16x16x32_bf16 v[46:49], v[126:129], v[98:101], v[46:49]
	v_mfma_f32_16x16x32_bf16 v[50:53], v[130:133], v[98:101], v[50:53]
	v_mfma_f32_16x16x32_bf16 v[42:45], v[134:137], v[98:101], v[42:45]
	s_waitcnt vmcnt(4)
	ds_write_b128 v238, v[14:17] offset:32768
	ds_write_b128 v238, v[10:13] offset:40960
.LBB0_1207:
	s_lshl_b32 s8, s42, 8
	s_ashr_i32 s9, s8, 31
	s_lshl_b64 s[14:15], s[8:9], 11
	s_add_u32 s8, s25, s14
	s_addc_u32 s9, s26, s15
	s_add_u32 s8, s8, s20
	s_addc_u32 s9, s9, s21
	global_load_dwordx4 v[10:13], v237, s[8:9]
	global_load_dwordx4 v[14:17], v236, s[8:9]
	s_and_b64 vcc, exec, s[2:3]
	s_waitcnt lgkmcnt(12)
	v_mfma_f32_16x16x32_bf16 v[34:37], v[122:125], v[102:105], v[34:37]
	v_mfma_f32_16x16x32_bf16 v[30:33], v[126:129], v[102:105], v[30:33]
	v_mfma_f32_16x16x32_bf16 v[38:41], v[130:133], v[102:105], v[38:41]
	v_mfma_f32_16x16x32_bf16 v[26:29], v[134:137], v[102:105], v[26:29]
	s_waitcnt vmcnt(4)
	ds_write_b128 v238, v[6:9] offset:49152
	ds_write_b128 v238, v[2:5] offset:57344
.LBB0_1209:
	global_load_dwordx4 v[2:5], v235, s[8:9]
	global_load_dwordx4 v[6:9], v234, s[8:9]
	s_waitcnt lgkmcnt(4)
	v_mfma_f32_16x16x32_bf16 v[58:61], v[138:141], v[106:109], v[58:61]
	v_mfma_f32_16x16x32_bf16 v[82:85], v[142:145], v[106:109], v[82:85]
	v_mfma_f32_16x16x32_bf16 v[86:89], v[146:149], v[106:109], v[86:89]
	v_mfma_f32_16x16x32_bf16 v[78:81], v[150:153], v[106:109], v[78:81]
	v_mfma_f32_16x16x32_bf16 v[74:77], v[138:141], v[110:113], v[74:77]
	v_mfma_f32_16x16x32_bf16 v[66:69], v[142:145], v[110:113], v[66:69]
	v_mfma_f32_16x16x32_bf16 v[70:73], v[146:149], v[110:113], v[70:73]
	v_mfma_f32_16x16x32_bf16 v[62:65], v[150:153], v[110:113], v[62:65]
	s_add_i32 s45, s45, 1
	s_cmp_lg_u32 s45, 16
	s_cbranch_scc1 .LBB0_1218
	s_add_i32 s22, s22, s23
	s_cmp_ge_i32 s22, s29
	s_cbranch_scc1 .LBB0_1217
	s_mov_b32 s8, s10
	s_cmpk_gt_i32 s22, 0xaf
	s_cbranch_scc1 .LBB0_1217
	s_cmpk_gt_i32 s22, 0x9f
	s_mov_b64 s[2:3], -1
	s_cbranch_scc0 .LBB0_1214
	s_lshl_b32 s2, s22, 2
	s_add_i32 s2, s2, 0x7ffffd80
	s_and_b32 s9, s2, 0x7ffffff8
	s_and_b32 s2, s22, 1
	s_or_b32 s42, s2, 20
	s_mov_b64 s[2:3], 0

.LBB0_1218:
	s_waitcnt lgkmcnt(0)
	s_barrier
	ds_read_b128 v[122:125], v250
	ds_read_b128 v[126:129], v248
	ds_read_b128 v[130:133], v250 offset:4096
	ds_read_b128 v[134:137], v248 offset:4096
	ds_read_b128 v[90:93], v254
	ds_read_b128 v[94:97], v252
	ds_read_b128 v[98:101], v254 offset:4096
	ds_read_b128 v[102:105], v252 offset:4096
	ds_read_b128 v[106:109], v246
	ds_read_b128 v[110:113], v244
	v_mfma_f32_16x16x32_bf16 v[54:57], v[138:141], v[114:117], v[54:57]
	v_mfma_f32_16x16x32_bf16 v[46:49], v[142:145], v[114:117], v[46:49]
	v_mfma_f32_16x16x32_bf16 v[50:53], v[146:149], v[114:117], v[50:53]
	v_mfma_f32_16x16x32_bf16 v[42:45], v[150:153], v[114:117], v[42:45]
	v_mfma_f32_16x16x32_bf16 v[34:37], v[138:141], v[118:121], v[34:37]
	v_mfma_f32_16x16x32_bf16 v[30:33], v[142:145], v[118:121], v[30:33]
	v_mfma_f32_16x16x32_bf16 v[38:41], v[146:149], v[118:121], v[38:41]
	v_mfma_f32_16x16x32_bf16 v[26:29], v[150:153], v[118:121], v[26:29]
	ds_read_b128 v[114:117], v246 offset:4096
	ds_read_b128 v[118:121], v244 offset:4096
	s_cmp_lt_i32 s36, s35
	s_cselect_b64 s[20:21], -1, 0
	s_cmp_ge_i32 s36, s35
	s_cselect_b64 s[8:9], -1, 0
	s_and_b64 vcc, exec, s[8:9]
	s_waitcnt lgkmcnt(7)
	v_mfma_f32_16x16x32_bf16 v[58:61], v[122:125], v[90:93], v[58:61]
	v_mfma_f32_16x16x32_bf16 v[82:85], v[126:129], v[90:93], v[82:85]
	v_mfma_f32_16x16x32_bf16 v[86:89], v[130:133], v[90:93], v[86:89]
	v_mfma_f32_16x16x32_bf16 v[78:81], v[134:137], v[90:93], v[78:81]
	s_waitcnt lgkmcnt(6)
	v_mfma_f32_16x16x32_bf16 v[74:77], v[122:125], v[94:97], v[74:77]
	v_mfma_f32_16x16x32_bf16 v[66:69], v[126:129], v[94:97], v[66:69]
	v_mfma_f32_16x16x32_bf16 v[70:73], v[130:133], v[94:97], v[70:73]
	v_mfma_f32_16x16x32_bf16 v[62:65], v[134:137], v[94:97], v[62:65]
	s_waitcnt vmcnt(4)
	ds_write_b128 v239, v[18:21]
	ds_write_b128 v239, v[22:25] offset:8192
.LBB0_1220:
	s_lshl_b32 s2, s45, 6
	s_ashr_i32 s3, s2, 31
	s_add_u32 s46, s11, s12
	s_addc_u32 s47, s24, s13
	s_lshl_b64 s[12:13], s[2:3], 1
	s_add_u32 s2, s46, s12
	s_addc_u32 s3, s47, s13
	global_load_dwordx4 v[22:25], v237, s[2:3]
	global_load_dwordx4 v[18:21], v236, s[2:3]
	s_andn2_b64 vcc, exec, s[20:21]
	ds_read_b128 v[138:141], v242
	ds_read_b128 v[142:145], v240
	ds_read_b128 v[146:149], v242 offset:4096
	ds_read_b128 v[150:153], v240 offset:4096
	s_waitcnt lgkmcnt(11)
	v_mfma_f32_16x16x32_bf16 v[54:57], v[122:125], v[98:101], v[54:57]
	v_mfma_f32_16x16x32_bf16 v[46:49], v[126:129], v[98:101], v[46:49]
	v_mfma_f32_16x16x32_bf16 v[50:53], v[130:133], v[98:101], v[50:53]
	v_mfma_f32_16x16x32_bf16 v[42:45], v[134:137], v[98:101], v[42:45]
	s_waitcnt vmcnt(4)
	ds_write_b128 v239, v[10:13] offset:32768
	ds_write_b128 v239, v[14:17] offset:40960
.LBB0_1222:
	s_add_u32 s14, s25, s14
	s_addc_u32 s15, s26, s15
	s_add_u32 s12, s14, s12
	s_addc_u32 s13, s15, s13
	global_load_dwordx4 v[14:17], v237, s[12:13]
	global_load_dwordx4 v[10:13], v236, s[12:13]
	s_and_b64 vcc, exec, s[2:3]
	s_waitcnt lgkmcnt(12)
	v_mfma_f32_16x16x32_bf16 v[34:37], v[122:125], v[102:105], v[34:37]
	v_mfma_f32_16x16x32_bf16 v[30:33], v[126:129], v[102:105], v[30:33]
	v_mfma_f32_16x16x32_bf16 v[38:41], v[130:133], v[102:105], v[38:41]
	v_mfma_f32_16x16x32_bf16 v[26:29], v[134:137], v[102:105], v[26:29]
	s_waitcnt vmcnt(4)
	ds_write_b128 v239, v[2:5] offset:49152
	ds_write_b128 v239, v[6:9] offset:57344
.LBB0_1224:
	global_load_dwordx4 v[6:9], v235, s[12:13]
	global_load_dwordx4 v[2:5], v234, s[12:13]
	s_waitcnt lgkmcnt(4)
	v_mfma_f32_16x16x32_bf16 v[58:61], v[138:141], v[106:109], v[58:61]
	v_mfma_f32_16x16x32_bf16 v[82:85], v[142:145], v[106:109], v[82:85]
	v_mfma_f32_16x16x32_bf16 v[86:89], v[146:149], v[106:109], v[86:89]
	v_mfma_f32_16x16x32_bf16 v[78:81], v[150:153], v[106:109], v[78:81]
	v_mfma_f32_16x16x32_bf16 v[74:77], v[138:141], v[110:113], v[74:77]
	v_mfma_f32_16x16x32_bf16 v[66:69], v[142:145], v[110:113], v[66:69]
	v_mfma_f32_16x16x32_bf16 v[70:73], v[146:149], v[110:113], v[70:73]
	v_mfma_f32_16x16x32_bf16 v[62:65], v[150:153], v[110:113], v[62:65]
	s_add_i32 s45, s45, 1
	s_cmp_lg_u32 s45, 16
	s_cbranch_scc1 .LBB0_1233
	s_add_i32 s22, s22, s23
	s_cmp_ge_i32 s22, s29
	s_cbranch_scc1 .LBB0_1232
	s_mov_b32 s12, s10
	s_cmpk_gt_i32 s22, 0xaf
	s_cbranch_scc1 .LBB0_1232
	s_cmpk_gt_i32 s22, 0x9f
	s_mov_b64 s[2:3], -1
	s_cbranch_scc0 .LBB0_1229
	s_lshl_b32 s2, s22, 2
	s_add_i32 s2, s2, 0x7ffffd80
	s_and_b32 s13, s2, 0x7ffffff8
	s_and_b32 s2, s22, 1
	s_or_b32 s42, s2, 20
	s_mov_b64 s[2:3], 0

.LBB0_1233:
	s_add_i32 s44, s44, 2
	s_cmp_lg_u32 s44, 16
	s_waitcnt lgkmcnt(0)
	s_mov_b32 s98, 1
	s_cbranch_scc1 .LBB0_1202
	s_mov_b32 s98, 0
	v_mfma_f32_16x16x32_bf16 v[54:57], v[138:141], v[114:117], v[54:57]
	v_mfma_f32_16x16x32_bf16 v[46:49], v[142:145], v[114:117], v[46:49]
	v_mfma_f32_16x16x32_bf16 v[50:53], v[146:149], v[114:117], v[50:53]
	v_mfma_f32_16x16x32_bf16 v[42:45], v[150:153], v[114:117], v[42:45]
	v_mfma_f32_16x16x32_bf16 v[34:37], v[138:141], v[118:121], v[34:37]
	v_mfma_f32_16x16x32_bf16 v[30:33], v[142:145], v[118:121], v[30:33]
	v_mfma_f32_16x16x32_bf16 v[38:41], v[146:149], v[118:121], v[38:41]
	v_mfma_f32_16x16x32_bf16 v[26:29], v[150:153], v[118:121], v[26:29]
	s_nop 7
	s_nop 7
	v_mov_b32_e32 v90, v0
	v_mul_f32_e32 v94, 0xbfb8aa3b, v59
	v_and_b32_e32 v91, 15, v90
	v_ashrrev_i32_e32 v93, 2, v90
	v_lshl_or_b32 v91, s30, 8, v91
	v_and_b32_e32 v92, 0xc0, v90
	v_and_b32_e32 v93, 0xffffffc0, v93
	v_or_b32_e32 v91, s27, v91
	v_add_u32_e32 v96, v91, v93
	v_lshl_or_b32 v91, s28, 8, v92
	v_mul_f32_e32 v92, 0xbfb8aa3b, v58
	v_exp_f32_e32 v93, v92
	v_exp_f32_e32 v97, v94
	v_ashrrev_i32_e32 v91, 1, v91
	v_lshrrev_b32_e32 v90, 2, v90
	v_add_f32_e32 v93, 1.0, v93
	v_rcp_f32_e32 v93, v93
	v_and_or_b32 v92, v90, 12, v91
	v_mov_b64_e32 v[90:91], s[6:7]
	v_mad_i64_i32 v[94:95], s[2:3], v96, s40, v[90:91]
	v_mul_f32_e32 v58, v58, v93
	v_mul_f32_e32 v58, v86, v58
	v_add_f32_e32 v86, 1.0, v97
	v_mul_f32_e32 v93, 0xbfb8aa3b, v60
	v_rcp_f32_e32 v86, v86
	v_exp_f32_e32 v93, v93
	v_mul_f32_e32 v97, 0xbfb8aa3b, v61
	v_exp_f32_e32 v97, v97
	v_mul_f32_e32 v59, v59, v86
	v_add_f32_e32 v86, 1.0, v93
	v_rcp_f32_e32 v86, v86
	v_add_f32_e32 v93, 1.0, v97
	v_rcp_f32_e32 v93, v93
	v_mul_f32_e32 v59, v87, v59
	v_mul_f32_e32 v60, v60, v86
	v_mul_f32_e32 v60, v88, v60
	v_mul_f32_e32 v61, v61, v93
	v_mul_f32_e32 v61, v89, v61
	v_cvt_pk_bf16_f32 v58, v58, v59
	v_cvt_pk_bf16_f32 v59, v60, v61
	v_mul_f32_e32 v60, 0xbfb8aa3b, v82
	v_exp_f32_e32 v88, v60
	v_ashrrev_i32_e32 v93, 31, v92
	v_lshlrev_b64 v[60:61], 1, v[92:93]
	v_lshl_add_u64 v[86:87], v[94:95], 0, v[60:61]
	v_add_f32_e32 v88, 1.0, v88
	v_rcp_f32_e32 v88, v88
	v_mul_f32_e32 v89, 0xbfb8aa3b, v83
	v_exp_f32_e32 v89, v89
	global_store_dwordx2 v[86:87], v[58:59], off
	v_mul_f32_e32 v58, v82, v88
	v_mul_f32_e32 v58, v78, v58
	v_mul_f32_e32 v78, 0xbfb8aa3b, v84
	v_exp_f32_e32 v78, v78
	v_add_f32_e32 v59, 1.0, v89
	v_mul_f32_e32 v82, 0xbfb8aa3b, v85
	v_rcp_f32_e32 v59, v59
	v_exp_f32_e32 v82, v82
	v_add_f32_e32 v78, 1.0, v78
	v_rcp_f32_e32 v78, v78
	v_mul_f32_e32 v59, v83, v59
	v_add_f32_e32 v82, 1.0, v82
	v_rcp_f32_e32 v82, v82
	v_mul_f32_e32 v59, v79, v59
	v_mul_f32_e32 v78, v84, v78
	v_cvt_pk_bf16_f32 v58, v58, v59
	v_mul_f32_e32 v59, 0xbfb8aa3b, v74
	v_mul_f32_e32 v78, v80, v78
	v_exp_f32_e32 v80, v59
	v_mul_f32_e32 v79, v85, v82
	v_mul_f32_e32 v79, v81, v79
	v_cvt_pk_bf16_f32 v59, v78, v79
	global_store_dwordx2 v[86:87], v[58:59], off offset:32
	v_add_f32_e32 v59, 1.0, v80
	v_rcp_f32_e32 v78, v59
	v_mul_f32_e32 v59, 0xbfb8aa3b, v75
	v_exp_f32_e32 v79, v59
	v_or_b32_e32 v58, 16, v96
	v_mul_f32_e32 v74, v74, v78
	v_mul_f32_e32 v70, v70, v74
	v_add_f32_e32 v74, 1.0, v79
	v_mul_f32_e32 v78, 0xbfb8aa3b, v76
	v_rcp_f32_e32 v74, v74
	v_exp_f32_e32 v78, v78
	v_mul_f32_e32 v79, 0xbfb8aa3b, v77
	v_exp_f32_e32 v79, v79
	v_mul_f32_e32 v74, v75, v74
	v_add_f32_e32 v75, 1.0, v78
	v_rcp_f32_e32 v75, v75
	v_add_f32_e32 v78, 1.0, v79
	v_rcp_f32_e32 v78, v78
	v_mul_f32_e32 v71, v71, v74
	v_mul_f32_e32 v74, v76, v75
	v_mul_f32_e32 v72, v72, v74
	v_mul_f32_e32 v74, v77, v78
	v_mul_f32_e32 v73, v73, v74
	v_mul_f32_e32 v74, 0xbfb8aa3b, v66
	v_exp_f32_e32 v74, v74
	v_cvt_pk_bf16_f32 v70, v70, v71
	v_cvt_pk_bf16_f32 v71, v72, v73
	v_mul_f32_e32 v73, 0xbfb8aa3b, v67
	v_add_f32_e32 v72, 1.0, v74
	v_rcp_f32_e32 v72, v72
	v_exp_f32_e32 v73, v73
	v_mad_i64_i32 v[58:59], s[2:3], v58, s40, v[90:91]
	v_lshl_add_u64 v[58:59], v[58:59], 0, v[60:61]
	v_mul_f32_e32 v66, v66, v72
	global_store_dwordx2 v[58:59], v[70:71], off
	v_mul_f32_e32 v62, v62, v66
	v_add_f32_e32 v66, 1.0, v73
	v_mul_f32_e32 v70, 0xbfb8aa3b, v68
	v_rcp_f32_e32 v66, v66
	v_exp_f32_e32 v70, v70
	v_mul_f32_e32 v71, 0xbfb8aa3b, v69
	v_exp_f32_e32 v71, v71
	v_mul_f32_e32 v66, v67, v66
	v_add_f32_e32 v67, 1.0, v70
	v_rcp_f32_e32 v67, v67
	v_add_f32_e32 v70, 1.0, v71
	v_rcp_f32_e32 v70, v70
	v_mul_f32_e32 v63, v63, v66
	v_mul_f32_e32 v66, v68, v67
	v_mul_f32_e32 v64, v64, v66
	v_mul_f32_e32 v66, v69, v70
	v_cvt_pk_bf16_f32 v62, v62, v63
	v_mul_f32_e32 v63, 0xbfb8aa3b, v54
	v_mul_f32_e32 v65, v65, v66
	v_exp_f32_e32 v66, v63
	v_cvt_pk_bf16_f32 v63, v64, v65
	global_store_dwordx2 v[58:59], v[62:63], off offset:32
	v_or_b32_e32 v58, 32, v96
	v_add_f32_e32 v59, 1.0, v66
	v_rcp_f32_e32 v62, v59
	v_mul_f32_e32 v59, 0xbfb8aa3b, v55
	v_exp_f32_e32 v63, v59
	v_mad_i64_i32 v[58:59], s[2:3], v58, s40, v[90:91]
	v_mul_f32_e32 v54, v54, v62
	v_mul_f32_e32 v50, v50, v54
	v_add_f32_e32 v54, 1.0, v63
	v_mul_f32_e32 v62, 0xbfb8aa3b, v56
	v_rcp_f32_e32 v54, v54
	v_exp_f32_e32 v62, v62
	v_mul_f32_e32 v63, 0xbfb8aa3b, v57
	v_exp_f32_e32 v63, v63
	v_mul_f32_e32 v54, v55, v54
	v_add_f32_e32 v55, 1.0, v62
	v_rcp_f32_e32 v55, v55
	v_add_f32_e32 v62, 1.0, v63
	v_rcp_f32_e32 v62, v62
	v_mul_f32_e32 v51, v51, v54
	v_mul_f32_e32 v54, v56, v55
	v_mul_f32_e32 v52, v52, v54
	v_mul_f32_e32 v54, v57, v62
	v_mul_f32_e32 v53, v53, v54
	v_mul_f32_e32 v54, 0xbfb8aa3b, v46
	v_exp_f32_e32 v54, v54
	v_mul_f32_e32 v55, 0xbfb8aa3b, v47
	v_exp_f32_e32 v55, v55
	v_cvt_pk_bf16_f32 v50, v50, v51
	v_add_f32_e32 v54, 1.0, v54
	v_rcp_f32_e32 v54, v54
	v_cvt_pk_bf16_f32 v51, v52, v53
	v_lshl_add_u64 v[52:53], v[58:59], 0, v[60:61]
	global_store_dwordx2 v[52:53], v[50:51], off
	v_mul_f32_e32 v46, v46, v54
	v_mul_f32_e32 v42, v42, v46
	v_add_f32_e32 v46, 1.0, v55
	v_mul_f32_e32 v50, 0xbfb8aa3b, v48
	v_rcp_f32_e32 v46, v46
	v_exp_f32_e32 v50, v50
	v_mul_f32_e32 v51, 0xbfb8aa3b, v49
	v_exp_f32_e32 v51, v51
	v_mul_f32_e32 v46, v47, v46
	v_add_f32_e32 v47, 1.0, v50
	v_rcp_f32_e32 v47, v47
	v_add_f32_e32 v50, 1.0, v51
	v_rcp_f32_e32 v50, v50
	v_mul_f32_e32 v43, v43, v46
	v_mul_f32_e32 v46, v48, v47
	v_mul_f32_e32 v44, v44, v46
	v_mul_f32_e32 v46, v49, v50
	v_cvt_pk_bf16_f32 v42, v42, v43
	v_mul_f32_e32 v43, 0xbfb8aa3b, v34
	v_mul_f32_e32 v45, v45, v46
	v_exp_f32_e32 v46, v43
	v_cvt_pk_bf16_f32 v43, v44, v45
	global_store_dwordx2 v[52:53], v[42:43], off offset:32
	v_or_b32_e32 v42, 48, v96
	v_add_f32_e32 v43, 1.0, v46
	v_rcp_f32_e32 v44, v43
	v_mul_f32_e32 v43, 0xbfb8aa3b, v35
	v_exp_f32_e32 v45, v43
	v_mad_i64_i32 v[42:43], s[2:3], v42, s40, v[90:91]
	v_mul_f32_e32 v34, v34, v44
	v_mul_f32_e32 v34, v38, v34
	v_add_f32_e32 v38, 1.0, v45
	v_mul_f32_e32 v44, 0xbfb8aa3b, v36
	v_rcp_f32_e32 v38, v38
	v_exp_f32_e32 v44, v44
	v_mul_f32_e32 v45, 0xbfb8aa3b, v37
	v_exp_f32_e32 v45, v45
	v_mul_f32_e32 v35, v35, v38
	v_add_f32_e32 v38, 1.0, v44
	v_rcp_f32_e32 v38, v38
	v_add_f32_e32 v44, 1.0, v45
	v_rcp_f32_e32 v44, v44
	v_mul_f32_e32 v35, v39, v35
	v_mul_f32_e32 v36, v36, v38
	v_mul_f32_e32 v38, 0xbfb8aa3b, v30
	v_exp_f32_e32 v38, v38
	v_mul_f32_e32 v39, 0xbfb8aa3b, v31
	v_exp_f32_e32 v39, v39
	v_mul_f32_e32 v37, v37, v44
	v_add_f32_e32 v38, 1.0, v38
	v_rcp_f32_e32 v38, v38
	v_mul_f32_e32 v36, v40, v36
	v_mul_f32_e32 v37, v41, v37
	v_cvt_pk_bf16_f32 v34, v34, v35
	v_cvt_pk_bf16_f32 v35, v36, v37
	v_lshl_add_u64 v[36:37], v[42:43], 0, v[60:61]
	v_mul_f32_e32 v30, v30, v38
	global_store_dwordx2 v[36:37], v[34:35], off
	v_mul_f32_e32 v26, v26, v30
	v_add_f32_e32 v30, 1.0, v39
	v_mul_f32_e32 v34, 0xbfb8aa3b, v32
	v_rcp_f32_e32 v30, v30
	v_exp_f32_e32 v34, v34
	v_mul_f32_e32 v35, 0xbfb8aa3b, v33
	v_exp_f32_e32 v35, v35
	v_mul_f32_e32 v30, v31, v30
	v_add_f32_e32 v31, 1.0, v34
	v_rcp_f32_e32 v31, v31
	v_add_f32_e32 v34, 1.0, v35
	v_rcp_f32_e32 v34, v34
	v_mul_f32_e32 v27, v27, v30
	v_mul_f32_e32 v30, v32, v31
	v_mul_f32_e32 v28, v28, v30
	v_mul_f32_e32 v30, v33, v34
	v_mul_f32_e32 v29, v29, v30
	s_add_i32 s41, s41, s23
	v_cvt_pk_bf16_f32 v26, v26, v27
	v_cvt_pk_bf16_f32 v27, v28, v29
	v_mov_b32_e32 v29, 0
	s_cmp_ge_i32 s41, s29
	global_store_dwordx2 v[36:37], v[26:27], off offset:32
	s_cbranch_scc1 .LBB0_1201
	s_mov_b32 s12, s10
	s_cmpk_gt_i32 s41, 0xaf
	s_cbranch_scc1 .LBB0_1201
	s_cmpk_gt_i32 s41, 0x9f
	s_mov_b64 s[2:3], -1
	s_cbranch_scc0 .LBB0_1238
	s_lshl_b32 s2, s41, 2
	s_add_i32 s2, s2, 0x7ffffd80
	s_and_b32 s13, s2, 0x7ffffff8
	s_and_b32 s2, s41, 1
	s_or_b32 s28, s2, 20
	s_mov_b64 s[2:3], 0

.Lnodef_J0_4:
	ds_read_b128 v[186:189], v255 offset:12288
	ds_read_b128 v[182:185], v253 offset:8192
	ds_read_b128 v[178:181], v255 offset:8192
	ds_read_b128 v[190:193], v253 offset:12288
	s_add_i32 s2, s39, -1
	s_cmp_lt_i32 s2, s41
	s_cselect_b64 s[22:23], -1, 0
	s_cmp_ge_i32 s2, s41
	s_waitcnt lgkmcnt(7)
	v_mfma_f32_16x16x32_bf16 v[158:161], v[194:197], v[162:165], v[158:161]
	v_mfma_f32_16x16x32_bf16 v[154:157], v[198:201], v[162:165], v[154:157]
	v_mfma_f32_16x16x32_bf16 v[150:153], v[202:205], v[162:165], v[150:153]
	v_mfma_f32_16x16x32_bf16 v[146:149], v[206:209], v[162:165], v[146:149]
	ds_read_b128 v[162:165], v247
	s_waitcnt lgkmcnt(7)
	v_mfma_f32_16x16x32_bf16 v[142:145], v[194:197], v[166:169], v[142:145]
	v_mfma_f32_16x16x32_bf16 v[138:141], v[198:201], v[166:169], v[138:141]
	v_mfma_f32_16x16x32_bf16 v[134:137], v[202:205], v[166:169], v[134:137]
	v_mfma_f32_16x16x32_bf16 v[130:133], v[206:209], v[166:169], v[130:133]
	s_waitcnt vmcnt(6)
	ds_write_b128 v235, v[30:33]
	ds_write_b128 v235, v[26:29] offset:8192
.LBB0_1304:
	s_lshl_b32 s2, s49, 8
	s_mul_i32 s20, s49, 0xb0000
	s_mul_hi_i32 s21, s2, 0xb00
	s_lshl_b32 s2, s26, 6
	s_ashr_i32 s3, s2, 31
	s_lshl_b64 s[6:7], s[20:21], 1
	s_add_u32 s24, s29, s6
	s_addc_u32 s25, s30, s7
	s_lshl_b64 s[6:7], s[2:3], 1
	s_add_u32 s24, s24, s6
	s_addc_u32 s25, s25, s7
	global_load_dwordx4 v[26:29], v234, s[24:25]
	global_load_dwordx4 v[30:33], v233, s[24:25]
	s_andn2_b64 vcc, exec, s[22:23]
	ds_read_b128 v[166:169], v245
	s_waitcnt lgkmcnt(9)
	v_mfma_f32_16x16x32_bf16 v[126:129], v[194:197], v[170:173], v[126:129]
	v_mfma_f32_16x16x32_bf16 v[122:125], v[198:201], v[170:173], v[122:125]
	v_mfma_f32_16x16x32_bf16 v[118:121], v[202:205], v[170:173], v[118:121]
	v_mfma_f32_16x16x32_bf16 v[114:117], v[206:209], v[170:173], v[114:117]
	ds_read_b128 v[170:173], v247 offset:4096
	s_waitcnt lgkmcnt(9)
	v_mfma_f32_16x16x32_bf16 v[110:113], v[194:197], v[174:177], v[110:113]
	v_mfma_f32_16x16x32_bf16 v[106:109], v[198:201], v[174:177], v[106:109]
	v_mfma_f32_16x16x32_bf16 v[102:105], v[202:205], v[174:177], v[102:105]
	v_mfma_f32_16x16x32_bf16 v[82:85], v[206:209], v[174:177], v[82:85]
	ds_read_b128 v[210:213], v243
	ds_read_b128 v[214:217], v241
	ds_read_b128 v[218:221], v243 offset:4096
	ds_read_b128 v[222:225], v241 offset:4096
	ds_read_b128 v[174:177], v245 offset:4096
	s_waitcnt lgkmcnt(11)
	v_mfma_f32_16x16x32_bf16 v[98:101], v[194:197], v[178:181], v[98:101]
	v_mfma_f32_16x16x32_bf16 v[94:97], v[198:201], v[178:181], v[94:97]
	v_mfma_f32_16x16x32_bf16 v[90:93], v[202:205], v[178:181], v[90:93]
	v_mfma_f32_16x16x32_bf16 v[86:89], v[206:209], v[178:181], v[86:89]
	s_waitcnt vmcnt(6)
	ds_write_b128 v235, v[22:25] offset:16384
	ds_write_b128 v235, v[18:21] offset:24576
.LBB0_1306:
	global_load_dwordx4 v[18:21], v232, s[24:25]
	global_load_dwordx4 v[22:25], v231, s[24:25]
	s_and_b64 vcc, exec, s[2:3]
	ds_read_b128 v[178:181], v247 offset:8192
	v_mfma_f32_16x16x32_bf16 v[78:81], v[194:197], v[182:185], v[78:81]
	v_mfma_f32_16x16x32_bf16 v[74:77], v[198:201], v[182:185], v[74:77]
	v_mfma_f32_16x16x32_bf16 v[70:73], v[202:205], v[182:185], v[70:73]
	v_mfma_f32_16x16x32_bf16 v[66:69], v[206:209], v[182:185], v[66:69]
	s_waitcnt lgkmcnt(10)
	ds_read_b128 v[182:185], v245 offset:8192
	v_mfma_f32_16x16x32_bf16 v[62:65], v[194:197], v[186:189], v[62:65]
	v_mfma_f32_16x16x32_bf16 v[58:61], v[198:201], v[186:189], v[58:61]
	v_mfma_f32_16x16x32_bf16 v[54:57], v[202:205], v[186:189], v[54:57]
	v_mfma_f32_16x16x32_bf16 v[50:53], v[206:209], v[186:189], v[50:53]
	s_waitcnt vmcnt(6)
	ds_write_b128 v235, v[14:17] offset:32768
	ds_write_b128 v235, v[10:13] offset:40960
.LBB0_1308:
	s_lshl_b32 s23, s48, 8
	s_mul_i32 s22, s48, 0xb0000
	s_mul_hi_i32 s23, s23, 0xb00
	s_lshl_b64 s[24:25], s[22:23], 1
	s_add_u32 s24, s31, s24
	s_addc_u32 s25, s33, s25
	s_add_u32 s6, s24, s6
	s_addc_u32 s7, s25, s7
	global_load_dwordx4 v[10:13], v234, s[6:7]
	global_load_dwordx4 v[14:17], v233, s[6:7]
	s_and_b64 vcc, exec, s[2:3]
	ds_read_b128 v[186:189], v247 offset:12288
	v_mfma_f32_16x16x32_bf16 v[46:49], v[194:197], v[190:193], v[46:49]
	v_mfma_f32_16x16x32_bf16 v[42:45], v[198:201], v[190:193], v[42:45]
	v_mfma_f32_16x16x32_bf16 v[38:41], v[202:205], v[190:193], v[38:41]
	v_mfma_f32_16x16x32_bf16 v[34:37], v[206:209], v[190:193], v[34:37]
	s_waitcnt lgkmcnt(10)
	ds_read_b128 v[190:193], v245 offset:12288
	s_waitcnt lgkmcnt(9)
	v_mfma_f32_16x16x32_bf16 v[158:161], v[210:213], v[162:165], v[158:161]
	v_mfma_f32_16x16x32_bf16 v[154:157], v[214:217], v[162:165], v[154:157]
	v_mfma_f32_16x16x32_bf16 v[150:153], v[218:221], v[162:165], v[150:153]
	v_mfma_f32_16x16x32_bf16 v[146:149], v[222:225], v[162:165], v[146:149]
	v_mfma_f32_16x16x32_bf16 v[142:145], v[210:213], v[166:169], v[142:145]
	v_mfma_f32_16x16x32_bf16 v[138:141], v[214:217], v[166:169], v[138:141]
	v_mfma_f32_16x16x32_bf16 v[134:137], v[218:221], v[166:169], v[134:137]
	v_mfma_f32_16x16x32_bf16 v[130:133], v[222:225], v[166:169], v[130:133]
	s_waitcnt vmcnt(6)
	ds_write_b128 v235, v[6:9] offset:49152
	ds_write_b128 v235, v[2:5] offset:57344
.LBB0_1310:
	global_load_dwordx4 v[2:5], v232, s[6:7]
	global_load_dwordx4 v[6:9], v231, s[6:7]
	v_mfma_f32_16x16x32_bf16 v[126:129], v[210:213], v[170:173], v[126:129]
	v_mfma_f32_16x16x32_bf16 v[122:125], v[214:217], v[170:173], v[122:125]
	v_mfma_f32_16x16x32_bf16 v[118:121], v[218:221], v[170:173], v[118:121]
	v_mfma_f32_16x16x32_bf16 v[114:117], v[222:225], v[170:173], v[114:117]
	s_waitcnt lgkmcnt(10)
	v_mfma_f32_16x16x32_bf16 v[110:113], v[210:213], v[174:177], v[110:113]
	v_mfma_f32_16x16x32_bf16 v[106:109], v[214:217], v[174:177], v[106:109]
	v_mfma_f32_16x16x32_bf16 v[102:105], v[218:221], v[174:177], v[102:105]
	v_mfma_f32_16x16x32_bf16 v[82:85], v[222:225], v[174:177], v[82:85]
	s_add_i32 s51, s26, 1
	s_cmp_lg_u32 s51, 44
	s_cbranch_scc1 .LBB0_1314
	s_add_i32 s28, s28, s11
	s_cmp_gt_i32 s28, 31
	s_cbranch_scc1 .LBB0_1313
	s_ashr_i32 s3, s28, 31
	s_lshr_b32 s3, s3, 27
	s_add_i32 s3, s28, s3
	s_ashr_i32 s3, s3, 5
	s_mov_b32 s2, s10
	s_lshl_b32 s6, s3, 6
	s_lshl_b32 s7, s28, 1
	s_sub_i32 s6, s7, s6
	s_and_b32 s2, s2, 7
	s_and_b32 s6, s6, -8
	s_lshl_b32 s3, s3, 2
	s_and_b32 s7, s28, 3
	s_or_b32 s49, s2, s6
	s_or_b32 s48, s3, s7
	s_lshl_b32 s2, s49, 8
	s_mul_hi_i32 s21, s2, 0xb00
	s_lshl_b32 s2, s48, 8
	s_mul_i32 s20, s49, 0xb0000
	s_mul_i32 s22, s48, 0xb0000
	s_mul_hi_i32 s23, s2, 0xb00

.LBB0_1314:
	s_waitcnt lgkmcnt(0)
	s_barrier
	ds_read_b128 v[194:197], v250
	ds_read_b128 v[198:201], v248
	ds_read_b128 v[202:205], v250 offset:4096
	ds_read_b128 v[206:209], v248 offset:4096
	ds_read_b128 v[162:165], v254
	ds_read_b128 v[166:169], v252
	ds_read_b128 v[170:173], v254 offset:4096
	ds_read_b128 v[174:177], v252 offset:4096
	v_mfma_f32_16x16x32_bf16 v[98:101], v[210:213], v[178:181], v[98:101]
	v_mfma_f32_16x16x32_bf16 v[94:97], v[214:217], v[178:181], v[94:97]
	v_mfma_f32_16x16x32_bf16 v[90:93], v[218:221], v[178:181], v[90:93]
	v_mfma_f32_16x16x32_bf16 v[86:89], v[222:225], v[178:181], v[86:89]
	v_mfma_f32_16x16x32_bf16 v[78:81], v[210:213], v[182:185], v[78:81]
	v_mfma_f32_16x16x32_bf16 v[74:77], v[214:217], v[182:185], v[74:77]
	v_mfma_f32_16x16x32_bf16 v[70:73], v[218:221], v[182:185], v[70:73]
	v_mfma_f32_16x16x32_bf16 v[66:69], v[222:225], v[182:185], v[66:69]
	v_mfma_f32_16x16x32_bf16 v[62:65], v[210:213], v[186:189], v[62:65]
	v_mfma_f32_16x16x32_bf16 v[58:61], v[214:217], v[186:189], v[58:61]
	v_mfma_f32_16x16x32_bf16 v[54:57], v[218:221], v[186:189], v[54:57]
	v_mfma_f32_16x16x32_bf16 v[50:53], v[222:225], v[186:189], v[50:53]
	v_mfma_f32_16x16x32_bf16 v[46:49], v[210:213], v[190:193], v[46:49]
	v_mfma_f32_16x16x32_bf16 v[42:45], v[214:217], v[190:193], v[42:45]
	v_mfma_f32_16x16x32_bf16 v[38:41], v[218:221], v[190:193], v[38:41]
	v_mfma_f32_16x16x32_bf16 v[34:37], v[222:225], v[190:193], v[34:37]
	ds_read_b128 v[186:189], v254 offset:12288
	ds_read_b128 v[182:185], v252 offset:8192
	ds_read_b128 v[178:181], v254 offset:8192
	ds_read_b128 v[190:193], v252 offset:12288
	s_cmp_lt_i32 s39, s41
	s_cselect_b64 s[24:25], -1, 0
	s_cmp_ge_i32 s39, s41
	s_cselect_b64 s[6:7], -1, 0
	s_and_b64 vcc, exec, s[6:7]
	s_waitcnt lgkmcnt(7)
	v_mfma_f32_16x16x32_bf16 v[158:161], v[194:197], v[162:165], v[158:161]
	v_mfma_f32_16x16x32_bf16 v[154:157], v[198:201], v[162:165], v[154:157]
	v_mfma_f32_16x16x32_bf16 v[150:153], v[202:205], v[162:165], v[150:153]
	v_mfma_f32_16x16x32_bf16 v[146:149], v[206:209], v[162:165], v[146:149]
	ds_read_b128 v[162:165], v246
	s_waitcnt lgkmcnt(7)
	v_mfma_f32_16x16x32_bf16 v[142:145], v[194:197], v[166:169], v[142:145]
	v_mfma_f32_16x16x32_bf16 v[138:141], v[198:201], v[166:169], v[138:141]
	v_mfma_f32_16x16x32_bf16 v[134:137], v[202:205], v[166:169], v[134:137]
	v_mfma_f32_16x16x32_bf16 v[130:133], v[206:209], v[166:169], v[130:133]
	s_waitcnt vmcnt(6)
	ds_write_b128 v236, v[26:29]
	ds_write_b128 v236, v[30:33] offset:8192
.LBB0_1316:
	s_lshl_b32 s2, s51, 6
	s_ashr_i32 s3, s2, 31
	s_lshl_b64 s[20:21], s[20:21], 1
	s_add_u32 s26, s29, s20
	s_addc_u32 s27, s30, s21
	s_lshl_b64 s[20:21], s[2:3], 1
	s_add_u32 s26, s26, s20
	s_addc_u32 s27, s27, s21
	global_load_dwordx4 v[30:33], v234, s[26:27]
	global_load_dwordx4 v[26:29], v233, s[26:27]
	s_andn2_b64 vcc, exec, s[24:25]
	ds_read_b128 v[166:169], v244
	s_waitcnt lgkmcnt(9)
	v_mfma_f32_16x16x32_bf16 v[126:129], v[194:197], v[170:173], v[126:129]
	v_mfma_f32_16x16x32_bf16 v[122:125], v[198:201], v[170:173], v[122:125]
	v_mfma_f32_16x16x32_bf16 v[118:121], v[202:205], v[170:173], v[118:121]
	v_mfma_f32_16x16x32_bf16 v[114:117], v[206:209], v[170:173], v[114:117]
	ds_read_b128 v[170:173], v246 offset:4096
	s_waitcnt lgkmcnt(9)
	v_mfma_f32_16x16x32_bf16 v[110:113], v[194:197], v[174:177], v[110:113]
	v_mfma_f32_16x16x32_bf16 v[106:109], v[198:201], v[174:177], v[106:109]
	v_mfma_f32_16x16x32_bf16 v[102:105], v[202:205], v[174:177], v[102:105]
	v_mfma_f32_16x16x32_bf16 v[82:85], v[206:209], v[174:177], v[82:85]
	ds_read_b128 v[210:213], v242
	ds_read_b128 v[214:217], v237
	ds_read_b128 v[218:221], v242 offset:4096
	ds_read_b128 v[222:225], v237 offset:4096
	ds_read_b128 v[174:177], v244 offset:4096
	s_waitcnt lgkmcnt(11)
	v_mfma_f32_16x16x32_bf16 v[98:101], v[194:197], v[178:181], v[98:101]
	v_mfma_f32_16x16x32_bf16 v[94:97], v[198:201], v[178:181], v[94:97]
	v_mfma_f32_16x16x32_bf16 v[90:93], v[202:205], v[178:181], v[90:93]
	v_mfma_f32_16x16x32_bf16 v[86:89], v[206:209], v[178:181], v[86:89]
	s_waitcnt vmcnt(6)
	ds_write_b128 v236, v[18:21] offset:16384
	ds_write_b128 v236, v[22:25] offset:24576
.LBB0_1318:
	global_load_dwordx4 v[22:25], v232, s[26:27]
	global_load_dwordx4 v[18:21], v231, s[26:27]
	s_and_b64 vcc, exec, s[2:3]
	ds_read_b128 v[178:181], v246 offset:8192
	v_mfma_f32_16x16x32_bf16 v[78:81], v[194:197], v[182:185], v[78:81]
	v_mfma_f32_16x16x32_bf16 v[74:77], v[198:201], v[182:185], v[74:77]
	v_mfma_f32_16x16x32_bf16 v[70:73], v[202:205], v[182:185], v[70:73]
	v_mfma_f32_16x16x32_bf16 v[66:69], v[206:209], v[182:185], v[66:69]
	s_waitcnt lgkmcnt(10)
	ds_read_b128 v[182:185], v244 offset:8192
	v_mfma_f32_16x16x32_bf16 v[62:65], v[194:197], v[186:189], v[62:65]
	v_mfma_f32_16x16x32_bf16 v[58:61], v[198:201], v[186:189], v[58:61]
	v_mfma_f32_16x16x32_bf16 v[54:57], v[202:205], v[186:189], v[54:57]
	v_mfma_f32_16x16x32_bf16 v[50:53], v[206:209], v[186:189], v[50:53]
	s_waitcnt vmcnt(6)
	ds_write_b128 v236, v[10:13] offset:32768
	ds_write_b128 v236, v[14:17] offset:40960
.LBB0_1320:
	s_lshl_b64 s[22:23], s[22:23], 1
	s_add_u32 s22, s31, s22
	s_addc_u32 s23, s33, s23
	s_add_u32 s20, s22, s20
	s_addc_u32 s21, s23, s21
	global_load_dwordx4 v[14:17], v234, s[20:21]
	global_load_dwordx4 v[10:13], v233, s[20:21]
	s_and_b64 vcc, exec, s[2:3]
	ds_read_b128 v[186:189], v246 offset:12288
	v_mfma_f32_16x16x32_bf16 v[46:49], v[194:197], v[190:193], v[46:49]
	v_mfma_f32_16x16x32_bf16 v[42:45], v[198:201], v[190:193], v[42:45]
	v_mfma_f32_16x16x32_bf16 v[38:41], v[202:205], v[190:193], v[38:41]
	v_mfma_f32_16x16x32_bf16 v[34:37], v[206:209], v[190:193], v[34:37]
	s_waitcnt lgkmcnt(10)
	ds_read_b128 v[190:193], v244 offset:12288
	s_waitcnt lgkmcnt(9)
	v_mfma_f32_16x16x32_bf16 v[158:161], v[210:213], v[162:165], v[158:161]
	v_mfma_f32_16x16x32_bf16 v[154:157], v[214:217], v[162:165], v[154:157]
	v_mfma_f32_16x16x32_bf16 v[150:153], v[218:221], v[162:165], v[150:153]
	v_mfma_f32_16x16x32_bf16 v[146:149], v[222:225], v[162:165], v[146:149]
	v_mfma_f32_16x16x32_bf16 v[142:145], v[210:213], v[166:169], v[142:145]
	v_mfma_f32_16x16x32_bf16 v[138:141], v[214:217], v[166:169], v[138:141]
	v_mfma_f32_16x16x32_bf16 v[134:137], v[218:221], v[166:169], v[134:137]
	v_mfma_f32_16x16x32_bf16 v[130:133], v[222:225], v[166:169], v[130:133]
	s_waitcnt vmcnt(6)
	ds_write_b128 v236, v[2:5] offset:49152
	ds_write_b128 v236, v[6:9] offset:57344
.LBB0_1322:
	global_load_dwordx4 v[6:9], v232, s[20:21]
	global_load_dwordx4 v[2:5], v231, s[20:21]
	v_mfma_f32_16x16x32_bf16 v[126:129], v[210:213], v[170:173], v[126:129]
	v_mfma_f32_16x16x32_bf16 v[122:125], v[214:217], v[170:173], v[122:125]
	v_mfma_f32_16x16x32_bf16 v[118:121], v[218:221], v[170:173], v[118:121]
	v_mfma_f32_16x16x32_bf16 v[114:117], v[222:225], v[170:173], v[114:117]
	s_waitcnt lgkmcnt(10)
	v_mfma_f32_16x16x32_bf16 v[110:113], v[210:213], v[174:177], v[110:113]
	v_mfma_f32_16x16x32_bf16 v[106:109], v[214:217], v[174:177], v[106:109]
	v_mfma_f32_16x16x32_bf16 v[102:105], v[218:221], v[174:177], v[102:105]
	v_mfma_f32_16x16x32_bf16 v[82:85], v[222:225], v[174:177], v[82:85]
	s_add_i32 s26, s51, 1
	s_cmp_lg_u32 s26, 44
	s_cbranch_scc1 .LBB0_1326
	s_add_i32 s28, s28, s11
	s_cmp_gt_i32 s28, 31
	s_cbranch_scc1 .LBB0_1325
	s_ashr_i32 s3, s28, 31
	s_lshr_b32 s3, s3, 27
	s_add_i32 s3, s28, s3
	s_ashr_i32 s3, s3, 5
	s_mov_b32 s2, s10
	s_lshl_b32 s20, s3, 6
	s_lshl_b32 s21, s28, 1
	s_sub_i32 s20, s21, s20
	s_and_b32 s2, s2, 7
	s_and_b32 s20, s20, -8
	s_lshl_b32 s3, s3, 2
	s_and_b32 s21, s28, 3
	s_or_b32 s48, s3, s21
	s_or_b32 s49, s2, s20

.LBB0_1326:
	s_add_i32 s50, s50, 2
	s_cmp_lg_u32 s50, 44
	s_waitcnt lgkmcnt(0)
	s_mov_b32 s98, 1
	s_cbranch_scc1 .LBB0_1301
	s_mov_b32 s98, 0
	v_mfma_f32_16x16x32_bf16 v[98:101], v[210:213], v[178:181], v[98:101]
	v_mfma_f32_16x16x32_bf16 v[94:97], v[214:217], v[178:181], v[94:97]
	v_mfma_f32_16x16x32_bf16 v[90:93], v[218:221], v[178:181], v[90:93]
	v_mfma_f32_16x16x32_bf16 v[86:89], v[222:225], v[178:181], v[86:89]
	v_mfma_f32_16x16x32_bf16 v[78:81], v[210:213], v[182:185], v[78:81]
	v_mfma_f32_16x16x32_bf16 v[74:77], v[214:217], v[182:185], v[74:77]
	v_mfma_f32_16x16x32_bf16 v[70:73], v[218:221], v[182:185], v[70:73]
	v_mfma_f32_16x16x32_bf16 v[66:69], v[222:225], v[182:185], v[66:69]
	v_mfma_f32_16x16x32_bf16 v[62:65], v[210:213], v[186:189], v[62:65]
	v_mfma_f32_16x16x32_bf16 v[58:61], v[214:217], v[186:189], v[58:61]
	v_mfma_f32_16x16x32_bf16 v[54:57], v[218:221], v[186:189], v[54:57]
	v_mfma_f32_16x16x32_bf16 v[50:53], v[222:225], v[186:189], v[50:53]
	v_mfma_f32_16x16x32_bf16 v[46:49], v[210:213], v[190:193], v[46:49]
	v_mfma_f32_16x16x32_bf16 v[42:45], v[214:217], v[190:193], v[42:45]
	v_mfma_f32_16x16x32_bf16 v[38:41], v[218:221], v[190:193], v[38:41]
	v_mfma_f32_16x16x32_bf16 v[34:37], v[222:225], v[190:193], v[34:37]
	s_nop 7
	s_nop 7
	v_mov_b32_e32 v172, v0
	s_nop 0
	v_ashrrev_i32_e32 v162, 1, v172
	v_and_b32_e32 v162, 0xffffff80, v162
	v_lshl_add_u32 v162, s36, 8, v162
	v_and_or_b32 v164, v172, 15, v162
	v_add_u32_e32 v162, 0xffffe000, v162
	v_ashrrev_i32_e32 v162, 11, v162
	v_mad_i32_i24 v162, v162, s45, s45
	v_cmp_lt_i32_e32 vcc, s46, v164
	v_ashrrev_i32_e32 v163, 31, v162
	s_and_saveexec_b64 s[2:3], vcc
	s_xor_b64 s[2:3], exec, s[2:3]
	v_add_u32_e32 v238, 0xffffe000, v164
	v_lshlrev_b64 v[166:167], 12, v[238:239]
	v_mov_b32_e32 v165, v239
	v_lshl_add_u64 v[168:169], s[12:13], 0, v[166:167]
	v_lshlrev_b64 v[170:171], 12, v[164:165]
	v_mov_b64_e32 v[166:167], v[162:163]
	s_andn2_saveexec_b64 s[2:3], s[2:3]
	v_ashrrev_i32_e32 v165, 31, v164
	v_lshlrev_b64 v[170:171], 12, v[164:165]
	v_lshl_add_u64 v[168:169], s[4:5], 0, v[170:171]
	v_mov_b64_e32 v[166:167], 0
	s_or_b64 exec, exec, s[2:3]
	v_and_b32_e32 v165, 0xc0, v172
	v_lshrrev_b32_e32 v172, 2, v172
	s_lshl_b32 s2, s34, 8
	v_and_b32_e32 v172, 12, v172
	v_or3_b32 v172, v165, s2, v172
	v_ashrrev_i32_e32 v173, 31, v172
	v_lshl_add_u64 v[176:177], v[166:167], 2, s[14:15]
	v_lshlrev_b64 v[166:167], 2, v[172:173]
	v_lshl_add_u64 v[180:181], v[168:169], 0, v[166:167]
	v_lshl_add_u64 v[182:183], v[176:177], 0, v[166:167]
	global_load_dwordx4 v[172:175], v[180:181], off
	global_load_dwordx4 v[176:179], v[182:183], off
	v_lshl_add_u64 v[168:169], s[4:5], 0, v[170:171]
	v_lshl_add_u64 v[184:185], v[168:169], 0, v[166:167]
	s_waitcnt vmcnt(0)
	v_pk_fma_f32 v[160:161], v[160:161], v[178:179], v[174:175]
	v_pk_fma_f32 v[158:159], v[158:159], v[176:177], v[172:173]
	global_store_dwordx4 v[184:185], v[158:161], off
	global_load_dwordx4 v[158:161], v[180:181], off offset:64
	s_nop 0
	global_load_dwordx4 v[168:171], v[182:183], off offset:64
	s_waitcnt vmcnt(0)
	v_pk_fma_f32 v[156:157], v[156:157], v[170:171], v[160:161]
	v_pk_fma_f32 v[154:155], v[154:155], v[168:169], v[158:159]
	global_store_dwordx4 v[184:185], v[154:157], off offset:64
	global_load_dwordx4 v[154:157], v[180:181], off offset:128
	s_nop 0
	global_load_dwordx4 v[158:161], v[182:183], off offset:128
	s_waitcnt vmcnt(0)
	v_pk_fma_f32 v[152:153], v[152:153], v[160:161], v[156:157]
	v_pk_fma_f32 v[150:151], v[150:151], v[158:159], v[154:155]
	global_store_dwordx4 v[184:185], v[150:153], off offset:128
	global_load_dwordx4 v[152:155], v[180:181], off offset:192
	s_nop 0
	global_load_dwordx4 v[156:159], v[182:183], off offset:192
	v_or_b32_e32 v150, 16, v164
	v_cmp_lt_i32_e32 vcc, s46, v150
	s_waitcnt vmcnt(0)
	v_pk_fma_f32 v[148:149], v[148:149], v[158:159], v[154:155]
	v_pk_fma_f32 v[146:147], v[146:147], v[156:157], v[152:153]
	global_store_dwordx4 v[184:185], v[146:149], off offset:192
	s_and_saveexec_b64 s[2:3], vcc
	s_xor_b64 s[2:3], exec, s[2:3]
	v_add_u32_e32 v238, 0xffffe010, v164
	v_lshlrev_b64 v[146:147], 12, v[238:239]
	v_mov_b32_e32 v151, v239
	v_lshl_add_u64 v[146:147], s[12:13], 0, v[146:147]
	v_lshlrev_b64 v[148:149], 12, v[150:151]
	v_mov_b64_e32 v[152:153], v[162:163]
	s_andn2_saveexec_b64 s[2:3], s[2:3]
	v_ashrrev_i32_e32 v151, 31, v150
	v_lshlrev_b64 v[148:149], 12, v[150:151]
	v_lshl_add_u64 v[146:147], s[4:5], 0, v[148:149]
	v_mov_b64_e32 v[152:153], 0
	s_or_b64 exec, exec, s[2:3]
	v_lshl_add_u64 v[154:155], v[152:153], 2, s[14:15]
	v_lshl_add_u64 v[158:159], v[146:147], 0, v[166:167]
	v_lshl_add_u64 v[160:161], v[154:155], 0, v[166:167]
	global_load_dwordx4 v[150:153], v[158:159], off
	global_load_dwordx4 v[154:157], v[160:161], off
	v_lshl_add_u64 v[146:147], s[4:5], 0, v[148:149]
	v_lshl_add_u64 v[168:169], v[146:147], 0, v[166:167]
	s_waitcnt vmcnt(0)
	v_pk_fma_f32 v[144:145], v[144:145], v[156:157], v[152:153]
	v_pk_fma_f32 v[142:143], v[142:143], v[154:155], v[150:151]
	global_store_dwordx4 v[168:169], v[142:145], off
	global_load_dwordx4 v[142:145], v[158:159], off offset:64
	s_nop 0
	global_load_dwordx4 v[146:149], v[160:161], off offset:64
	s_waitcnt vmcnt(0)
	v_pk_fma_f32 v[140:141], v[140:141], v[148:149], v[144:145]
	v_pk_fma_f32 v[138:139], v[138:139], v[146:147], v[142:143]
	global_store_dwordx4 v[168:169], v[138:141], off offset:64
	global_load_dwordx4 v[138:141], v[158:159], off offset:128
	s_nop 0
	global_load_dwordx4 v[142:145], v[160:161], off offset:128
	s_waitcnt vmcnt(0)
	v_pk_fma_f32 v[136:137], v[136:137], v[144:145], v[140:141]
	v_pk_fma_f32 v[134:135], v[134:135], v[142:143], v[138:139]
	global_store_dwordx4 v[168:169], v[134:137], off offset:128
	global_load_dwordx4 v[136:139], v[158:159], off offset:192
	s_nop 0
	global_load_dwordx4 v[140:143], v[160:161], off offset:192
	v_or_b32_e32 v134, 32, v164
	v_cmp_lt_i32_e32 vcc, s46, v134
	s_waitcnt vmcnt(0)
	v_pk_fma_f32 v[132:133], v[132:133], v[142:143], v[138:139]
	v_pk_fma_f32 v[130:131], v[130:131], v[140:141], v[136:137]
	global_store_dwordx4 v[168:169], v[130:133], off offset:192
	s_and_saveexec_b64 s[2:3], vcc
	s_xor_b64 s[2:3], exec, s[2:3]
	v_add_u32_e32 v238, 0xffffe020, v164
	v_lshlrev_b64 v[130:131], 12, v[238:239]
	v_mov_b32_e32 v135, v239
	v_lshl_add_u64 v[130:131], s[12:13], 0, v[130:131]
	v_lshlrev_b64 v[132:133], 12, v[134:135]
	v_mov_b64_e32 v[136:137], v[162:163]
	s_andn2_saveexec_b64 s[2:3], s[2:3]
	v_ashrrev_i32_e32 v135, 31, v134
	v_lshlrev_b64 v[132:133], 12, v[134:135]
	v_lshl_add_u64 v[130:131], s[4:5], 0, v[132:133]
	v_mov_b64_e32 v[136:137], 0
	s_or_b64 exec, exec, s[2:3]
	v_lshl_add_u64 v[138:139], v[136:137], 2, s[14:15]
	v_lshl_add_u64 v[142:143], v[130:131], 0, v[166:167]
	v_lshl_add_u64 v[144:145], v[138:139], 0, v[166:167]
	global_load_dwordx4 v[134:137], v[142:143], off
	global_load_dwordx4 v[138:141], v[144:145], off
	v_lshl_add_u64 v[130:131], s[4:5], 0, v[132:133]
	v_lshl_add_u64 v[146:147], v[130:131], 0, v[166:167]
	s_waitcnt vmcnt(0)
	v_pk_fma_f32 v[128:129], v[128:129], v[140:141], v[136:137]
	v_pk_fma_f32 v[126:127], v[126:127], v[138:139], v[134:135]
	global_store_dwordx4 v[146:147], v[126:129], off
	global_load_dwordx4 v[126:129], v[142:143], off offset:64
	s_nop 0
	global_load_dwordx4 v[130:133], v[144:145], off offset:64
	s_waitcnt vmcnt(0)
	v_pk_fma_f32 v[124:125], v[124:125], v[132:133], v[128:129]
	v_pk_fma_f32 v[122:123], v[122:123], v[130:131], v[126:127]
	global_store_dwordx4 v[146:147], v[122:125], off offset:64
	global_load_dwordx4 v[122:125], v[142:143], off offset:128
	s_nop 0
	global_load_dwordx4 v[126:129], v[144:145], off offset:128
	s_waitcnt vmcnt(0)
	v_pk_fma_f32 v[120:121], v[120:121], v[128:129], v[124:125]
	v_pk_fma_f32 v[118:119], v[118:119], v[126:127], v[122:123]
	global_store_dwordx4 v[146:147], v[118:121], off offset:128
	global_load_dwordx4 v[120:123], v[142:143], off offset:192
	s_nop 0
	global_load_dwordx4 v[124:127], v[144:145], off offset:192
	v_or_b32_e32 v118, 48, v164
	v_cmp_lt_i32_e32 vcc, s46, v118
	s_waitcnt vmcnt(0)
	v_pk_fma_f32 v[116:117], v[116:117], v[126:127], v[122:123]
	v_pk_fma_f32 v[114:115], v[114:115], v[124:125], v[120:121]
	global_store_dwordx4 v[146:147], v[114:117], off offset:192
	s_and_saveexec_b64 s[2:3], vcc
	s_xor_b64 s[2:3], exec, s[2:3]
	v_add_u32_e32 v238, 0xffffe030, v164
	v_lshlrev_b64 v[114:115], 12, v[238:239]
	v_mov_b32_e32 v119, v239
	v_lshl_add_u64 v[114:115], s[12:13], 0, v[114:115]
	v_lshlrev_b64 v[116:117], 12, v[118:119]
	v_mov_b64_e32 v[120:121], v[162:163]
	s_andn2_saveexec_b64 s[2:3], s[2:3]
	v_ashrrev_i32_e32 v119, 31, v118
	v_lshlrev_b64 v[116:117], 12, v[118:119]
	v_lshl_add_u64 v[114:115], s[4:5], 0, v[116:117]
	v_mov_b64_e32 v[120:121], 0
	s_or_b64 exec, exec, s[2:3]
	v_lshl_add_u64 v[122:123], v[120:121], 2, s[14:15]
	v_lshl_add_u64 v[126:127], v[114:115], 0, v[166:167]
	v_lshl_add_u64 v[128:129], v[122:123], 0, v[166:167]
	global_load_dwordx4 v[118:121], v[126:127], off
	global_load_dwordx4 v[122:125], v[128:129], off
	v_lshl_add_u64 v[114:115], s[4:5], 0, v[116:117]
	v_lshl_add_u64 v[130:131], v[114:115], 0, v[166:167]
	s_waitcnt vmcnt(0)
	v_pk_fma_f32 v[112:113], v[112:113], v[124:125], v[120:121]
	v_pk_fma_f32 v[110:111], v[110:111], v[122:123], v[118:119]
	global_store_dwordx4 v[130:131], v[110:113], off
	global_load_dwordx4 v[110:113], v[126:127], off offset:64
	s_nop 0
	global_load_dwordx4 v[114:117], v[128:129], off offset:64
	s_waitcnt vmcnt(0)
	v_pk_fma_f32 v[108:109], v[108:109], v[116:117], v[112:113]
	v_pk_fma_f32 v[106:107], v[106:107], v[114:115], v[110:111]
	global_store_dwordx4 v[130:131], v[106:109], off offset:64
	global_load_dwordx4 v[106:109], v[126:127], off offset:128
	s_nop 0
	global_load_dwordx4 v[110:113], v[128:129], off offset:128
	s_waitcnt vmcnt(0)
	v_pk_fma_f32 v[104:105], v[104:105], v[112:113], v[108:109]
	v_pk_fma_f32 v[102:103], v[102:103], v[110:111], v[106:107]
	global_store_dwordx4 v[130:131], v[102:105], off offset:128
	global_load_dwordx4 v[104:107], v[126:127], off offset:192
	s_nop 0
	global_load_dwordx4 v[108:111], v[128:129], off offset:192
	v_or_b32_e32 v102, 64, v164
	v_cmp_lt_i32_e32 vcc, s46, v102
	s_waitcnt vmcnt(0)
	v_pk_fma_f32 v[84:85], v[84:85], v[110:111], v[106:107]
	v_pk_fma_f32 v[82:83], v[82:83], v[108:109], v[104:105]
	global_store_dwordx4 v[130:131], v[82:85], off offset:192
	s_and_saveexec_b64 s[2:3], vcc
	s_xor_b64 s[2:3], exec, s[2:3]
	v_add_u32_e32 v238, 0xffffe040, v164
	v_lshlrev_b64 v[82:83], 12, v[238:239]
	v_mov_b32_e32 v103, v239
	v_lshl_add_u64 v[82:83], s[12:13], 0, v[82:83]
	v_lshlrev_b64 v[84:85], 12, v[102:103]
	v_mov_b64_e32 v[104:105], v[162:163]
	s_andn2_saveexec_b64 s[2:3], s[2:3]
	v_ashrrev_i32_e32 v103, 31, v102
	v_lshlrev_b64 v[84:85], 12, v[102:103]
	v_lshl_add_u64 v[82:83], s[4:5], 0, v[84:85]
	v_mov_b64_e32 v[104:105], 0
	s_or_b64 exec, exec, s[2:3]
	v_lshl_add_u64 v[106:107], v[104:105], 2, s[14:15]
	v_lshl_add_u64 v[110:111], v[82:83], 0, v[166:167]
	v_lshl_add_u64 v[112:113], v[106:107], 0, v[166:167]
	global_load_dwordx4 v[102:105], v[110:111], off
	global_load_dwordx4 v[106:109], v[112:113], off
	v_lshl_add_u64 v[82:83], s[4:5], 0, v[84:85]
	v_lshl_add_u64 v[114:115], v[82:83], 0, v[166:167]
	s_waitcnt vmcnt(0)
	v_pk_fma_f32 v[84:85], v[100:101], v[108:109], v[104:105]
	v_pk_fma_f32 v[82:83], v[98:99], v[106:107], v[102:103]
	global_store_dwordx4 v[114:115], v[82:85], off
	global_load_dwordx4 v[82:85], v[110:111], off offset:64
	s_nop 0
	global_load_dwordx4 v[98:101], v[112:113], off offset:64
	s_waitcnt vmcnt(0)
	v_pk_fma_f32 v[84:85], v[96:97], v[100:101], v[84:85]
	v_pk_fma_f32 v[82:83], v[94:95], v[98:99], v[82:83]
	global_store_dwordx4 v[114:115], v[82:85], off offset:64
	global_load_dwordx4 v[82:85], v[110:111], off offset:128
	s_nop 0
	global_load_dwordx4 v[94:97], v[112:113], off offset:128
	s_waitcnt vmcnt(0)
	v_pk_fma_f32 v[84:85], v[92:93], v[96:97], v[84:85]
	v_pk_fma_f32 v[82:83], v[90:91], v[94:95], v[82:83]
	global_store_dwordx4 v[114:115], v[82:85], off offset:128
	global_load_dwordx4 v[90:93], v[110:111], off offset:192
	global_load_dwordx4 v[94:97], v[112:113], off offset:192
	v_or_b32_e32 v84, 0x50, v164
	v_cmp_lt_i32_e32 vcc, s46, v84
	s_waitcnt vmcnt(0)
	v_pk_fma_f32 v[88:89], v[88:89], v[96:97], v[92:93]
	v_pk_fma_f32 v[86:87], v[86:87], v[94:95], v[90:91]
	global_store_dwordx4 v[114:115], v[86:89], off offset:192
	s_and_saveexec_b64 s[2:3], vcc
	s_xor_b64 s[2:3], exec, s[2:3]
	v_add_u32_e32 v238, 0xffffe050, v164
	v_lshlrev_b64 v[82:83], 12, v[238:239]
	v_mov_b32_e32 v85, v239
	v_lshl_add_u64 v[82:83], s[12:13], 0, v[82:83]
	v_lshlrev_b64 v[86:87], 12, v[84:85]
	v_mov_b64_e32 v[88:89], v[162:163]
	s_andn2_saveexec_b64 s[2:3], s[2:3]
	v_ashrrev_i32_e32 v85, 31, v84
	v_lshlrev_b64 v[86:87], 12, v[84:85]
	v_lshl_add_u64 v[82:83], s[4:5], 0, v[86:87]
	v_mov_b64_e32 v[88:89], 0
	s_or_b64 exec, exec, s[2:3]
	v_lshl_add_u64 v[88:89], v[88:89], 2, s[14:15]
	v_lshl_add_u64 v[92:93], v[82:83], 0, v[166:167]
	v_lshl_add_u64 v[94:95], v[88:89], 0, v[166:167]
	global_load_dwordx4 v[82:85], v[92:93], off
	global_load_dwordx4 v[88:91], v[94:95], off
	v_lshl_add_u64 v[86:87], s[4:5], 0, v[86:87]
	v_lshl_add_u64 v[86:87], v[86:87], 0, v[166:167]
	s_waitcnt vmcnt(0)
	v_pk_fma_f32 v[80:81], v[80:81], v[90:91], v[84:85]
	v_pk_fma_f32 v[78:79], v[78:79], v[88:89], v[82:83]
	global_store_dwordx4 v[86:87], v[78:81], off
	global_load_dwordx4 v[78:81], v[92:93], off offset:64
	s_nop 0
	global_load_dwordx4 v[82:85], v[94:95], off offset:64
	s_waitcnt vmcnt(0)
	v_pk_fma_f32 v[76:77], v[76:77], v[84:85], v[80:81]
	v_pk_fma_f32 v[74:75], v[74:75], v[82:83], v[78:79]
	global_store_dwordx4 v[86:87], v[74:77], off offset:64
	global_load_dwordx4 v[74:77], v[92:93], off offset:128
	s_nop 0
	global_load_dwordx4 v[78:81], v[94:95], off offset:128
	s_waitcnt vmcnt(0)
	v_pk_fma_f32 v[72:73], v[72:73], v[80:81], v[76:77]
	v_pk_fma_f32 v[70:71], v[70:71], v[78:79], v[74:75]
	global_store_dwordx4 v[86:87], v[70:73], off offset:128
	global_load_dwordx4 v[72:75], v[92:93], off offset:192
	s_nop 0
	global_load_dwordx4 v[76:79], v[94:95], off offset:192
	v_or_b32_e32 v70, 0x60, v164
	v_cmp_lt_i32_e32 vcc, s46, v70
	s_waitcnt vmcnt(0)
	v_pk_fma_f32 v[68:69], v[68:69], v[78:79], v[74:75]
	v_pk_fma_f32 v[66:67], v[66:67], v[76:77], v[72:73]
	global_store_dwordx4 v[86:87], v[66:69], off offset:192
	s_and_saveexec_b64 s[2:3], vcc
	s_xor_b64 s[2:3], exec, s[2:3]
	v_add_u32_e32 v238, 0xffffe060, v164
	v_lshlrev_b64 v[66:67], 12, v[238:239]
	v_mov_b32_e32 v71, v239
	v_lshl_add_u64 v[66:67], s[12:13], 0, v[66:67]
	v_lshlrev_b64 v[68:69], 12, v[70:71]
	v_mov_b64_e32 v[72:73], v[162:163]
	s_andn2_saveexec_b64 s[2:3], s[2:3]
	v_ashrrev_i32_e32 v71, 31, v70
	v_lshlrev_b64 v[68:69], 12, v[70:71]
	v_lshl_add_u64 v[66:67], s[4:5], 0, v[68:69]
	v_mov_b64_e32 v[72:73], 0
	s_or_b64 exec, exec, s[2:3]
	v_lshl_add_u64 v[74:75], v[72:73], 2, s[14:15]
	v_lshl_add_u64 v[78:79], v[66:67], 0, v[166:167]
	v_lshl_add_u64 v[80:81], v[74:75], 0, v[166:167]
	global_load_dwordx4 v[70:73], v[78:79], off
	global_load_dwordx4 v[74:77], v[80:81], off
	v_lshl_add_u64 v[66:67], s[4:5], 0, v[68:69]
	v_lshl_add_u64 v[82:83], v[66:67], 0, v[166:167]
	s_waitcnt vmcnt(0)
	v_pk_fma_f32 v[64:65], v[64:65], v[76:77], v[72:73]
	v_pk_fma_f32 v[62:63], v[62:63], v[74:75], v[70:71]
	global_store_dwordx4 v[82:83], v[62:65], off
	global_load_dwordx4 v[62:65], v[78:79], off offset:64
	s_nop 0
	global_load_dwordx4 v[66:69], v[80:81], off offset:64
	s_waitcnt vmcnt(0)
	v_pk_fma_f32 v[60:61], v[60:61], v[68:69], v[64:65]
	v_pk_fma_f32 v[58:59], v[58:59], v[66:67], v[62:63]
	global_store_dwordx4 v[82:83], v[58:61], off offset:64
	global_load_dwordx4 v[58:61], v[78:79], off offset:128
	s_nop 0
	global_load_dwordx4 v[62:65], v[80:81], off offset:128
	s_waitcnt vmcnt(0)
	v_pk_fma_f32 v[56:57], v[56:57], v[64:65], v[60:61]
	v_pk_fma_f32 v[54:55], v[54:55], v[62:63], v[58:59]
	global_store_dwordx4 v[82:83], v[54:57], off offset:128
	global_load_dwordx4 v[56:59], v[78:79], off offset:192
	s_nop 0
	global_load_dwordx4 v[60:63], v[80:81], off offset:192
	v_or_b32_e32 v54, 0x70, v164
	v_cmp_lt_i32_e32 vcc, s46, v54
	s_waitcnt vmcnt(0)
	v_pk_fma_f32 v[52:53], v[52:53], v[62:63], v[58:59]
	v_pk_fma_f32 v[50:51], v[50:51], v[60:61], v[56:57]
	global_store_dwordx4 v[82:83], v[50:53], off offset:192
	s_and_saveexec_b64 s[2:3], vcc
	s_xor_b64 s[2:3], exec, s[2:3]
	v_add_u32_e32 v238, 0xffffe070, v164
	v_lshlrev_b64 v[50:51], 12, v[238:239]
	v_mov_b32_e32 v55, v239
	v_lshl_add_u64 v[50:51], s[12:13], 0, v[50:51]
	v_lshlrev_b64 v[52:53], 12, v[54:55]
	s_andn2_saveexec_b64 s[2:3], s[2:3]
	v_ashrrev_i32_e32 v55, 31, v54
	v_lshlrev_b64 v[52:53], 12, v[54:55]
	v_lshl_add_u64 v[50:51], s[4:5], 0, v[52:53]
	v_mov_b64_e32 v[162:163], 0
	s_or_b64 exec, exec, s[2:3]
	v_lshl_add_u64 v[58:59], v[162:163], 2, s[14:15]
	v_lshl_add_u64 v[62:63], v[50:51], 0, v[166:167]
	v_lshl_add_u64 v[64:65], v[58:59], 0, v[166:167]
	global_load_dwordx4 v[54:57], v[62:63], off
	global_load_dwordx4 v[58:61], v[64:65], off
	v_lshl_add_u64 v[50:51], s[4:5], 0, v[52:53]
	v_lshl_add_u64 v[66:67], v[50:51], 0, v[166:167]
	s_add_i32 s47, s47, s11
	s_cmp_gt_i32 s47, 31
	s_waitcnt vmcnt(0)
	v_pk_fma_f32 v[48:49], v[48:49], v[60:61], v[56:57]
	v_pk_fma_f32 v[46:47], v[46:47], v[58:59], v[54:55]
	global_store_dwordx4 v[66:67], v[46:49], off
	global_load_dwordx4 v[46:49], v[62:63], off offset:64
	s_nop 0
	global_load_dwordx4 v[50:53], v[64:65], off offset:64
	s_waitcnt vmcnt(0)
	v_pk_fma_f32 v[44:45], v[44:45], v[52:53], v[48:49]
	v_pk_fma_f32 v[42:43], v[42:43], v[50:51], v[46:47]
	global_store_dwordx4 v[66:67], v[42:45], off offset:64
	global_load_dwordx4 v[42:45], v[62:63], off offset:128
	s_nop 0
	global_load_dwordx4 v[46:49], v[64:65], off offset:128
	s_waitcnt vmcnt(0)
	v_pk_fma_f32 v[40:41], v[40:41], v[48:49], v[44:45]
	v_pk_fma_f32 v[38:39], v[38:39], v[46:47], v[42:43]
	global_store_dwordx4 v[66:67], v[38:41], off offset:128
	global_load_dwordx4 v[38:41], v[62:63], off offset:192
	s_nop 0
	global_load_dwordx4 v[42:45], v[64:65], off offset:192
	s_waitcnt vmcnt(0)
	v_pk_fma_f32 v[40:41], v[36:37], v[44:45], v[40:41]
	v_pk_fma_f32 v[38:39], v[34:35], v[42:43], v[38:39]
	v_mov_b32_e32 v37, 0
	global_store_dwordx4 v[66:67], v[38:41], off offset:192
	s_cbranch_scc1 .LBB0_1300
	s_ashr_i32 s3, s47, 31
	s_lshr_b32 s3, s3, 27
	s_add_i32 s3, s47, s3
	s_ashr_i32 s3, s3, 5
	s_mov_b32 s2, s10
	s_lshl_b32 s20, s3, 6
	s_lshl_b32 s21, s47, 1
	s_sub_i32 s20, s21, s20
	s_and_b32 s2, s2, 7
	s_and_b32 s20, s20, -8
	s_lshl_b32 s3, s3, 2
	s_and_b32 s21, s47, 3
	s_or_b32 s34, s3, s21
	s_or_b32 s36, s2, s20
	s_branch .LBB0_1300

.Lnodef_G1_6:
	ds_read_b128 v[186:189], v255 offset:12288
	ds_read_b128 v[182:185], v253 offset:8192
	ds_read_b128 v[178:181], v255 offset:8192
	ds_read_b128 v[190:193], v253 offset:12288
	s_add_i32 s2, s40, -1
	s_cmp_lt_i32 s2, s35
	s_cselect_b64 s[22:23], -1, 0
	s_cmp_ge_i32 s2, s35
	s_waitcnt lgkmcnt(7)
	v_mfma_f32_16x16x32_bf16 v[158:161], v[194:197], v[162:165], v[158:161]
	v_mfma_f32_16x16x32_bf16 v[154:157], v[198:201], v[162:165], v[154:157]
	v_mfma_f32_16x16x32_bf16 v[150:153], v[202:205], v[162:165], v[150:153]
	v_mfma_f32_16x16x32_bf16 v[146:149], v[206:209], v[162:165], v[146:149]
	ds_read_b128 v[162:165], v247
	s_waitcnt lgkmcnt(7)
	v_mfma_f32_16x16x32_bf16 v[142:145], v[194:197], v[166:169], v[142:145]
	v_mfma_f32_16x16x32_bf16 v[138:141], v[198:201], v[166:169], v[138:141]
	v_mfma_f32_16x16x32_bf16 v[134:137], v[202:205], v[166:169], v[134:137]
	v_mfma_f32_16x16x32_bf16 v[130:133], v[206:209], v[166:169], v[130:133]
	s_waitcnt vmcnt(6)
	ds_write_b128 v235, v[30:33]
	ds_write_b128 v235, v[26:29] offset:8192
.LBB0_2205:
	s_lshl_b32 s6, s49, 8
	s_ashr_i32 s7, s6, 31
	s_lshl_b32 s2, s26, 6
	s_ashr_i32 s3, s2, 31
	s_lshl_b64 s[20:21], s[6:7], 11
	s_add_u32 s24, s29, s20
	s_addc_u32 s25, s30, s21
	s_lshl_b64 s[20:21], s[2:3], 1
	s_add_u32 s24, s24, s20
	s_addc_u32 s25, s25, s21
	global_load_dwordx4 v[30:33], v233, s[24:25]
	global_load_dwordx4 v[26:29], v234, s[24:25]
	s_andn2_b64 vcc, exec, s[22:23]
	ds_read_b128 v[166:169], v245
	s_waitcnt lgkmcnt(9)
	v_mfma_f32_16x16x32_bf16 v[126:129], v[194:197], v[170:173], v[126:129]
	v_mfma_f32_16x16x32_bf16 v[122:125], v[198:201], v[170:173], v[122:125]
	v_mfma_f32_16x16x32_bf16 v[118:121], v[202:205], v[170:173], v[118:121]
	v_mfma_f32_16x16x32_bf16 v[114:117], v[206:209], v[170:173], v[114:117]
	ds_read_b128 v[170:173], v247 offset:4096
	s_waitcnt lgkmcnt(9)
	v_mfma_f32_16x16x32_bf16 v[110:113], v[194:197], v[174:177], v[110:113]
	v_mfma_f32_16x16x32_bf16 v[106:109], v[198:201], v[174:177], v[106:109]
	v_mfma_f32_16x16x32_bf16 v[102:105], v[202:205], v[174:177], v[102:105]
	v_mfma_f32_16x16x32_bf16 v[82:85], v[206:209], v[174:177], v[82:85]
	ds_read_b128 v[210:213], v243
	ds_read_b128 v[214:217], v241
	ds_read_b128 v[218:221], v243 offset:4096
	ds_read_b128 v[222:225], v241 offset:4096
	ds_read_b128 v[174:177], v245 offset:4096
	s_waitcnt lgkmcnt(11)
	v_mfma_f32_16x16x32_bf16 v[98:101], v[194:197], v[178:181], v[98:101]
	v_mfma_f32_16x16x32_bf16 v[94:97], v[198:201], v[178:181], v[94:97]
	v_mfma_f32_16x16x32_bf16 v[90:93], v[202:205], v[178:181], v[90:93]
	v_mfma_f32_16x16x32_bf16 v[86:89], v[206:209], v[178:181], v[86:89]
	s_waitcnt vmcnt(6)
	ds_write_b128 v235, v[22:25] offset:16384
	ds_write_b128 v235, v[18:21] offset:24576

.LBB0_2209:
	s_lshl_b32 s22, s48, 8
	s_ashr_i32 s23, s22, 31
	s_lshl_b64 s[24:25], s[22:23], 11
	s_add_u32 s24, s31, s24
	s_addc_u32 s25, s33, s25
	s_add_u32 s20, s24, s20
	s_addc_u32 s21, s25, s21
	global_load_dwordx4 v[10:13], v234, s[20:21]
	global_load_dwordx4 v[14:17], v233, s[20:21]
	s_and_b64 vcc, exec, s[2:3]
	ds_read_b128 v[186:189], v247 offset:12288
	v_mfma_f32_16x16x32_bf16 v[46:49], v[194:197], v[190:193], v[46:49]
	v_mfma_f32_16x16x32_bf16 v[42:45], v[198:201], v[190:193], v[42:45]
	v_mfma_f32_16x16x32_bf16 v[38:41], v[202:205], v[190:193], v[38:41]
	v_mfma_f32_16x16x32_bf16 v[34:37], v[206:209], v[190:193], v[34:37]
	s_waitcnt lgkmcnt(10)
	ds_read_b128 v[190:193], v245 offset:12288
	s_waitcnt lgkmcnt(9)
	v_mfma_f32_16x16x32_bf16 v[158:161], v[210:213], v[162:165], v[158:161]
	v_mfma_f32_16x16x32_bf16 v[154:157], v[214:217], v[162:165], v[154:157]
	v_mfma_f32_16x16x32_bf16 v[150:153], v[218:221], v[162:165], v[150:153]
	v_mfma_f32_16x16x32_bf16 v[146:149], v[222:225], v[162:165], v[146:149]
	v_mfma_f32_16x16x32_bf16 v[142:145], v[210:213], v[166:169], v[142:145]
	v_mfma_f32_16x16x32_bf16 v[138:141], v[214:217], v[166:169], v[138:141]
	v_mfma_f32_16x16x32_bf16 v[134:137], v[218:221], v[166:169], v[134:137]
	v_mfma_f32_16x16x32_bf16 v[130:133], v[222:225], v[166:169], v[130:133]
	s_waitcnt vmcnt(6)
	ds_write_b128 v235, v[6:9] offset:49152
	ds_write_b128 v235, v[2:5] offset:57344
.LBB0_2211:
	global_load_dwordx4 v[2:5], v232, s[20:21]
	global_load_dwordx4 v[6:9], v231, s[20:21]
	v_mfma_f32_16x16x32_bf16 v[126:129], v[210:213], v[170:173], v[126:129]
	v_mfma_f32_16x16x32_bf16 v[122:125], v[214:217], v[170:173], v[122:125]
	v_mfma_f32_16x16x32_bf16 v[118:121], v[218:221], v[170:173], v[118:121]
	v_mfma_f32_16x16x32_bf16 v[114:117], v[222:225], v[170:173], v[114:117]
	s_waitcnt lgkmcnt(10)
	v_mfma_f32_16x16x32_bf16 v[110:113], v[210:213], v[174:177], v[110:113]
	v_mfma_f32_16x16x32_bf16 v[106:109], v[214:217], v[174:177], v[106:109]
	v_mfma_f32_16x16x32_bf16 v[102:105], v[218:221], v[174:177], v[102:105]
	v_mfma_f32_16x16x32_bf16 v[82:85], v[222:225], v[174:177], v[82:85]
	s_lshl_b64 s[2:3], s[6:7], 10
	s_lshl_b64 s[20:21], s[22:23], 10
	s_add_i32 s51, s26, 1
	s_cmp_lg_u32 s51, 16
	s_cbranch_scc1 .LBB0_2215
	s_add_i32 s28, s28, s11
	s_cmp_gt_i32 s28, 31
	s_cbranch_scc1 .LBB0_2214
	s_ashr_i32 s3, s28, 31
	s_lshr_b32 s3, s3, 27
	s_add_i32 s3, s28, s3
	s_ashr_i32 s3, s3, 5
	s_mov_b32 s2, s10
	s_lshl_b32 s6, s3, 6
	s_lshl_b32 s7, s28, 1
	s_sub_i32 s6, s7, s6
	s_and_b32 s2, s2, 7
	s_and_b32 s6, s6, -8
	s_lshl_b32 s3, s3, 2
	s_and_b32 s7, s28, 3
	s_or_b32 s48, s3, s7
	s_or_b32 s49, s2, s6
	s_lshl_b32 s2, s49, 8
	s_lshl_b32 s6, s48, 8
	s_ashr_i32 s3, s2, 31
	s_ashr_i32 s7, s6, 31
	s_lshl_b64 s[2:3], s[2:3], 10
	s_lshl_b64 s[20:21], s[6:7], 10

.LBB0_2215:
	s_waitcnt lgkmcnt(0)
	s_barrier
	ds_read_b128 v[194:197], v250
	ds_read_b128 v[198:201], v248
	ds_read_b128 v[202:205], v250 offset:4096
	ds_read_b128 v[206:209], v248 offset:4096
	ds_read_b128 v[162:165], v254
	ds_read_b128 v[166:169], v252
	ds_read_b128 v[170:173], v254 offset:4096
	ds_read_b128 v[174:177], v252 offset:4096
	v_mfma_f32_16x16x32_bf16 v[98:101], v[210:213], v[178:181], v[98:101]
	v_mfma_f32_16x16x32_bf16 v[94:97], v[214:217], v[178:181], v[94:97]
	v_mfma_f32_16x16x32_bf16 v[90:93], v[218:221], v[178:181], v[90:93]
	v_mfma_f32_16x16x32_bf16 v[86:89], v[222:225], v[178:181], v[86:89]
	v_mfma_f32_16x16x32_bf16 v[78:81], v[210:213], v[182:185], v[78:81]
	v_mfma_f32_16x16x32_bf16 v[74:77], v[214:217], v[182:185], v[74:77]
	v_mfma_f32_16x16x32_bf16 v[70:73], v[218:221], v[182:185], v[70:73]
	v_mfma_f32_16x16x32_bf16 v[66:69], v[222:225], v[182:185], v[66:69]
	v_mfma_f32_16x16x32_bf16 v[62:65], v[210:213], v[186:189], v[62:65]
	v_mfma_f32_16x16x32_bf16 v[58:61], v[214:217], v[186:189], v[58:61]
	v_mfma_f32_16x16x32_bf16 v[54:57], v[218:221], v[186:189], v[54:57]
	v_mfma_f32_16x16x32_bf16 v[50:53], v[222:225], v[186:189], v[50:53]
	v_mfma_f32_16x16x32_bf16 v[46:49], v[210:213], v[190:193], v[46:49]
	v_mfma_f32_16x16x32_bf16 v[42:45], v[214:217], v[190:193], v[42:45]
	v_mfma_f32_16x16x32_bf16 v[38:41], v[218:221], v[190:193], v[38:41]
	v_mfma_f32_16x16x32_bf16 v[34:37], v[222:225], v[190:193], v[34:37]
	ds_read_b128 v[186:189], v254 offset:12288
	ds_read_b128 v[182:185], v252 offset:8192
	ds_read_b128 v[178:181], v254 offset:8192
	ds_read_b128 v[190:193], v252 offset:12288
	s_cmp_lt_i32 s40, s35
	s_cselect_b64 s[24:25], -1, 0
	s_cmp_ge_i32 s40, s35
	s_cselect_b64 s[6:7], -1, 0
	s_and_b64 vcc, exec, s[6:7]
	s_waitcnt lgkmcnt(7)
	v_mfma_f32_16x16x32_bf16 v[158:161], v[194:197], v[162:165], v[158:161]
	v_mfma_f32_16x16x32_bf16 v[154:157], v[198:201], v[162:165], v[154:157]
	v_mfma_f32_16x16x32_bf16 v[150:153], v[202:205], v[162:165], v[150:153]
	v_mfma_f32_16x16x32_bf16 v[146:149], v[206:209], v[162:165], v[146:149]
	ds_read_b128 v[162:165], v246
	s_waitcnt lgkmcnt(7)
	v_mfma_f32_16x16x32_bf16 v[142:145], v[194:197], v[166:169], v[142:145]
	v_mfma_f32_16x16x32_bf16 v[138:141], v[198:201], v[166:169], v[138:141]
	v_mfma_f32_16x16x32_bf16 v[134:137], v[202:205], v[166:169], v[134:137]
	v_mfma_f32_16x16x32_bf16 v[130:133], v[206:209], v[166:169], v[130:133]
	s_waitcnt vmcnt(6)
	ds_write_b128 v236, v[26:29]
	ds_write_b128 v236, v[30:33] offset:8192
.LBB0_2217:
	s_lshl_b32 s22, s51, 6
	s_ashr_i32 s23, s22, 31
	s_lshl_b64 s[2:3], s[2:3], 1
	s_add_u32 s2, s29, s2
	s_addc_u32 s3, s30, s3
	s_lshl_b64 s[22:23], s[22:23], 1
	s_add_u32 s26, s2, s22
	s_addc_u32 s27, s3, s23
	global_load_dwordx4 v[30:33], v234, s[26:27]
	global_load_dwordx4 v[26:29], v233, s[26:27]
	s_andn2_b64 vcc, exec, s[24:25]
	ds_read_b128 v[166:169], v244
	s_waitcnt lgkmcnt(9)
	v_mfma_f32_16x16x32_bf16 v[126:129], v[194:197], v[170:173], v[126:129]
	v_mfma_f32_16x16x32_bf16 v[122:125], v[198:201], v[170:173], v[122:125]
	v_mfma_f32_16x16x32_bf16 v[118:121], v[202:205], v[170:173], v[118:121]
	v_mfma_f32_16x16x32_bf16 v[114:117], v[206:209], v[170:173], v[114:117]
	ds_read_b128 v[170:173], v246 offset:4096
	s_waitcnt lgkmcnt(9)
	v_mfma_f32_16x16x32_bf16 v[110:113], v[194:197], v[174:177], v[110:113]
	v_mfma_f32_16x16x32_bf16 v[106:109], v[198:201], v[174:177], v[106:109]
	v_mfma_f32_16x16x32_bf16 v[102:105], v[202:205], v[174:177], v[102:105]
	v_mfma_f32_16x16x32_bf16 v[82:85], v[206:209], v[174:177], v[82:85]
	ds_read_b128 v[210:213], v242
	ds_read_b128 v[214:217], v237
	ds_read_b128 v[218:221], v242 offset:4096
	ds_read_b128 v[222:225], v237 offset:4096
	ds_read_b128 v[174:177], v244 offset:4096
	s_waitcnt lgkmcnt(11)
	v_mfma_f32_16x16x32_bf16 v[98:101], v[194:197], v[178:181], v[98:101]
	v_mfma_f32_16x16x32_bf16 v[94:97], v[198:201], v[178:181], v[94:97]
	v_mfma_f32_16x16x32_bf16 v[90:93], v[202:205], v[178:181], v[90:93]
	v_mfma_f32_16x16x32_bf16 v[86:89], v[206:209], v[178:181], v[86:89]
	s_waitcnt vmcnt(6)
	ds_write_b128 v236, v[18:21] offset:16384
	ds_write_b128 v236, v[22:25] offset:24576

.LBB0_2221:
	s_lshl_b64 s[20:21], s[20:21], 1
	s_add_u32 s20, s31, s20
	s_addc_u32 s21, s33, s21
	s_add_u32 s20, s20, s22
	s_addc_u32 s21, s21, s23
	global_load_dwordx4 v[14:17], v234, s[20:21]
	global_load_dwordx4 v[10:13], v233, s[20:21]
	s_and_b64 vcc, exec, s[2:3]
	ds_read_b128 v[186:189], v246 offset:12288
	v_mfma_f32_16x16x32_bf16 v[46:49], v[194:197], v[190:193], v[46:49]
	v_mfma_f32_16x16x32_bf16 v[42:45], v[198:201], v[190:193], v[42:45]
	v_mfma_f32_16x16x32_bf16 v[38:41], v[202:205], v[190:193], v[38:41]
	v_mfma_f32_16x16x32_bf16 v[34:37], v[206:209], v[190:193], v[34:37]
	s_waitcnt lgkmcnt(10)
	ds_read_b128 v[190:193], v244 offset:12288
	s_waitcnt lgkmcnt(9)
	v_mfma_f32_16x16x32_bf16 v[158:161], v[210:213], v[162:165], v[158:161]
	v_mfma_f32_16x16x32_bf16 v[154:157], v[214:217], v[162:165], v[154:157]
	v_mfma_f32_16x16x32_bf16 v[150:153], v[218:221], v[162:165], v[150:153]
	v_mfma_f32_16x16x32_bf16 v[146:149], v[222:225], v[162:165], v[146:149]
	v_mfma_f32_16x16x32_bf16 v[142:145], v[210:213], v[166:169], v[142:145]
	v_mfma_f32_16x16x32_bf16 v[138:141], v[214:217], v[166:169], v[138:141]
	v_mfma_f32_16x16x32_bf16 v[134:137], v[218:221], v[166:169], v[134:137]
	v_mfma_f32_16x16x32_bf16 v[130:133], v[222:225], v[166:169], v[130:133]
	s_waitcnt vmcnt(6)
	ds_write_b128 v236, v[2:5] offset:49152
	ds_write_b128 v236, v[6:9] offset:57344
.LBB0_2223:
	global_load_dwordx4 v[6:9], v232, s[20:21]
	global_load_dwordx4 v[2:5], v231, s[20:21]
	v_mfma_f32_16x16x32_bf16 v[126:129], v[210:213], v[170:173], v[126:129]
	v_mfma_f32_16x16x32_bf16 v[122:125], v[214:217], v[170:173], v[122:125]
	v_mfma_f32_16x16x32_bf16 v[118:121], v[218:221], v[170:173], v[118:121]
	v_mfma_f32_16x16x32_bf16 v[114:117], v[222:225], v[170:173], v[114:117]
	s_waitcnt lgkmcnt(10)
	v_mfma_f32_16x16x32_bf16 v[110:113], v[210:213], v[174:177], v[110:113]
	v_mfma_f32_16x16x32_bf16 v[106:109], v[214:217], v[174:177], v[106:109]
	v_mfma_f32_16x16x32_bf16 v[102:105], v[218:221], v[174:177], v[102:105]
	v_mfma_f32_16x16x32_bf16 v[82:85], v[222:225], v[174:177], v[82:85]
	s_add_i32 s26, s51, 1
	s_cmp_lg_u32 s26, 16
	s_cbranch_scc1 .LBB0_2227
	s_add_i32 s28, s28, s11
	s_cmp_gt_i32 s28, 31
	s_cbranch_scc1 .LBB0_2226
	s_ashr_i32 s3, s28, 31
	s_lshr_b32 s3, s3, 27
	s_add_i32 s3, s28, s3
	s_ashr_i32 s3, s3, 5
	s_mov_b32 s2, s10
	s_lshl_b32 s20, s3, 6
	s_lshl_b32 s21, s28, 1
	s_sub_i32 s20, s21, s20
	s_and_b32 s2, s2, 7
	s_and_b32 s20, s20, -8
	s_lshl_b32 s3, s3, 2
	s_and_b32 s21, s28, 3
	s_or_b32 s48, s3, s21
	s_or_b32 s49, s2, s20

.LBB0_2227:
	s_add_i32 s50, s50, 2
	s_cmp_lg_u32 s50, 16
	s_waitcnt lgkmcnt(0)
	s_mov_b32 s98, 1
	s_cbranch_scc1 .LBB0_2202
	s_mov_b32 s98, 0
	v_mfma_f32_16x16x32_bf16 v[98:101], v[210:213], v[178:181], v[98:101]
	v_mfma_f32_16x16x32_bf16 v[94:97], v[214:217], v[178:181], v[94:97]
	v_mfma_f32_16x16x32_bf16 v[90:93], v[218:221], v[178:181], v[90:93]
	v_mfma_f32_16x16x32_bf16 v[86:89], v[222:225], v[178:181], v[86:89]
	v_mfma_f32_16x16x32_bf16 v[78:81], v[210:213], v[182:185], v[78:81]
	v_mfma_f32_16x16x32_bf16 v[74:77], v[214:217], v[182:185], v[74:77]
	v_mfma_f32_16x16x32_bf16 v[70:73], v[218:221], v[182:185], v[70:73]
	v_mfma_f32_16x16x32_bf16 v[66:69], v[222:225], v[182:185], v[66:69]
	v_mfma_f32_16x16x32_bf16 v[62:65], v[210:213], v[186:189], v[62:65]
	v_mfma_f32_16x16x32_bf16 v[58:61], v[214:217], v[186:189], v[58:61]
	v_mfma_f32_16x16x32_bf16 v[54:57], v[218:221], v[186:189], v[54:57]
	v_mfma_f32_16x16x32_bf16 v[50:53], v[222:225], v[186:189], v[50:53]
	v_mfma_f32_16x16x32_bf16 v[46:49], v[210:213], v[190:193], v[46:49]
	v_mfma_f32_16x16x32_bf16 v[42:45], v[214:217], v[190:193], v[42:45]
	v_mfma_f32_16x16x32_bf16 v[38:41], v[218:221], v[190:193], v[38:41]
	v_mfma_f32_16x16x32_bf16 v[34:37], v[222:225], v[190:193], v[34:37]
	s_nop 7
	s_nop 7
	v_mov_b32_e32 v172, v0
	s_nop 0
	v_ashrrev_i32_e32 v162, 1, v172
	v_and_b32_e32 v162, 0xffffff80, v162
	v_lshl_add_u32 v162, s36, 8, v162
	v_and_or_b32 v164, v172, 15, v162
	v_add_u32_e32 v162, 0xffffe000, v162
	v_ashrrev_i32_e32 v162, 11, v162
	v_mad_i32_i24 v162, v162, s45, s45
	v_cmp_lt_i32_e32 vcc, s46, v164
	v_ashrrev_i32_e32 v163, 31, v162
	s_and_saveexec_b64 s[2:3], vcc
	s_xor_b64 s[2:3], exec, s[2:3]
	v_add_u32_e32 v238, 0xffffe000, v164
	v_lshlrev_b64 v[166:167], 12, v[238:239]
	v_mov_b32_e32 v165, v239
	v_lshl_add_u64 v[168:169], s[12:13], 0, v[166:167]
	v_lshlrev_b64 v[170:171], 12, v[164:165]
	v_mov_b64_e32 v[166:167], v[162:163]
	s_andn2_saveexec_b64 s[2:3], s[2:3]
	v_ashrrev_i32_e32 v165, 31, v164
	v_lshlrev_b64 v[170:171], 12, v[164:165]
	v_lshl_add_u64 v[168:169], s[4:5], 0, v[170:171]
	v_mov_b64_e32 v[166:167], 0
	s_or_b64 exec, exec, s[2:3]
	v_and_b32_e32 v165, 0xc0, v172
	v_lshrrev_b32_e32 v172, 2, v172
	s_lshl_b32 s2, s34, 8
	v_and_b32_e32 v172, 12, v172
	v_or3_b32 v172, v165, s2, v172
	v_ashrrev_i32_e32 v173, 31, v172
	v_lshl_add_u64 v[176:177], v[166:167], 2, s[14:15]
	v_lshlrev_b64 v[166:167], 2, v[172:173]
	v_lshl_add_u64 v[180:181], v[168:169], 0, v[166:167]
	v_lshl_add_u64 v[182:183], v[176:177], 0, v[166:167]
	global_load_dwordx4 v[172:175], v[180:181], off
	global_load_dwordx4 v[176:179], v[182:183], off
	v_lshl_add_u64 v[168:169], s[4:5], 0, v[170:171]
	v_lshl_add_u64 v[184:185], v[168:169], 0, v[166:167]
	s_waitcnt vmcnt(0)
	v_pk_fma_f32 v[160:161], v[160:161], v[178:179], v[174:175]
	v_pk_fma_f32 v[158:159], v[158:159], v[176:177], v[172:173]
	global_store_dwordx4 v[184:185], v[158:161], off
	global_load_dwordx4 v[158:161], v[180:181], off offset:64
	s_nop 0
	global_load_dwordx4 v[168:171], v[182:183], off offset:64
	s_waitcnt vmcnt(0)
	v_pk_fma_f32 v[156:157], v[156:157], v[170:171], v[160:161]
	v_pk_fma_f32 v[154:155], v[154:155], v[168:169], v[158:159]
	global_store_dwordx4 v[184:185], v[154:157], off offset:64
	global_load_dwordx4 v[154:157], v[180:181], off offset:128
	s_nop 0
	global_load_dwordx4 v[158:161], v[182:183], off offset:128
	s_waitcnt vmcnt(0)
	v_pk_fma_f32 v[152:153], v[152:153], v[160:161], v[156:157]
	v_pk_fma_f32 v[150:151], v[150:151], v[158:159], v[154:155]
	global_store_dwordx4 v[184:185], v[150:153], off offset:128
	global_load_dwordx4 v[152:155], v[180:181], off offset:192
	s_nop 0
	global_load_dwordx4 v[156:159], v[182:183], off offset:192
	v_or_b32_e32 v150, 16, v164
	v_cmp_lt_i32_e32 vcc, s46, v150
	s_waitcnt vmcnt(0)
	v_pk_fma_f32 v[148:149], v[148:149], v[158:159], v[154:155]
	v_pk_fma_f32 v[146:147], v[146:147], v[156:157], v[152:153]
	global_store_dwordx4 v[184:185], v[146:149], off offset:192
	s_and_saveexec_b64 s[2:3], vcc
	s_xor_b64 s[2:3], exec, s[2:3]
	v_add_u32_e32 v238, 0xffffe010, v164
	v_lshlrev_b64 v[146:147], 12, v[238:239]
	v_mov_b32_e32 v151, v239
	v_lshl_add_u64 v[146:147], s[12:13], 0, v[146:147]
	v_lshlrev_b64 v[148:149], 12, v[150:151]
	v_mov_b64_e32 v[152:153], v[162:163]
	s_andn2_saveexec_b64 s[2:3], s[2:3]
	v_ashrrev_i32_e32 v151, 31, v150
	v_lshlrev_b64 v[148:149], 12, v[150:151]
	v_lshl_add_u64 v[146:147], s[4:5], 0, v[148:149]
	v_mov_b64_e32 v[152:153], 0
	s_or_b64 exec, exec, s[2:3]
	v_lshl_add_u64 v[154:155], v[152:153], 2, s[14:15]
	v_lshl_add_u64 v[158:159], v[146:147], 0, v[166:167]
	v_lshl_add_u64 v[160:161], v[154:155], 0, v[166:167]
	global_load_dwordx4 v[150:153], v[158:159], off
	global_load_dwordx4 v[154:157], v[160:161], off
	v_lshl_add_u64 v[146:147], s[4:5], 0, v[148:149]
	v_lshl_add_u64 v[168:169], v[146:147], 0, v[166:167]
	s_waitcnt vmcnt(0)
	v_pk_fma_f32 v[144:145], v[144:145], v[156:157], v[152:153]
	v_pk_fma_f32 v[142:143], v[142:143], v[154:155], v[150:151]
	global_store_dwordx4 v[168:169], v[142:145], off
	global_load_dwordx4 v[142:145], v[158:159], off offset:64
	s_nop 0
	global_load_dwordx4 v[146:149], v[160:161], off offset:64
	s_waitcnt vmcnt(0)
	v_pk_fma_f32 v[140:141], v[140:141], v[148:149], v[144:145]
	v_pk_fma_f32 v[138:139], v[138:139], v[146:147], v[142:143]
	global_store_dwordx4 v[168:169], v[138:141], off offset:64
	global_load_dwordx4 v[138:141], v[158:159], off offset:128
	s_nop 0
	global_load_dwordx4 v[142:145], v[160:161], off offset:128
	s_waitcnt vmcnt(0)
	v_pk_fma_f32 v[136:137], v[136:137], v[144:145], v[140:141]
	v_pk_fma_f32 v[134:135], v[134:135], v[142:143], v[138:139]
	global_store_dwordx4 v[168:169], v[134:137], off offset:128
	global_load_dwordx4 v[136:139], v[158:159], off offset:192
	s_nop 0
	global_load_dwordx4 v[140:143], v[160:161], off offset:192
	v_or_b32_e32 v134, 32, v164
	v_cmp_lt_i32_e32 vcc, s46, v134
	s_waitcnt vmcnt(0)
	v_pk_fma_f32 v[132:133], v[132:133], v[142:143], v[138:139]
	v_pk_fma_f32 v[130:131], v[130:131], v[140:141], v[136:137]
	global_store_dwordx4 v[168:169], v[130:133], off offset:192
	s_and_saveexec_b64 s[2:3], vcc
	s_xor_b64 s[2:3], exec, s[2:3]
	v_add_u32_e32 v238, 0xffffe020, v164
	v_lshlrev_b64 v[130:131], 12, v[238:239]
	v_mov_b32_e32 v135, v239
	v_lshl_add_u64 v[130:131], s[12:13], 0, v[130:131]
	v_lshlrev_b64 v[132:133], 12, v[134:135]
	v_mov_b64_e32 v[136:137], v[162:163]
	s_andn2_saveexec_b64 s[2:3], s[2:3]
	v_ashrrev_i32_e32 v135, 31, v134
	v_lshlrev_b64 v[132:133], 12, v[134:135]
	v_lshl_add_u64 v[130:131], s[4:5], 0, v[132:133]
	v_mov_b64_e32 v[136:137], 0
	s_or_b64 exec, exec, s[2:3]
	v_lshl_add_u64 v[138:139], v[136:137], 2, s[14:15]
	v_lshl_add_u64 v[142:143], v[130:131], 0, v[166:167]
	v_lshl_add_u64 v[144:145], v[138:139], 0, v[166:167]
	global_load_dwordx4 v[134:137], v[142:143], off
	global_load_dwordx4 v[138:141], v[144:145], off
	v_lshl_add_u64 v[130:131], s[4:5], 0, v[132:133]
	v_lshl_add_u64 v[146:147], v[130:131], 0, v[166:167]
	s_waitcnt vmcnt(0)
	v_pk_fma_f32 v[128:129], v[128:129], v[140:141], v[136:137]
	v_pk_fma_f32 v[126:127], v[126:127], v[138:139], v[134:135]
	global_store_dwordx4 v[146:147], v[126:129], off
	global_load_dwordx4 v[126:129], v[142:143], off offset:64
	s_nop 0
	global_load_dwordx4 v[130:133], v[144:145], off offset:64
	s_waitcnt vmcnt(0)
	v_pk_fma_f32 v[124:125], v[124:125], v[132:133], v[128:129]
	v_pk_fma_f32 v[122:123], v[122:123], v[130:131], v[126:127]
	global_store_dwordx4 v[146:147], v[122:125], off offset:64
	global_load_dwordx4 v[122:125], v[142:143], off offset:128
	s_nop 0
	global_load_dwordx4 v[126:129], v[144:145], off offset:128
	s_waitcnt vmcnt(0)
	v_pk_fma_f32 v[120:121], v[120:121], v[128:129], v[124:125]
	v_pk_fma_f32 v[118:119], v[118:119], v[126:127], v[122:123]
	global_store_dwordx4 v[146:147], v[118:121], off offset:128
	global_load_dwordx4 v[120:123], v[142:143], off offset:192
	s_nop 0
	global_load_dwordx4 v[124:127], v[144:145], off offset:192
	v_or_b32_e32 v118, 48, v164
	v_cmp_lt_i32_e32 vcc, s46, v118
	s_waitcnt vmcnt(0)
	v_pk_fma_f32 v[116:117], v[116:117], v[126:127], v[122:123]
	v_pk_fma_f32 v[114:115], v[114:115], v[124:125], v[120:121]
	global_store_dwordx4 v[146:147], v[114:117], off offset:192
	s_and_saveexec_b64 s[2:3], vcc
	s_xor_b64 s[2:3], exec, s[2:3]
	v_add_u32_e32 v238, 0xffffe030, v164
	v_lshlrev_b64 v[114:115], 12, v[238:239]
	v_mov_b32_e32 v119, v239
	v_lshl_add_u64 v[114:115], s[12:13], 0, v[114:115]
	v_lshlrev_b64 v[116:117], 12, v[118:119]
	v_mov_b64_e32 v[120:121], v[162:163]
	s_andn2_saveexec_b64 s[2:3], s[2:3]
	v_ashrrev_i32_e32 v119, 31, v118
	v_lshlrev_b64 v[116:117], 12, v[118:119]
	v_lshl_add_u64 v[114:115], s[4:5], 0, v[116:117]
	v_mov_b64_e32 v[120:121], 0
	s_or_b64 exec, exec, s[2:3]
	v_lshl_add_u64 v[122:123], v[120:121], 2, s[14:15]
	v_lshl_add_u64 v[126:127], v[114:115], 0, v[166:167]
	v_lshl_add_u64 v[128:129], v[122:123], 0, v[166:167]
	global_load_dwordx4 v[118:121], v[126:127], off
	global_load_dwordx4 v[122:125], v[128:129], off
	v_lshl_add_u64 v[114:115], s[4:5], 0, v[116:117]
	v_lshl_add_u64 v[130:131], v[114:115], 0, v[166:167]
	s_waitcnt vmcnt(0)
	v_pk_fma_f32 v[112:113], v[112:113], v[124:125], v[120:121]
	v_pk_fma_f32 v[110:111], v[110:111], v[122:123], v[118:119]
	global_store_dwordx4 v[130:131], v[110:113], off
	global_load_dwordx4 v[110:113], v[126:127], off offset:64
	s_nop 0
	global_load_dwordx4 v[114:117], v[128:129], off offset:64
	s_waitcnt vmcnt(0)
	v_pk_fma_f32 v[108:109], v[108:109], v[116:117], v[112:113]
	v_pk_fma_f32 v[106:107], v[106:107], v[114:115], v[110:111]
	global_store_dwordx4 v[130:131], v[106:109], off offset:64
	global_load_dwordx4 v[106:109], v[126:127], off offset:128
	s_nop 0
	global_load_dwordx4 v[110:113], v[128:129], off offset:128
	s_waitcnt vmcnt(0)
	v_pk_fma_f32 v[104:105], v[104:105], v[112:113], v[108:109]
	v_pk_fma_f32 v[102:103], v[102:103], v[110:111], v[106:107]
	global_store_dwordx4 v[130:131], v[102:105], off offset:128
	global_load_dwordx4 v[104:107], v[126:127], off offset:192
	s_nop 0
	global_load_dwordx4 v[108:111], v[128:129], off offset:192
	v_or_b32_e32 v102, 64, v164
	v_cmp_lt_i32_e32 vcc, s46, v102
	s_waitcnt vmcnt(0)
	v_pk_fma_f32 v[84:85], v[84:85], v[110:111], v[106:107]
	v_pk_fma_f32 v[82:83], v[82:83], v[108:109], v[104:105]
	global_store_dwordx4 v[130:131], v[82:85], off offset:192
	s_and_saveexec_b64 s[2:3], vcc
	s_xor_b64 s[2:3], exec, s[2:3]
	v_add_u32_e32 v238, 0xffffe040, v164
	v_lshlrev_b64 v[82:83], 12, v[238:239]
	v_mov_b32_e32 v103, v239
	v_lshl_add_u64 v[82:83], s[12:13], 0, v[82:83]
	v_lshlrev_b64 v[84:85], 12, v[102:103]
	v_mov_b64_e32 v[104:105], v[162:163]
	s_andn2_saveexec_b64 s[2:3], s[2:3]
	v_ashrrev_i32_e32 v103, 31, v102
	v_lshlrev_b64 v[84:85], 12, v[102:103]
	v_lshl_add_u64 v[82:83], s[4:5], 0, v[84:85]
	v_mov_b64_e32 v[104:105], 0
	s_or_b64 exec, exec, s[2:3]
	v_lshl_add_u64 v[106:107], v[104:105], 2, s[14:15]
	v_lshl_add_u64 v[110:111], v[82:83], 0, v[166:167]
	v_lshl_add_u64 v[112:113], v[106:107], 0, v[166:167]
	global_load_dwordx4 v[102:105], v[110:111], off
	global_load_dwordx4 v[106:109], v[112:113], off
	v_lshl_add_u64 v[82:83], s[4:5], 0, v[84:85]
	v_lshl_add_u64 v[114:115], v[82:83], 0, v[166:167]
	s_waitcnt vmcnt(0)
	v_pk_fma_f32 v[84:85], v[100:101], v[108:109], v[104:105]
	v_pk_fma_f32 v[82:83], v[98:99], v[106:107], v[102:103]
	global_store_dwordx4 v[114:115], v[82:85], off
	global_load_dwordx4 v[82:85], v[110:111], off offset:64
	s_nop 0
	global_load_dwordx4 v[98:101], v[112:113], off offset:64
	s_waitcnt vmcnt(0)
	v_pk_fma_f32 v[84:85], v[96:97], v[100:101], v[84:85]
	v_pk_fma_f32 v[82:83], v[94:95], v[98:99], v[82:83]
	global_store_dwordx4 v[114:115], v[82:85], off offset:64
	global_load_dwordx4 v[82:85], v[110:111], off offset:128
	s_nop 0
	global_load_dwordx4 v[94:97], v[112:113], off offset:128
	s_waitcnt vmcnt(0)
	v_pk_fma_f32 v[84:85], v[92:93], v[96:97], v[84:85]
	v_pk_fma_f32 v[82:83], v[90:91], v[94:95], v[82:83]
	global_store_dwordx4 v[114:115], v[82:85], off offset:128
	global_load_dwordx4 v[90:93], v[110:111], off offset:192
	global_load_dwordx4 v[94:97], v[112:113], off offset:192
	v_or_b32_e32 v84, 0x50, v164
	v_cmp_lt_i32_e32 vcc, s46, v84
	s_waitcnt vmcnt(0)
	v_pk_fma_f32 v[88:89], v[88:89], v[96:97], v[92:93]
	v_pk_fma_f32 v[86:87], v[86:87], v[94:95], v[90:91]
	global_store_dwordx4 v[114:115], v[86:89], off offset:192
	s_and_saveexec_b64 s[2:3], vcc
	s_xor_b64 s[2:3], exec, s[2:3]
	v_add_u32_e32 v238, 0xffffe050, v164
	v_lshlrev_b64 v[82:83], 12, v[238:239]
	v_mov_b32_e32 v85, v239
	v_lshl_add_u64 v[82:83], s[12:13], 0, v[82:83]
	v_lshlrev_b64 v[86:87], 12, v[84:85]
	v_mov_b64_e32 v[88:89], v[162:163]
	s_andn2_saveexec_b64 s[2:3], s[2:3]
	v_ashrrev_i32_e32 v85, 31, v84
	v_lshlrev_b64 v[86:87], 12, v[84:85]
	v_lshl_add_u64 v[82:83], s[4:5], 0, v[86:87]
	v_mov_b64_e32 v[88:89], 0
	s_or_b64 exec, exec, s[2:3]
	v_lshl_add_u64 v[88:89], v[88:89], 2, s[14:15]
	v_lshl_add_u64 v[92:93], v[82:83], 0, v[166:167]
	v_lshl_add_u64 v[94:95], v[88:89], 0, v[166:167]
	global_load_dwordx4 v[82:85], v[92:93], off
	global_load_dwordx4 v[88:91], v[94:95], off
	v_lshl_add_u64 v[86:87], s[4:5], 0, v[86:87]
	v_lshl_add_u64 v[86:87], v[86:87], 0, v[166:167]
	s_waitcnt vmcnt(0)
	v_pk_fma_f32 v[80:81], v[80:81], v[90:91], v[84:85]
	v_pk_fma_f32 v[78:79], v[78:79], v[88:89], v[82:83]
	global_store_dwordx4 v[86:87], v[78:81], off
	global_load_dwordx4 v[78:81], v[92:93], off offset:64
	s_nop 0
	global_load_dwordx4 v[82:85], v[94:95], off offset:64
	s_waitcnt vmcnt(0)
	v_pk_fma_f32 v[76:77], v[76:77], v[84:85], v[80:81]
	v_pk_fma_f32 v[74:75], v[74:75], v[82:83], v[78:79]
	global_store_dwordx4 v[86:87], v[74:77], off offset:64
	global_load_dwordx4 v[74:77], v[92:93], off offset:128
	s_nop 0
	global_load_dwordx4 v[78:81], v[94:95], off offset:128
	s_waitcnt vmcnt(0)
	v_pk_fma_f32 v[72:73], v[72:73], v[80:81], v[76:77]
	v_pk_fma_f32 v[70:71], v[70:71], v[78:79], v[74:75]
	global_store_dwordx4 v[86:87], v[70:73], off offset:128
	global_load_dwordx4 v[72:75], v[92:93], off offset:192
	s_nop 0
	global_load_dwordx4 v[76:79], v[94:95], off offset:192
	v_or_b32_e32 v70, 0x60, v164
	v_cmp_lt_i32_e32 vcc, s46, v70
	s_waitcnt vmcnt(0)
	v_pk_fma_f32 v[68:69], v[68:69], v[78:79], v[74:75]
	v_pk_fma_f32 v[66:67], v[66:67], v[76:77], v[72:73]
	global_store_dwordx4 v[86:87], v[66:69], off offset:192
	s_and_saveexec_b64 s[2:3], vcc
	s_xor_b64 s[2:3], exec, s[2:3]
	v_add_u32_e32 v238, 0xffffe060, v164
	v_lshlrev_b64 v[66:67], 12, v[238:239]
	v_mov_b32_e32 v71, v239
	v_lshl_add_u64 v[66:67], s[12:13], 0, v[66:67]
	v_lshlrev_b64 v[68:69], 12, v[70:71]
	v_mov_b64_e32 v[72:73], v[162:163]
	s_andn2_saveexec_b64 s[2:3], s[2:3]
	v_ashrrev_i32_e32 v71, 31, v70
	v_lshlrev_b64 v[68:69], 12, v[70:71]
	v_lshl_add_u64 v[66:67], s[4:5], 0, v[68:69]
	v_mov_b64_e32 v[72:73], 0
	s_or_b64 exec, exec, s[2:3]
	v_lshl_add_u64 v[74:75], v[72:73], 2, s[14:15]
	v_lshl_add_u64 v[78:79], v[66:67], 0, v[166:167]
	v_lshl_add_u64 v[80:81], v[74:75], 0, v[166:167]
	global_load_dwordx4 v[70:73], v[78:79], off
	global_load_dwordx4 v[74:77], v[80:81], off
	v_lshl_add_u64 v[66:67], s[4:5], 0, v[68:69]
	v_lshl_add_u64 v[82:83], v[66:67], 0, v[166:167]
	s_waitcnt vmcnt(0)
	v_pk_fma_f32 v[64:65], v[64:65], v[76:77], v[72:73]
	v_pk_fma_f32 v[62:63], v[62:63], v[74:75], v[70:71]
	global_store_dwordx4 v[82:83], v[62:65], off
	global_load_dwordx4 v[62:65], v[78:79], off offset:64
	s_nop 0
	global_load_dwordx4 v[66:69], v[80:81], off offset:64
	s_waitcnt vmcnt(0)
	v_pk_fma_f32 v[60:61], v[60:61], v[68:69], v[64:65]
	v_pk_fma_f32 v[58:59], v[58:59], v[66:67], v[62:63]
	global_store_dwordx4 v[82:83], v[58:61], off offset:64
	global_load_dwordx4 v[58:61], v[78:79], off offset:128
	s_nop 0
	global_load_dwordx4 v[62:65], v[80:81], off offset:128
	s_waitcnt vmcnt(0)
	v_pk_fma_f32 v[56:57], v[56:57], v[64:65], v[60:61]
	v_pk_fma_f32 v[54:55], v[54:55], v[62:63], v[58:59]
	global_store_dwordx4 v[82:83], v[54:57], off offset:128
	global_load_dwordx4 v[56:59], v[78:79], off offset:192
	s_nop 0
	global_load_dwordx4 v[60:63], v[80:81], off offset:192
	v_or_b32_e32 v54, 0x70, v164
	v_cmp_lt_i32_e32 vcc, s46, v54
	s_waitcnt vmcnt(0)
	v_pk_fma_f32 v[52:53], v[52:53], v[62:63], v[58:59]
	v_pk_fma_f32 v[50:51], v[50:51], v[60:61], v[56:57]
	global_store_dwordx4 v[82:83], v[50:53], off offset:192
	s_and_saveexec_b64 s[2:3], vcc
	s_xor_b64 s[2:3], exec, s[2:3]
	v_add_u32_e32 v238, 0xffffe070, v164
	v_lshlrev_b64 v[50:51], 12, v[238:239]
	v_mov_b32_e32 v55, v239
	v_lshl_add_u64 v[50:51], s[12:13], 0, v[50:51]
	v_lshlrev_b64 v[52:53], 12, v[54:55]
	s_andn2_saveexec_b64 s[2:3], s[2:3]
	v_ashrrev_i32_e32 v55, 31, v54
	v_lshlrev_b64 v[52:53], 12, v[54:55]
	v_lshl_add_u64 v[50:51], s[4:5], 0, v[52:53]
	v_mov_b64_e32 v[162:163], 0
	s_or_b64 exec, exec, s[2:3]
	v_lshl_add_u64 v[58:59], v[162:163], 2, s[14:15]
	v_lshl_add_u64 v[62:63], v[50:51], 0, v[166:167]
	v_lshl_add_u64 v[64:65], v[58:59], 0, v[166:167]
	global_load_dwordx4 v[54:57], v[62:63], off
	global_load_dwordx4 v[58:61], v[64:65], off
	v_lshl_add_u64 v[50:51], s[4:5], 0, v[52:53]
	v_lshl_add_u64 v[66:67], v[50:51], 0, v[166:167]
	s_add_i32 s47, s47, s11
	s_cmp_gt_i32 s47, 31
	s_waitcnt vmcnt(0)
	v_pk_fma_f32 v[48:49], v[48:49], v[60:61], v[56:57]
	v_pk_fma_f32 v[46:47], v[46:47], v[58:59], v[54:55]
	global_store_dwordx4 v[66:67], v[46:49], off
	global_load_dwordx4 v[46:49], v[62:63], off offset:64
	s_nop 0
	global_load_dwordx4 v[50:53], v[64:65], off offset:64
	s_waitcnt vmcnt(0)
	v_pk_fma_f32 v[44:45], v[44:45], v[52:53], v[48:49]
	v_pk_fma_f32 v[42:43], v[42:43], v[50:51], v[46:47]
	global_store_dwordx4 v[66:67], v[42:45], off offset:64
	global_load_dwordx4 v[42:45], v[62:63], off offset:128
	s_nop 0
	global_load_dwordx4 v[46:49], v[64:65], off offset:128
	s_waitcnt vmcnt(0)
	v_pk_fma_f32 v[40:41], v[40:41], v[48:49], v[44:45]
	v_pk_fma_f32 v[38:39], v[38:39], v[46:47], v[42:43]
	global_store_dwordx4 v[66:67], v[38:41], off offset:128
	global_load_dwordx4 v[38:41], v[62:63], off offset:192
	s_nop 0
	global_load_dwordx4 v[42:45], v[64:65], off offset:192
	s_waitcnt vmcnt(0)
	v_pk_fma_f32 v[40:41], v[36:37], v[44:45], v[40:41]
	v_pk_fma_f32 v[38:39], v[34:35], v[42:43], v[38:39]
	v_mov_b32_e32 v37, 0
	global_store_dwordx4 v[66:67], v[38:41], off offset:192
	s_cbranch_scc1 .LBB0_2201
	s_ashr_i32 s3, s47, 31
	s_lshr_b32 s3, s3, 27
	s_add_i32 s3, s47, s3
	s_ashr_i32 s3, s3, 5
	s_mov_b32 s2, s10
	s_lshl_b32 s20, s3, 6
	s_lshl_b32 s21, s47, 1
	s_sub_i32 s20, s21, s20
	s_and_b32 s2, s2, 7
	s_and_b32 s20, s20, -8
	s_lshl_b32 s3, s3, 2
	s_and_b32 s21, s47, 3
	s_or_b32 s34, s3, s21
	s_or_b32 s36, s2, s20
	s_branch .LBB0_2201

.Lnodef_J1_9:
	ds_read_b128 v[186:189], v255 offset:12288
	ds_read_b128 v[182:185], v253 offset:8192
	ds_read_b128 v[178:181], v255 offset:8192
	ds_read_b128 v[190:193], v253 offset:12288
	s_add_i32 s0, s30, -1
	s_cmp_lt_i32 s0, s33
	s_cselect_b64 s[14:15], -1, 0
	s_cmp_ge_i32 s0, s33
	s_waitcnt lgkmcnt(7)
	v_mfma_f32_16x16x32_bf16 v[158:161], v[194:197], v[162:165], v[158:161]
	v_mfma_f32_16x16x32_bf16 v[154:157], v[198:201], v[162:165], v[154:157]
	v_mfma_f32_16x16x32_bf16 v[150:153], v[202:205], v[162:165], v[150:153]
	v_mfma_f32_16x16x32_bf16 v[146:149], v[206:209], v[162:165], v[146:149]
	ds_read_b128 v[162:165], v247
	s_waitcnt lgkmcnt(7)
	v_mfma_f32_16x16x32_bf16 v[142:145], v[194:197], v[166:169], v[142:145]
	v_mfma_f32_16x16x32_bf16 v[138:141], v[198:201], v[166:169], v[138:141]
	v_mfma_f32_16x16x32_bf16 v[134:137], v[202:205], v[166:169], v[134:137]
	v_mfma_f32_16x16x32_bf16 v[130:133], v[206:209], v[166:169], v[130:133]
	s_waitcnt vmcnt(6)
	ds_write_b128 v235, v[30:33]
	ds_write_b128 v235, v[26:29] offset:8192
.LBB0_2547:
	s_lshl_b32 s0, s41, 8
	s_mul_i32 s12, s41, 0xb0000
	s_mul_hi_i32 s13, s0, 0xb00
	s_lshl_b32 s0, s18, 6
	s_ashr_i32 s1, s0, 31
	s_lshl_b64 s[6:7], s[12:13], 1
	s_add_u32 s16, s21, s6
	s_addc_u32 s17, s22, s7
	s_lshl_b64 s[6:7], s[0:1], 1
	s_add_u32 s16, s16, s6
	s_addc_u32 s17, s17, s7
	global_load_dwordx4 v[26:29], v234, s[16:17]
	global_load_dwordx4 v[30:33], v233, s[16:17]
	s_andn2_b64 vcc, exec, s[14:15]
	ds_read_b128 v[166:169], v245
	s_waitcnt lgkmcnt(9)
	v_mfma_f32_16x16x32_bf16 v[126:129], v[194:197], v[170:173], v[126:129]
	v_mfma_f32_16x16x32_bf16 v[122:125], v[198:201], v[170:173], v[122:125]
	v_mfma_f32_16x16x32_bf16 v[118:121], v[202:205], v[170:173], v[118:121]
	v_mfma_f32_16x16x32_bf16 v[114:117], v[206:209], v[170:173], v[114:117]
	ds_read_b128 v[170:173], v247 offset:4096
	s_waitcnt lgkmcnt(9)
	v_mfma_f32_16x16x32_bf16 v[110:113], v[194:197], v[174:177], v[110:113]
	v_mfma_f32_16x16x32_bf16 v[106:109], v[198:201], v[174:177], v[106:109]
	v_mfma_f32_16x16x32_bf16 v[102:105], v[202:205], v[174:177], v[102:105]
	v_mfma_f32_16x16x32_bf16 v[82:85], v[206:209], v[174:177], v[82:85]
	ds_read_b128 v[210:213], v243
	ds_read_b128 v[214:217], v241
	ds_read_b128 v[218:221], v243 offset:4096
	ds_read_b128 v[222:225], v241 offset:4096
	ds_read_b128 v[174:177], v245 offset:4096
	s_waitcnt lgkmcnt(11)
	v_mfma_f32_16x16x32_bf16 v[98:101], v[194:197], v[178:181], v[98:101]
	v_mfma_f32_16x16x32_bf16 v[94:97], v[198:201], v[178:181], v[94:97]
	v_mfma_f32_16x16x32_bf16 v[90:93], v[202:205], v[178:181], v[90:93]
	v_mfma_f32_16x16x32_bf16 v[86:89], v[206:209], v[178:181], v[86:89]
	s_waitcnt vmcnt(6)
	ds_write_b128 v235, v[22:25] offset:16384
	ds_write_b128 v235, v[18:21] offset:24576
.LBB0_2549:
	global_load_dwordx4 v[18:21], v232, s[16:17]
	global_load_dwordx4 v[22:25], v231, s[16:17]
	s_and_b64 vcc, exec, s[0:1]
	ds_read_b128 v[178:181], v247 offset:8192
	v_mfma_f32_16x16x32_bf16 v[78:81], v[194:197], v[182:185], v[78:81]
	v_mfma_f32_16x16x32_bf16 v[74:77], v[198:201], v[182:185], v[74:77]
	v_mfma_f32_16x16x32_bf16 v[70:73], v[202:205], v[182:185], v[70:73]
	v_mfma_f32_16x16x32_bf16 v[66:69], v[206:209], v[182:185], v[66:69]
	s_waitcnt lgkmcnt(10)
	ds_read_b128 v[182:185], v245 offset:8192
	v_mfma_f32_16x16x32_bf16 v[62:65], v[194:197], v[186:189], v[62:65]
	v_mfma_f32_16x16x32_bf16 v[58:61], v[198:201], v[186:189], v[58:61]
	v_mfma_f32_16x16x32_bf16 v[54:57], v[202:205], v[186:189], v[54:57]
	v_mfma_f32_16x16x32_bf16 v[50:53], v[206:209], v[186:189], v[50:53]
	s_waitcnt vmcnt(6)
	ds_write_b128 v235, v[14:17] offset:32768
	ds_write_b128 v235, v[10:13] offset:40960
.LBB0_2551:
	s_lshl_b32 s15, s40, 8
	s_mul_i32 s14, s40, 0xb0000
	s_mul_hi_i32 s15, s15, 0xb00
	s_lshl_b64 s[16:17], s[14:15], 1
	s_add_u32 s16, s23, s16
	s_addc_u32 s17, s24, s17
	s_add_u32 s6, s16, s6
	s_addc_u32 s7, s17, s7
	global_load_dwordx4 v[10:13], v234, s[6:7]
	global_load_dwordx4 v[14:17], v233, s[6:7]
	s_and_b64 vcc, exec, s[0:1]
	ds_read_b128 v[186:189], v247 offset:12288
	v_mfma_f32_16x16x32_bf16 v[46:49], v[194:197], v[190:193], v[46:49]
	v_mfma_f32_16x16x32_bf16 v[42:45], v[198:201], v[190:193], v[42:45]
	v_mfma_f32_16x16x32_bf16 v[38:41], v[202:205], v[190:193], v[38:41]
	v_mfma_f32_16x16x32_bf16 v[34:37], v[206:209], v[190:193], v[34:37]
	s_waitcnt lgkmcnt(10)
	ds_read_b128 v[190:193], v245 offset:12288
	s_waitcnt lgkmcnt(9)
	v_mfma_f32_16x16x32_bf16 v[158:161], v[210:213], v[162:165], v[158:161]
	v_mfma_f32_16x16x32_bf16 v[154:157], v[214:217], v[162:165], v[154:157]
	v_mfma_f32_16x16x32_bf16 v[150:153], v[218:221], v[162:165], v[150:153]
	v_mfma_f32_16x16x32_bf16 v[146:149], v[222:225], v[162:165], v[146:149]
	v_mfma_f32_16x16x32_bf16 v[142:145], v[210:213], v[166:169], v[142:145]
	v_mfma_f32_16x16x32_bf16 v[138:141], v[214:217], v[166:169], v[138:141]
	v_mfma_f32_16x16x32_bf16 v[134:137], v[218:221], v[166:169], v[134:137]
	v_mfma_f32_16x16x32_bf16 v[130:133], v[222:225], v[166:169], v[130:133]
	s_waitcnt vmcnt(6)
	ds_write_b128 v235, v[6:9] offset:49152
	ds_write_b128 v235, v[2:5] offset:57344
.LBB0_2553:
	global_load_dwordx4 v[2:5], v232, s[6:7]
	global_load_dwordx4 v[6:9], v231, s[6:7]
	v_mfma_f32_16x16x32_bf16 v[126:129], v[210:213], v[170:173], v[126:129]
	v_mfma_f32_16x16x32_bf16 v[122:125], v[214:217], v[170:173], v[122:125]
	v_mfma_f32_16x16x32_bf16 v[118:121], v[218:221], v[170:173], v[118:121]
	v_mfma_f32_16x16x32_bf16 v[114:117], v[222:225], v[170:173], v[114:117]
	s_waitcnt lgkmcnt(10)
	v_mfma_f32_16x16x32_bf16 v[110:113], v[210:213], v[174:177], v[110:113]
	v_mfma_f32_16x16x32_bf16 v[106:109], v[214:217], v[174:177], v[106:109]
	v_mfma_f32_16x16x32_bf16 v[102:105], v[218:221], v[174:177], v[102:105]
	v_mfma_f32_16x16x32_bf16 v[82:85], v[222:225], v[174:177], v[82:85]
	s_add_i32 s43, s18, 1
	s_cmp_lg_u32 s43, 44
	s_cbranch_scc1 .LBB0_2557
	s_add_i32 s20, s20, s11
	s_cmp_gt_i32 s20, 31
	s_cbranch_scc1 .LBB0_2556
	s_ashr_i32 s1, s20, 31
	s_lshr_b32 s1, s1, 27
	s_add_i32 s1, s20, s1
	s_ashr_i32 s1, s1, 5
	s_mov_b32 s0, s10
	s_lshl_b32 s6, s1, 6
	s_lshl_b32 s7, s20, 1
	s_sub_i32 s6, s7, s6
	s_and_b32 s0, s0, 7
	s_and_b32 s6, s6, -8
	s_lshl_b32 s1, s1, 2
	s_and_b32 s7, s20, 3
	s_or_b32 s41, s0, s6
	s_or_b32 s40, s1, s7
	s_lshl_b32 s0, s41, 8
	s_mul_hi_i32 s13, s0, 0xb00
	s_lshl_b32 s0, s40, 8
	s_mul_i32 s12, s41, 0xb0000
	s_mul_i32 s14, s40, 0xb0000
	s_mul_hi_i32 s15, s0, 0xb00

.LBB0_2557:
	s_waitcnt lgkmcnt(0)
	s_barrier
	ds_read_b128 v[194:197], v250
	ds_read_b128 v[198:201], v248
	ds_read_b128 v[202:205], v250 offset:4096
	ds_read_b128 v[206:209], v248 offset:4096
	ds_read_b128 v[162:165], v254
	ds_read_b128 v[166:169], v252
	ds_read_b128 v[170:173], v254 offset:4096
	ds_read_b128 v[174:177], v252 offset:4096
	v_mfma_f32_16x16x32_bf16 v[98:101], v[210:213], v[178:181], v[98:101]
	v_mfma_f32_16x16x32_bf16 v[94:97], v[214:217], v[178:181], v[94:97]
	v_mfma_f32_16x16x32_bf16 v[90:93], v[218:221], v[178:181], v[90:93]
	v_mfma_f32_16x16x32_bf16 v[86:89], v[222:225], v[178:181], v[86:89]
	v_mfma_f32_16x16x32_bf16 v[78:81], v[210:213], v[182:185], v[78:81]
	v_mfma_f32_16x16x32_bf16 v[74:77], v[214:217], v[182:185], v[74:77]
	v_mfma_f32_16x16x32_bf16 v[70:73], v[218:221], v[182:185], v[70:73]
	v_mfma_f32_16x16x32_bf16 v[66:69], v[222:225], v[182:185], v[66:69]
	v_mfma_f32_16x16x32_bf16 v[62:65], v[210:213], v[186:189], v[62:65]
	v_mfma_f32_16x16x32_bf16 v[58:61], v[214:217], v[186:189], v[58:61]
	v_mfma_f32_16x16x32_bf16 v[54:57], v[218:221], v[186:189], v[54:57]
	v_mfma_f32_16x16x32_bf16 v[50:53], v[222:225], v[186:189], v[50:53]
	v_mfma_f32_16x16x32_bf16 v[46:49], v[210:213], v[190:193], v[46:49]
	v_mfma_f32_16x16x32_bf16 v[42:45], v[214:217], v[190:193], v[42:45]
	v_mfma_f32_16x16x32_bf16 v[38:41], v[218:221], v[190:193], v[38:41]
	v_mfma_f32_16x16x32_bf16 v[34:37], v[222:225], v[190:193], v[34:37]
	ds_read_b128 v[186:189], v254 offset:12288
	ds_read_b128 v[182:185], v252 offset:8192
	ds_read_b128 v[178:181], v254 offset:8192
	ds_read_b128 v[190:193], v252 offset:12288
	s_cmp_lt_i32 s30, s33
	s_cselect_b64 s[16:17], -1, 0
	s_cmp_ge_i32 s30, s33
	s_cselect_b64 s[6:7], -1, 0
	s_and_b64 vcc, exec, s[6:7]
	s_waitcnt lgkmcnt(7)
	v_mfma_f32_16x16x32_bf16 v[158:161], v[194:197], v[162:165], v[158:161]
	v_mfma_f32_16x16x32_bf16 v[154:157], v[198:201], v[162:165], v[154:157]
	v_mfma_f32_16x16x32_bf16 v[150:153], v[202:205], v[162:165], v[150:153]
	v_mfma_f32_16x16x32_bf16 v[146:149], v[206:209], v[162:165], v[146:149]
	ds_read_b128 v[162:165], v246
	s_waitcnt lgkmcnt(7)
	v_mfma_f32_16x16x32_bf16 v[142:145], v[194:197], v[166:169], v[142:145]
	v_mfma_f32_16x16x32_bf16 v[138:141], v[198:201], v[166:169], v[138:141]
	v_mfma_f32_16x16x32_bf16 v[134:137], v[202:205], v[166:169], v[134:137]
	v_mfma_f32_16x16x32_bf16 v[130:133], v[206:209], v[166:169], v[130:133]
	s_waitcnt vmcnt(6)
	ds_write_b128 v236, v[26:29]
	ds_write_b128 v236, v[30:33] offset:8192
.LBB0_2559:
	s_lshl_b32 s0, s43, 6
	s_ashr_i32 s1, s0, 31
	s_lshl_b64 s[12:13], s[12:13], 1
	s_add_u32 s18, s21, s12
	s_addc_u32 s19, s22, s13
	s_lshl_b64 s[12:13], s[0:1], 1
	s_add_u32 s18, s18, s12
	s_addc_u32 s19, s19, s13
	global_load_dwordx4 v[30:33], v234, s[18:19]
	global_load_dwordx4 v[26:29], v233, s[18:19]
	s_andn2_b64 vcc, exec, s[16:17]
	ds_read_b128 v[166:169], v244
	s_waitcnt lgkmcnt(9)
	v_mfma_f32_16x16x32_bf16 v[126:129], v[194:197], v[170:173], v[126:129]
	v_mfma_f32_16x16x32_bf16 v[122:125], v[198:201], v[170:173], v[122:125]
	v_mfma_f32_16x16x32_bf16 v[118:121], v[202:205], v[170:173], v[118:121]
	v_mfma_f32_16x16x32_bf16 v[114:117], v[206:209], v[170:173], v[114:117]
	ds_read_b128 v[170:173], v246 offset:4096
	s_waitcnt lgkmcnt(9)
	v_mfma_f32_16x16x32_bf16 v[110:113], v[194:197], v[174:177], v[110:113]
	v_mfma_f32_16x16x32_bf16 v[106:109], v[198:201], v[174:177], v[106:109]
	v_mfma_f32_16x16x32_bf16 v[102:105], v[202:205], v[174:177], v[102:105]
	v_mfma_f32_16x16x32_bf16 v[82:85], v[206:209], v[174:177], v[82:85]
	ds_read_b128 v[210:213], v242
	ds_read_b128 v[214:217], v237
	ds_read_b128 v[218:221], v242 offset:4096
	ds_read_b128 v[222:225], v237 offset:4096
	ds_read_b128 v[174:177], v244 offset:4096
	s_waitcnt lgkmcnt(11)
	v_mfma_f32_16x16x32_bf16 v[98:101], v[194:197], v[178:181], v[98:101]
	v_mfma_f32_16x16x32_bf16 v[94:97], v[198:201], v[178:181], v[94:97]
	v_mfma_f32_16x16x32_bf16 v[90:93], v[202:205], v[178:181], v[90:93]
	v_mfma_f32_16x16x32_bf16 v[86:89], v[206:209], v[178:181], v[86:89]
	s_waitcnt vmcnt(6)
	ds_write_b128 v236, v[18:21] offset:16384
	ds_write_b128 v236, v[22:25] offset:24576
.LBB0_2561:
	global_load_dwordx4 v[22:25], v232, s[18:19]
	global_load_dwordx4 v[18:21], v231, s[18:19]
	s_and_b64 vcc, exec, s[0:1]
	ds_read_b128 v[178:181], v246 offset:8192
	v_mfma_f32_16x16x32_bf16 v[78:81], v[194:197], v[182:185], v[78:81]
	v_mfma_f32_16x16x32_bf16 v[74:77], v[198:201], v[182:185], v[74:77]
	v_mfma_f32_16x16x32_bf16 v[70:73], v[202:205], v[182:185], v[70:73]
	v_mfma_f32_16x16x32_bf16 v[66:69], v[206:209], v[182:185], v[66:69]
	s_waitcnt lgkmcnt(10)
	ds_read_b128 v[182:185], v244 offset:8192
	v_mfma_f32_16x16x32_bf16 v[62:65], v[194:197], v[186:189], v[62:65]
	v_mfma_f32_16x16x32_bf16 v[58:61], v[198:201], v[186:189], v[58:61]
	v_mfma_f32_16x16x32_bf16 v[54:57], v[202:205], v[186:189], v[54:57]
	v_mfma_f32_16x16x32_bf16 v[50:53], v[206:209], v[186:189], v[50:53]
	s_waitcnt vmcnt(6)
	ds_write_b128 v236, v[10:13] offset:32768
	ds_write_b128 v236, v[14:17] offset:40960
.LBB0_2563:
	s_lshl_b64 s[14:15], s[14:15], 1
	s_add_u32 s14, s23, s14
	s_addc_u32 s15, s24, s15
	s_add_u32 s12, s14, s12
	s_addc_u32 s13, s15, s13
	global_load_dwordx4 v[14:17], v234, s[12:13]
	global_load_dwordx4 v[10:13], v233, s[12:13]
	s_and_b64 vcc, exec, s[0:1]
	ds_read_b128 v[186:189], v246 offset:12288
	v_mfma_f32_16x16x32_bf16 v[46:49], v[194:197], v[190:193], v[46:49]
	v_mfma_f32_16x16x32_bf16 v[42:45], v[198:201], v[190:193], v[42:45]
	v_mfma_f32_16x16x32_bf16 v[38:41], v[202:205], v[190:193], v[38:41]
	v_mfma_f32_16x16x32_bf16 v[34:37], v[206:209], v[190:193], v[34:37]
	s_waitcnt lgkmcnt(10)
	ds_read_b128 v[190:193], v244 offset:12288
	s_waitcnt lgkmcnt(9)
	v_mfma_f32_16x16x32_bf16 v[158:161], v[210:213], v[162:165], v[158:161]
	v_mfma_f32_16x16x32_bf16 v[154:157], v[214:217], v[162:165], v[154:157]
	v_mfma_f32_16x16x32_bf16 v[150:153], v[218:221], v[162:165], v[150:153]
	v_mfma_f32_16x16x32_bf16 v[146:149], v[222:225], v[162:165], v[146:149]
	v_mfma_f32_16x16x32_bf16 v[142:145], v[210:213], v[166:169], v[142:145]
	v_mfma_f32_16x16x32_bf16 v[138:141], v[214:217], v[166:169], v[138:141]
	v_mfma_f32_16x16x32_bf16 v[134:137], v[218:221], v[166:169], v[134:137]
	v_mfma_f32_16x16x32_bf16 v[130:133], v[222:225], v[166:169], v[130:133]
	s_waitcnt vmcnt(6)
	ds_write_b128 v236, v[2:5] offset:49152
	ds_write_b128 v236, v[6:9] offset:57344
.LBB0_2565:
	global_load_dwordx4 v[6:9], v232, s[12:13]
	global_load_dwordx4 v[2:5], v231, s[12:13]
	v_mfma_f32_16x16x32_bf16 v[126:129], v[210:213], v[170:173], v[126:129]
	v_mfma_f32_16x16x32_bf16 v[122:125], v[214:217], v[170:173], v[122:125]
	v_mfma_f32_16x16x32_bf16 v[118:121], v[218:221], v[170:173], v[118:121]
	v_mfma_f32_16x16x32_bf16 v[114:117], v[222:225], v[170:173], v[114:117]
	s_waitcnt lgkmcnt(10)
	v_mfma_f32_16x16x32_bf16 v[110:113], v[210:213], v[174:177], v[110:113]
	v_mfma_f32_16x16x32_bf16 v[106:109], v[214:217], v[174:177], v[106:109]
	v_mfma_f32_16x16x32_bf16 v[102:105], v[218:221], v[174:177], v[102:105]
	v_mfma_f32_16x16x32_bf16 v[82:85], v[222:225], v[174:177], v[82:85]
	s_add_i32 s18, s43, 1
	s_cmp_lg_u32 s18, 44
	s_cbranch_scc1 .LBB0_2569
	s_add_i32 s20, s20, s11
	s_cmp_gt_i32 s20, 31
	s_cbranch_scc1 .LBB0_2568
	s_ashr_i32 s1, s20, 31
	s_lshr_b32 s1, s1, 27
	s_add_i32 s1, s20, s1
	s_ashr_i32 s1, s1, 5
	s_mov_b32 s0, s10
	s_lshl_b32 s12, s1, 6
	s_lshl_b32 s13, s20, 1
	s_sub_i32 s12, s13, s12
	s_and_b32 s0, s0, 7
	s_and_b32 s12, s12, -8
	s_lshl_b32 s1, s1, 2
	s_and_b32 s13, s20, 3
	s_or_b32 s40, s1, s13
	s_or_b32 s41, s0, s12

.LBB0_2569:
	s_add_i32 s42, s42, 2
	s_cmp_lg_u32 s42, 44
	s_waitcnt lgkmcnt(0)
	s_mov_b32 s98, 1
	s_cbranch_scc1 .LBB0_2544
	s_mov_b32 s98, 0
	v_mfma_f32_16x16x32_bf16 v[98:101], v[210:213], v[178:181], v[98:101]
	v_mfma_f32_16x16x32_bf16 v[94:97], v[214:217], v[178:181], v[94:97]
	v_mfma_f32_16x16x32_bf16 v[90:93], v[218:221], v[178:181], v[90:93]
	v_mfma_f32_16x16x32_bf16 v[86:89], v[222:225], v[178:181], v[86:89]
	v_mfma_f32_16x16x32_bf16 v[78:81], v[210:213], v[182:185], v[78:81]
	v_mfma_f32_16x16x32_bf16 v[74:77], v[214:217], v[182:185], v[74:77]
	v_mfma_f32_16x16x32_bf16 v[70:73], v[218:221], v[182:185], v[70:73]
	v_mfma_f32_16x16x32_bf16 v[66:69], v[222:225], v[182:185], v[66:69]
	v_mfma_f32_16x16x32_bf16 v[62:65], v[210:213], v[186:189], v[62:65]
	v_mfma_f32_16x16x32_bf16 v[58:61], v[214:217], v[186:189], v[58:61]
	v_mfma_f32_16x16x32_bf16 v[54:57], v[218:221], v[186:189], v[54:57]
	v_mfma_f32_16x16x32_bf16 v[50:53], v[222:225], v[186:189], v[50:53]
	v_mfma_f32_16x16x32_bf16 v[46:49], v[210:213], v[190:193], v[46:49]
	v_mfma_f32_16x16x32_bf16 v[42:45], v[214:217], v[190:193], v[42:45]
	v_mfma_f32_16x16x32_bf16 v[38:41], v[218:221], v[190:193], v[38:41]
	v_mfma_f32_16x16x32_bf16 v[34:37], v[222:225], v[190:193], v[34:37]
	s_nop 7
	s_nop 7
	v_mov_b32_e32 v172, v0
	s_nop 0
	v_ashrrev_i32_e32 v162, 1, v172
	v_and_b32_e32 v162, 0xffffff80, v162
	v_lshl_add_u32 v162, s27, 8, v162
	v_and_or_b32 v164, v172, 15, v162
	v_add_u32_e32 v162, 0xffffe000, v162
	v_ashrrev_i32_e32 v162, 11, v162
	v_mad_i32_i24 v162, v162, s37, s37
	v_cmp_lt_i32_e32 vcc, s38, v164
	v_ashrrev_i32_e32 v163, 31, v162
	s_and_saveexec_b64 s[0:1], vcc
	s_xor_b64 s[0:1], exec, s[0:1]
	v_add_u32_e32 v238, 0xffffe000, v164
	v_lshlrev_b64 v[166:167], 12, v[238:239]
	v_mov_b32_e32 v165, v239
	v_lshl_add_u64 v[168:169], s[2:3], 0, v[166:167]
	v_lshlrev_b64 v[170:171], 12, v[164:165]
	v_mov_b64_e32 v[166:167], v[162:163]
	s_andn2_saveexec_b64 s[0:1], s[0:1]
	v_ashrrev_i32_e32 v165, 31, v164
	v_lshlrev_b64 v[170:171], 12, v[164:165]
	v_lshl_add_u64 v[168:169], s[4:5], 0, v[170:171]
	v_mov_b64_e32 v[166:167], 0
	s_or_b64 exec, exec, s[0:1]
	v_and_b32_e32 v165, 0xc0, v172
	v_lshrrev_b32_e32 v172, 2, v172
	s_lshl_b32 s0, s25, 8
	v_and_b32_e32 v172, 12, v172
	v_or3_b32 v172, v165, s0, v172
	v_ashrrev_i32_e32 v173, 31, v172
	v_lshl_add_u64 v[176:177], v[166:167], 2, s[8:9]
	v_lshlrev_b64 v[166:167], 2, v[172:173]
	v_lshl_add_u64 v[180:181], v[168:169], 0, v[166:167]
	v_lshl_add_u64 v[182:183], v[176:177], 0, v[166:167]
	global_load_dwordx4 v[172:175], v[180:181], off
	global_load_dwordx4 v[176:179], v[182:183], off
	v_lshl_add_u64 v[168:169], s[4:5], 0, v[170:171]
	v_lshl_add_u64 v[184:185], v[168:169], 0, v[166:167]
	s_waitcnt vmcnt(0)
	v_pk_fma_f32 v[160:161], v[160:161], v[178:179], v[174:175]
	v_pk_fma_f32 v[158:159], v[158:159], v[176:177], v[172:173]
	global_store_dwordx4 v[184:185], v[158:161], off
	global_load_dwordx4 v[158:161], v[180:181], off offset:64
	s_nop 0
	global_load_dwordx4 v[168:171], v[182:183], off offset:64
	s_waitcnt vmcnt(0)
	v_pk_fma_f32 v[156:157], v[156:157], v[170:171], v[160:161]
	v_pk_fma_f32 v[154:155], v[154:155], v[168:169], v[158:159]
	global_store_dwordx4 v[184:185], v[154:157], off offset:64
	global_load_dwordx4 v[154:157], v[180:181], off offset:128
	s_nop 0
	global_load_dwordx4 v[158:161], v[182:183], off offset:128
	s_waitcnt vmcnt(0)
	v_pk_fma_f32 v[152:153], v[152:153], v[160:161], v[156:157]
	v_pk_fma_f32 v[150:151], v[150:151], v[158:159], v[154:155]
	global_store_dwordx4 v[184:185], v[150:153], off offset:128
	global_load_dwordx4 v[152:155], v[180:181], off offset:192
	s_nop 0
	global_load_dwordx4 v[156:159], v[182:183], off offset:192
	v_or_b32_e32 v150, 16, v164
	v_cmp_lt_i32_e32 vcc, s38, v150
	s_waitcnt vmcnt(0)
	v_pk_fma_f32 v[148:149], v[148:149], v[158:159], v[154:155]
	v_pk_fma_f32 v[146:147], v[146:147], v[156:157], v[152:153]
	global_store_dwordx4 v[184:185], v[146:149], off offset:192
	s_and_saveexec_b64 s[0:1], vcc
	s_xor_b64 s[0:1], exec, s[0:1]
	v_add_u32_e32 v238, 0xffffe010, v164
	v_lshlrev_b64 v[146:147], 12, v[238:239]
	v_mov_b32_e32 v151, v239
	v_lshl_add_u64 v[146:147], s[2:3], 0, v[146:147]
	v_lshlrev_b64 v[148:149], 12, v[150:151]
	v_mov_b64_e32 v[152:153], v[162:163]
	s_andn2_saveexec_b64 s[0:1], s[0:1]
	v_ashrrev_i32_e32 v151, 31, v150
	v_lshlrev_b64 v[148:149], 12, v[150:151]
	v_lshl_add_u64 v[146:147], s[4:5], 0, v[148:149]
	v_mov_b64_e32 v[152:153], 0
	s_or_b64 exec, exec, s[0:1]
	v_lshl_add_u64 v[154:155], v[152:153], 2, s[8:9]
	v_lshl_add_u64 v[158:159], v[146:147], 0, v[166:167]
	v_lshl_add_u64 v[160:161], v[154:155], 0, v[166:167]
	global_load_dwordx4 v[150:153], v[158:159], off
	global_load_dwordx4 v[154:157], v[160:161], off
	v_lshl_add_u64 v[146:147], s[4:5], 0, v[148:149]
	v_lshl_add_u64 v[168:169], v[146:147], 0, v[166:167]
	s_waitcnt vmcnt(0)
	v_pk_fma_f32 v[144:145], v[144:145], v[156:157], v[152:153]
	v_pk_fma_f32 v[142:143], v[142:143], v[154:155], v[150:151]
	global_store_dwordx4 v[168:169], v[142:145], off
	global_load_dwordx4 v[142:145], v[158:159], off offset:64
	s_nop 0
	global_load_dwordx4 v[146:149], v[160:161], off offset:64
	s_waitcnt vmcnt(0)
	v_pk_fma_f32 v[140:141], v[140:141], v[148:149], v[144:145]
	v_pk_fma_f32 v[138:139], v[138:139], v[146:147], v[142:143]
	global_store_dwordx4 v[168:169], v[138:141], off offset:64
	global_load_dwordx4 v[138:141], v[158:159], off offset:128
	s_nop 0
	global_load_dwordx4 v[142:145], v[160:161], off offset:128
	s_waitcnt vmcnt(0)
	v_pk_fma_f32 v[136:137], v[136:137], v[144:145], v[140:141]
	v_pk_fma_f32 v[134:135], v[134:135], v[142:143], v[138:139]
	global_store_dwordx4 v[168:169], v[134:137], off offset:128
	global_load_dwordx4 v[136:139], v[158:159], off offset:192
	s_nop 0
	global_load_dwordx4 v[140:143], v[160:161], off offset:192
	v_or_b32_e32 v134, 32, v164
	v_cmp_lt_i32_e32 vcc, s38, v134
	s_waitcnt vmcnt(0)
	v_pk_fma_f32 v[132:133], v[132:133], v[142:143], v[138:139]
	v_pk_fma_f32 v[130:131], v[130:131], v[140:141], v[136:137]
	global_store_dwordx4 v[168:169], v[130:133], off offset:192
	s_and_saveexec_b64 s[0:1], vcc
	s_xor_b64 s[0:1], exec, s[0:1]
	v_add_u32_e32 v238, 0xffffe020, v164
	v_lshlrev_b64 v[130:131], 12, v[238:239]
	v_mov_b32_e32 v135, v239
	v_lshl_add_u64 v[130:131], s[2:3], 0, v[130:131]
	v_lshlrev_b64 v[132:133], 12, v[134:135]
	v_mov_b64_e32 v[136:137], v[162:163]
	s_andn2_saveexec_b64 s[0:1], s[0:1]
	v_ashrrev_i32_e32 v135, 31, v134
	v_lshlrev_b64 v[132:133], 12, v[134:135]
	v_lshl_add_u64 v[130:131], s[4:5], 0, v[132:133]
	v_mov_b64_e32 v[136:137], 0
	s_or_b64 exec, exec, s[0:1]
	v_lshl_add_u64 v[138:139], v[136:137], 2, s[8:9]
	v_lshl_add_u64 v[142:143], v[130:131], 0, v[166:167]
	v_lshl_add_u64 v[144:145], v[138:139], 0, v[166:167]
	global_load_dwordx4 v[134:137], v[142:143], off
	global_load_dwordx4 v[138:141], v[144:145], off
	v_lshl_add_u64 v[130:131], s[4:5], 0, v[132:133]
	v_lshl_add_u64 v[146:147], v[130:131], 0, v[166:167]
	s_waitcnt vmcnt(0)
	v_pk_fma_f32 v[128:129], v[128:129], v[140:141], v[136:137]
	v_pk_fma_f32 v[126:127], v[126:127], v[138:139], v[134:135]
	global_store_dwordx4 v[146:147], v[126:129], off
	global_load_dwordx4 v[126:129], v[142:143], off offset:64
	s_nop 0
	global_load_dwordx4 v[130:133], v[144:145], off offset:64
	s_waitcnt vmcnt(0)
	v_pk_fma_f32 v[124:125], v[124:125], v[132:133], v[128:129]
	v_pk_fma_f32 v[122:123], v[122:123], v[130:131], v[126:127]
	global_store_dwordx4 v[146:147], v[122:125], off offset:64
	global_load_dwordx4 v[122:125], v[142:143], off offset:128
	s_nop 0
	global_load_dwordx4 v[126:129], v[144:145], off offset:128
	s_waitcnt vmcnt(0)
	v_pk_fma_f32 v[120:121], v[120:121], v[128:129], v[124:125]
	v_pk_fma_f32 v[118:119], v[118:119], v[126:127], v[122:123]
	global_store_dwordx4 v[146:147], v[118:121], off offset:128
	global_load_dwordx4 v[120:123], v[142:143], off offset:192
	s_nop 0
	global_load_dwordx4 v[124:127], v[144:145], off offset:192
	v_or_b32_e32 v118, 48, v164
	v_cmp_lt_i32_e32 vcc, s38, v118
	s_waitcnt vmcnt(0)
	v_pk_fma_f32 v[116:117], v[116:117], v[126:127], v[122:123]
	v_pk_fma_f32 v[114:115], v[114:115], v[124:125], v[120:121]
	global_store_dwordx4 v[146:147], v[114:117], off offset:192
	s_and_saveexec_b64 s[0:1], vcc
	s_xor_b64 s[0:1], exec, s[0:1]
	v_add_u32_e32 v238, 0xffffe030, v164
	v_lshlrev_b64 v[114:115], 12, v[238:239]
	v_mov_b32_e32 v119, v239
	v_lshl_add_u64 v[114:115], s[2:3], 0, v[114:115]
	v_lshlrev_b64 v[116:117], 12, v[118:119]
	v_mov_b64_e32 v[120:121], v[162:163]
	s_andn2_saveexec_b64 s[0:1], s[0:1]
	v_ashrrev_i32_e32 v119, 31, v118
	v_lshlrev_b64 v[116:117], 12, v[118:119]
	v_lshl_add_u64 v[114:115], s[4:5], 0, v[116:117]
	v_mov_b64_e32 v[120:121], 0
	s_or_b64 exec, exec, s[0:1]
	v_lshl_add_u64 v[122:123], v[120:121], 2, s[8:9]
	v_lshl_add_u64 v[126:127], v[114:115], 0, v[166:167]
	v_lshl_add_u64 v[128:129], v[122:123], 0, v[166:167]
	global_load_dwordx4 v[118:121], v[126:127], off
	global_load_dwordx4 v[122:125], v[128:129], off
	v_lshl_add_u64 v[114:115], s[4:5], 0, v[116:117]
	v_lshl_add_u64 v[130:131], v[114:115], 0, v[166:167]
	s_waitcnt vmcnt(0)
	v_pk_fma_f32 v[112:113], v[112:113], v[124:125], v[120:121]
	v_pk_fma_f32 v[110:111], v[110:111], v[122:123], v[118:119]
	global_store_dwordx4 v[130:131], v[110:113], off
	global_load_dwordx4 v[110:113], v[126:127], off offset:64
	s_nop 0
	global_load_dwordx4 v[114:117], v[128:129], off offset:64
	s_waitcnt vmcnt(0)
	v_pk_fma_f32 v[108:109], v[108:109], v[116:117], v[112:113]
	v_pk_fma_f32 v[106:107], v[106:107], v[114:115], v[110:111]
	global_store_dwordx4 v[130:131], v[106:109], off offset:64
	global_load_dwordx4 v[106:109], v[126:127], off offset:128
	s_nop 0
	global_load_dwordx4 v[110:113], v[128:129], off offset:128
	s_waitcnt vmcnt(0)
	v_pk_fma_f32 v[104:105], v[104:105], v[112:113], v[108:109]
	v_pk_fma_f32 v[102:103], v[102:103], v[110:111], v[106:107]
	global_store_dwordx4 v[130:131], v[102:105], off offset:128
	global_load_dwordx4 v[104:107], v[126:127], off offset:192
	s_nop 0
	global_load_dwordx4 v[108:111], v[128:129], off offset:192
	v_or_b32_e32 v102, 64, v164
	v_cmp_lt_i32_e32 vcc, s38, v102
	s_waitcnt vmcnt(0)
	v_pk_fma_f32 v[84:85], v[84:85], v[110:111], v[106:107]
	v_pk_fma_f32 v[82:83], v[82:83], v[108:109], v[104:105]
	global_store_dwordx4 v[130:131], v[82:85], off offset:192
	s_and_saveexec_b64 s[0:1], vcc
	s_xor_b64 s[0:1], exec, s[0:1]
	v_add_u32_e32 v238, 0xffffe040, v164
	v_lshlrev_b64 v[82:83], 12, v[238:239]
	v_mov_b32_e32 v103, v239
	v_lshl_add_u64 v[82:83], s[2:3], 0, v[82:83]
	v_lshlrev_b64 v[84:85], 12, v[102:103]
	v_mov_b64_e32 v[104:105], v[162:163]
	s_andn2_saveexec_b64 s[0:1], s[0:1]
	v_ashrrev_i32_e32 v103, 31, v102
	v_lshlrev_b64 v[84:85], 12, v[102:103]
	v_lshl_add_u64 v[82:83], s[4:5], 0, v[84:85]
	v_mov_b64_e32 v[104:105], 0
	s_or_b64 exec, exec, s[0:1]
	v_lshl_add_u64 v[106:107], v[104:105], 2, s[8:9]
	v_lshl_add_u64 v[110:111], v[82:83], 0, v[166:167]
	v_lshl_add_u64 v[112:113], v[106:107], 0, v[166:167]
	global_load_dwordx4 v[102:105], v[110:111], off
	global_load_dwordx4 v[106:109], v[112:113], off
	v_lshl_add_u64 v[82:83], s[4:5], 0, v[84:85]
	v_lshl_add_u64 v[114:115], v[82:83], 0, v[166:167]
	s_waitcnt vmcnt(0)
	v_pk_fma_f32 v[84:85], v[100:101], v[108:109], v[104:105]
	v_pk_fma_f32 v[82:83], v[98:99], v[106:107], v[102:103]
	global_store_dwordx4 v[114:115], v[82:85], off
	global_load_dwordx4 v[82:85], v[110:111], off offset:64
	s_nop 0
	global_load_dwordx4 v[98:101], v[112:113], off offset:64
	s_waitcnt vmcnt(0)
	v_pk_fma_f32 v[84:85], v[96:97], v[100:101], v[84:85]
	v_pk_fma_f32 v[82:83], v[94:95], v[98:99], v[82:83]
	global_store_dwordx4 v[114:115], v[82:85], off offset:64
	global_load_dwordx4 v[82:85], v[110:111], off offset:128
	s_nop 0
	global_load_dwordx4 v[94:97], v[112:113], off offset:128
	s_waitcnt vmcnt(0)
	v_pk_fma_f32 v[84:85], v[92:93], v[96:97], v[84:85]
	v_pk_fma_f32 v[82:83], v[90:91], v[94:95], v[82:83]
	global_store_dwordx4 v[114:115], v[82:85], off offset:128
	global_load_dwordx4 v[90:93], v[110:111], off offset:192
	global_load_dwordx4 v[94:97], v[112:113], off offset:192
	v_or_b32_e32 v84, 0x50, v164
	v_cmp_lt_i32_e32 vcc, s38, v84
	s_waitcnt vmcnt(0)
	v_pk_fma_f32 v[88:89], v[88:89], v[96:97], v[92:93]
	v_pk_fma_f32 v[86:87], v[86:87], v[94:95], v[90:91]
	global_store_dwordx4 v[114:115], v[86:89], off offset:192
	s_and_saveexec_b64 s[0:1], vcc
	s_xor_b64 s[0:1], exec, s[0:1]
	v_add_u32_e32 v238, 0xffffe050, v164
	v_lshlrev_b64 v[82:83], 12, v[238:239]
	v_mov_b32_e32 v85, v239
	v_lshl_add_u64 v[82:83], s[2:3], 0, v[82:83]
	v_lshlrev_b64 v[86:87], 12, v[84:85]
	v_mov_b64_e32 v[88:89], v[162:163]
	s_andn2_saveexec_b64 s[0:1], s[0:1]
	v_ashrrev_i32_e32 v85, 31, v84
	v_lshlrev_b64 v[86:87], 12, v[84:85]
	v_lshl_add_u64 v[82:83], s[4:5], 0, v[86:87]
	v_mov_b64_e32 v[88:89], 0
	s_or_b64 exec, exec, s[0:1]
	v_lshl_add_u64 v[88:89], v[88:89], 2, s[8:9]
	v_lshl_add_u64 v[92:93], v[82:83], 0, v[166:167]
	v_lshl_add_u64 v[94:95], v[88:89], 0, v[166:167]
	global_load_dwordx4 v[82:85], v[92:93], off
	global_load_dwordx4 v[88:91], v[94:95], off
	v_lshl_add_u64 v[86:87], s[4:5], 0, v[86:87]
	v_lshl_add_u64 v[86:87], v[86:87], 0, v[166:167]
	s_waitcnt vmcnt(0)
	v_pk_fma_f32 v[80:81], v[80:81], v[90:91], v[84:85]
	v_pk_fma_f32 v[78:79], v[78:79], v[88:89], v[82:83]
	global_store_dwordx4 v[86:87], v[78:81], off
	global_load_dwordx4 v[78:81], v[92:93], off offset:64
	s_nop 0
	global_load_dwordx4 v[82:85], v[94:95], off offset:64
	s_waitcnt vmcnt(0)
	v_pk_fma_f32 v[76:77], v[76:77], v[84:85], v[80:81]
	v_pk_fma_f32 v[74:75], v[74:75], v[82:83], v[78:79]
	global_store_dwordx4 v[86:87], v[74:77], off offset:64
	global_load_dwordx4 v[74:77], v[92:93], off offset:128
	s_nop 0
	global_load_dwordx4 v[78:81], v[94:95], off offset:128
	s_waitcnt vmcnt(0)
	v_pk_fma_f32 v[72:73], v[72:73], v[80:81], v[76:77]
	v_pk_fma_f32 v[70:71], v[70:71], v[78:79], v[74:75]
	global_store_dwordx4 v[86:87], v[70:73], off offset:128
	global_load_dwordx4 v[72:75], v[92:93], off offset:192
	s_nop 0
	global_load_dwordx4 v[76:79], v[94:95], off offset:192
	v_or_b32_e32 v70, 0x60, v164
	v_cmp_lt_i32_e32 vcc, s38, v70
	s_waitcnt vmcnt(0)
	v_pk_fma_f32 v[68:69], v[68:69], v[78:79], v[74:75]
	v_pk_fma_f32 v[66:67], v[66:67], v[76:77], v[72:73]
	global_store_dwordx4 v[86:87], v[66:69], off offset:192
	s_and_saveexec_b64 s[0:1], vcc
	s_xor_b64 s[0:1], exec, s[0:1]
	v_add_u32_e32 v238, 0xffffe060, v164
	v_lshlrev_b64 v[66:67], 12, v[238:239]
	v_mov_b32_e32 v71, v239
	v_lshl_add_u64 v[66:67], s[2:3], 0, v[66:67]
	v_lshlrev_b64 v[68:69], 12, v[70:71]
	v_mov_b64_e32 v[72:73], v[162:163]
	s_andn2_saveexec_b64 s[0:1], s[0:1]
	v_ashrrev_i32_e32 v71, 31, v70
	v_lshlrev_b64 v[68:69], 12, v[70:71]
	v_lshl_add_u64 v[66:67], s[4:5], 0, v[68:69]
	v_mov_b64_e32 v[72:73], 0
	s_or_b64 exec, exec, s[0:1]
	v_lshl_add_u64 v[74:75], v[72:73], 2, s[8:9]
	v_lshl_add_u64 v[78:79], v[66:67], 0, v[166:167]
	v_lshl_add_u64 v[80:81], v[74:75], 0, v[166:167]
	global_load_dwordx4 v[70:73], v[78:79], off
	global_load_dwordx4 v[74:77], v[80:81], off
	v_lshl_add_u64 v[66:67], s[4:5], 0, v[68:69]
	v_lshl_add_u64 v[82:83], v[66:67], 0, v[166:167]
	s_waitcnt vmcnt(0)
	v_pk_fma_f32 v[64:65], v[64:65], v[76:77], v[72:73]
	v_pk_fma_f32 v[62:63], v[62:63], v[74:75], v[70:71]
	global_store_dwordx4 v[82:83], v[62:65], off
	global_load_dwordx4 v[62:65], v[78:79], off offset:64
	s_nop 0
	global_load_dwordx4 v[66:69], v[80:81], off offset:64
	s_waitcnt vmcnt(0)
	v_pk_fma_f32 v[60:61], v[60:61], v[68:69], v[64:65]
	v_pk_fma_f32 v[58:59], v[58:59], v[66:67], v[62:63]
	global_store_dwordx4 v[82:83], v[58:61], off offset:64
	global_load_dwordx4 v[58:61], v[78:79], off offset:128
	s_nop 0
	global_load_dwordx4 v[62:65], v[80:81], off offset:128
	s_waitcnt vmcnt(0)
	v_pk_fma_f32 v[56:57], v[56:57], v[64:65], v[60:61]
	v_pk_fma_f32 v[54:55], v[54:55], v[62:63], v[58:59]
	global_store_dwordx4 v[82:83], v[54:57], off offset:128
	global_load_dwordx4 v[56:59], v[78:79], off offset:192
	s_nop 0
	global_load_dwordx4 v[60:63], v[80:81], off offset:192
	v_or_b32_e32 v54, 0x70, v164
	v_cmp_lt_i32_e32 vcc, s38, v54
	s_waitcnt vmcnt(0)
	v_pk_fma_f32 v[52:53], v[52:53], v[62:63], v[58:59]
	v_pk_fma_f32 v[50:51], v[50:51], v[60:61], v[56:57]
	global_store_dwordx4 v[82:83], v[50:53], off offset:192
	s_and_saveexec_b64 s[0:1], vcc
	s_xor_b64 s[0:1], exec, s[0:1]
	v_add_u32_e32 v238, 0xffffe070, v164
	v_lshlrev_b64 v[50:51], 12, v[238:239]
	v_mov_b32_e32 v55, v239
	v_lshl_add_u64 v[50:51], s[2:3], 0, v[50:51]
	v_lshlrev_b64 v[52:53], 12, v[54:55]
	s_andn2_saveexec_b64 s[0:1], s[0:1]
	v_ashrrev_i32_e32 v55, 31, v54
	v_lshlrev_b64 v[52:53], 12, v[54:55]
	v_lshl_add_u64 v[50:51], s[4:5], 0, v[52:53]
	v_mov_b64_e32 v[162:163], 0
	s_or_b64 exec, exec, s[0:1]
	v_lshl_add_u64 v[58:59], v[162:163], 2, s[8:9]
	v_lshl_add_u64 v[62:63], v[50:51], 0, v[166:167]
	v_lshl_add_u64 v[64:65], v[58:59], 0, v[166:167]
	global_load_dwordx4 v[54:57], v[62:63], off
	global_load_dwordx4 v[58:61], v[64:65], off
	v_lshl_add_u64 v[50:51], s[4:5], 0, v[52:53]
	v_lshl_add_u64 v[66:67], v[50:51], 0, v[166:167]
	s_add_i32 s39, s39, s11
	s_cmp_gt_i32 s39, 31
	s_waitcnt vmcnt(0)
	v_pk_fma_f32 v[48:49], v[48:49], v[60:61], v[56:57]
	v_pk_fma_f32 v[46:47], v[46:47], v[58:59], v[54:55]
	global_store_dwordx4 v[66:67], v[46:49], off
	global_load_dwordx4 v[46:49], v[62:63], off offset:64
	s_nop 0
	global_load_dwordx4 v[50:53], v[64:65], off offset:64
	s_waitcnt vmcnt(0)
	v_pk_fma_f32 v[44:45], v[44:45], v[52:53], v[48:49]
	v_pk_fma_f32 v[42:43], v[42:43], v[50:51], v[46:47]
	global_store_dwordx4 v[66:67], v[42:45], off offset:64
	global_load_dwordx4 v[42:45], v[62:63], off offset:128
	s_nop 0
	global_load_dwordx4 v[46:49], v[64:65], off offset:128
	s_waitcnt vmcnt(0)
	v_pk_fma_f32 v[40:41], v[40:41], v[48:49], v[44:45]
	v_pk_fma_f32 v[38:39], v[38:39], v[46:47], v[42:43]
	global_store_dwordx4 v[66:67], v[38:41], off offset:128
	global_load_dwordx4 v[38:41], v[62:63], off offset:192
	s_nop 0
	global_load_dwordx4 v[42:45], v[64:65], off offset:192
	s_waitcnt vmcnt(0)
	v_pk_fma_f32 v[40:41], v[36:37], v[44:45], v[40:41]
	v_pk_fma_f32 v[38:39], v[34:35], v[42:43], v[38:39]
	v_mov_b32_e32 v37, 0
	global_store_dwordx4 v[66:67], v[38:41], off offset:192
	s_cbranch_scc1 .LBB0_2543
	s_ashr_i32 s1, s39, 31
	s_lshr_b32 s1, s1, 27
	s_add_i32 s1, s39, s1
	s_ashr_i32 s1, s1, 5
	s_mov_b32 s0, s10
	s_lshl_b32 s12, s1, 6
	s_lshl_b32 s13, s39, 1
	s_sub_i32 s12, s13, s12
	s_and_b32 s0, s0, 7
	s_and_b32 s12, s12, -8
	s_lshl_b32 s1, s1, 2
	s_and_b32 s13, s39, 3
	s_or_b32 s25, s1, s13
	s_or_b32 s27, s0, s12
	s_branch .LBB0_2543
